# NSA LDS bank conflicts removed: K/V tile row pitch 144 -> 160 B (conflict-free for ds_read_b128 and transposed reads under the real lane grouping), per-head bias tables skewed by 8 banks in free LDS
# speedup vs baseline: 1.0364x; 1.0090x over previous
; #define LAS __attribute__((address_space(3)))
; __global__ void __launch_bounds__(512, 2) fwd_megakernel(Params PK) {
;     ...
;                 if (hkv != cur_hkv) { __syncthreads(); const float* src = (const float*)(ws + WS_LUT) + (size_t)hkv * 4 * 4096; LAS float* dst = (LAS float*)(lds + NSA_LUT);
;                     for (int q = tid; q < 4096; q += 512) dst[q] = src[(q >> 10) * 4096 + (q & 1023)];
;                     cur_hkv = hkv; __syncthreads(); }
.LBB0_185:
	s_and_b32 s60, s6, 3
	s_cmp_lg_u32 s60, s16
	s_mov_b64 s[0:1], -1
	s_cbranch_scc0 .LBB0_197
	s_lshl_b32 s17, s60, 14
	s_barrier
	s_lshl_b32 s4, s17, 2
	v_readlane_b32 s5, v255, 48
	s_add_u32 s4, s5, s4
	v_readlane_b32 s5, v255, 49
	s_addc_u32 s5, s5, 0
	v_lshlrev_b32_e32 v0, 2, v234
	global_load_dword v2, v0, s[4:5]
	global_load_dword v3, v0, s[4:5] offset:2048
	s_add_u32 s4, s4, 0x4000
	s_addc_u32 s5, s5, 0
	global_load_dword v4, v0, s[4:5]
	global_load_dword v5, v0, s[4:5] offset:2048
	s_add_u32 s4, s4, 0x4000
	s_addc_u32 s5, s5, 0
	global_load_dword v6, v0, s[4:5]
	global_load_dword v7, v0, s[4:5] offset:2048
	s_add_u32 s4, s4, 0x4000
	s_addc_u32 s5, s5, 0
	global_load_dword v8, v0, s[4:5]
	global_load_dword v9, v0, s[4:5] offset:2048
	v_add_u32_e32 v0, 0x1d200, v0
	s_waitcnt vmcnt(0)
	ds_write_b32 v0, v2
	ds_write_b32 v0, v3 offset:2048
	ds_write_b32 v0, v4 offset:4128
	ds_write_b32 v0, v5 offset:6176
	ds_write_b32 v0, v6 offset:8256
	ds_write_b32 v0, v7 offset:10304
	ds_write_b32 v0, v8 offset:12384
	ds_write_b32 v0, v9 offset:14432
	s_mov_b64 s[0:1], 0
	s_waitcnt lgkmcnt(0)
	s_barrier

; #define LAS __attribute__((address_space(3)))
; __device__ __forceinline__ int opaque_tid() { int t = threadIdx.x; asm volatile("" : "+v"(t)); return t; }
; __device__ __forceinline__ void nsa_unit(LAS unsigned char* lds, const Ctx& P, int l, int b, int hkv, int tb) {
;     ...
;     const int tid = opaque_tid(), wid = tid >> 6, lane = tid & 63, c = lane & 15, i = lane >> 4, g = wid & 3, th = wid >> 2, hq = hkv * 4 + g;
;     const LAS float* lut = (const LAS float*)(lds + NSA_LUT) + g * 1024;
;     const int t0 = tb * 64, qb = tb;
;     int tq[2]; size_t tok[2];
; #pragma unroll
;     for (int sb = 0; sb < 2; ++sb) { tq[sb] = t0 + 32 * th + 16 * sb + c; tok[sb] = (size_t)b * SEQ + tq[sb]; }
;     bf16x8 qf[2][2];
; #pragma unroll
;     for (int sb = 0; sb < 2; ++sb)
; #pragma unroll
;         for (int ks = 0; ks < 2; ++ks) qf[sb][ks] = load_q_scaled(H + tok[sb] * LDH + C_Q + hq * 64 + ks * 32 + 8 * i, 0.125f);
.LBB0_199:
	s_ashr_i32 s4, s6, 4
	s_bfe_u32 s0, s6, 0x40004
	s_and_b32 s5, s4, -16
	s_or_b32 s4, s4, 15
	s_bfe_u32 s61, s6, 0x20002
	s_and_b32 s1, s6, 0x100
	s_sub_i32 s4, s4, s0
	s_or_b32 s0, s5, s0
	s_cmp_eq_u32 s1, 0
	s_cselect_b32 s54, s0, s4
	s_lshl_b32 s0, s61, 16
	s_or_b32 s44, s0, s17
	s_lshl_b64 s[0:1], s[44:45], 1
	v_readlane_b32 s4, v255, 52
	v_mov_b32_e32 v154, v234
	s_add_u32 s0, s4, s0
	v_readlane_b32 s4, v255, 53
	s_addc_u32 s1, s4, s1
	v_ashrrev_i32_e32 v144, 3, v154
	s_lshl_b32 s55, s54, 6
	v_and_b32_e32 v101, 0xfffffff8, v144
	v_and_b32_e32 v97, 15, v154
	v_add_u32_e32 v0, s55, v101
	v_lshrrev_b32_e32 v131, 2, v97
	v_or_b32_e32 v130, v0, v131
	v_ashrrev_i32_e32 v155, 6, v154
	s_lshl_b32 s58, s61, 12
	s_mov_b32 s59, s45
	v_ashrrev_i32_e32 v131, 31, v130
	v_and_b32_e32 v24, 3, v154
	v_lshl_add_u64 v[126:127], v[130:131], 0, s[58:59]
	v_mov_b64_e32 v[10:11], s[10:11]
	v_lshl_or_b32 v96, s60, 2, v24
	v_mad_u64_u32 v[128:129], s[4:5], v126, s42, v[10:11]
	v_mad_i32_i24 v129, v127, s42, v129
	v_lshlrev_b32_e32 v0, 7, v96
	v_or_b32_e32 v98, 4, v130
	v_lshl_add_u64 v[2:3], v[128:129], 0, v[0:1]
	v_and_b32_e32 v18, 48, v154
	v_mov_b32_e32 v19, v1
	v_ashrrev_i32_e32 v99, 31, v98
	v_lshl_add_u64 v[6:7], v[2:3], 0, v[18:19]
	v_lshl_add_u64 v[120:121], v[98:99], 0, s[58:59]
	v_add_co_u32_e32 v2, vcc, s85, v6
	v_mad_u64_u32 v[122:123], s[4:5], v120, s42, v[10:11]
	s_nop 0
	v_addc_co_u32_e32 v3, vcc, 0, v7, vcc
	v_mad_i32_i24 v123, v121, s42, v123
	global_load_dwordx4 v[2:5], v[2:3], off offset:2048
	v_lshl_add_u64 v[10:11], v[122:123], 0, v[0:1]
	v_lshl_add_u64 v[6:7], v[6:7], 0, s[78:79]
	v_lshl_add_u64 v[14:15], v[10:11], 0, v[18:19]
	global_load_dwordx4 v[6:9], v[6:7], off offset:64
	v_add_co_u32_e32 v10, vcc, s85, v14
	v_readlane_b32 s4, v253, 15
	s_nop 0
	v_addc_co_u32_e32 v11, vcc, 0, v15, vcc
	global_load_dwordx4 v[10:13], v[10:11], off offset:2048
	v_lshl_add_u64 v[14:15], v[14:15], 0, s[78:79]
	global_load_dwordx4 v[14:17], v[14:15], off offset:64
	v_and_b32_e32 v99, 63, v154
	s_movk_i32 s18, 0x90
	v_bfe_u32 v103, v154, 4, 2
	v_and_b32_e32 v94, -8, v144
	v_cmp_eq_u32_e64 s[12:13], 3, v103
	v_ashrrev_i32_e32 v95, 31, v94
	v_lshlrev_b32_e32 v153, 12, v24
	v_add_u32_e32 v150, 0, v18
	v_lshlrev_b32_e32 v30, 3, v103
	v_or_b32_e32 v26, 4, v103
	v_or_b32_e32 v27, 8, v103
	v_or_b32_e32 v28, 12, v103
	v_add_u32_e32 v151, 0, v30
	v_mul_lo_u32 v147, v94, s18
	v_mad_u32_u24 v152, v97, s18, v151
	s_mov_b64 s[66:67], 0x86000
	v_or_b32_e32 v32, s71, v96
	s_mov_b32 s44, 0
	v_lshlrev_b32_e32 v102, 6, v96
	v_mul_u32_u24_e32 v131, 0x1020, v24
	v_add_u32_e32 v131, 0x1d200, v131
	v_lshl_add_u32 v145, v99, 1, 0
	v_mul_u32_u24_e32 v148, 0xa0, v97
	v_lshlrev_b32_e32 v157, 6, v103
	v_lshlrev_b32_e32 v136, 1, v30
	v_lshlrev_b32_e32 v158, 2, v32
	s_waitcnt vmcnt(0)
	v_lshlrev_b32_e32 v0, 16, v2
	v_and_b32_e32 v2, 0xffff0000, v2
	v_mul_f32_e32 v0, 0x3e000000, v0
	v_mul_f32_e32 v2, 0x3e000000, v2
	v_cvt_pk_bf16_f32 v2, v0, v2
	s_waitcnt vmcnt(2)
	v_lshlrev_b32_e32 v0, 16, v9
	v_and_b32_e32 v9, 0xffff0000, v9
	v_mul_f32_e32 v0, 0x3e000000, v0
	v_mul_f32_e32 v9, 0x3e000000, v9
	v_cvt_pk_bf16_f32 v9, v0, v9
	s_waitcnt vmcnt(1)
	v_lshlrev_b32_e32 v0, 16, v10
	v_and_b32_e32 v10, 0xffff0000, v10
	v_mul_f32_e32 v0, 0x3e000000, v0
	v_mul_f32_e32 v10, 0x3e000000, v10
	v_cvt_pk_bf16_f32 v10, v0, v10
	v_lshlrev_b32_e32 v0, 16, v11
	v_and_b32_e32 v11, 0xffff0000, v11
	v_mul_f32_e32 v0, 0x3e000000, v0
	v_mul_f32_e32 v11, 0x3e000000, v11
	v_cvt_pk_bf16_f32 v11, v0, v11
	v_lshlrev_b32_e32 v0, 16, v12
	v_and_b32_e32 v12, 0xffff0000, v12
	v_mul_f32_e32 v0, 0x3e000000, v0
	v_mul_f32_e32 v12, 0x3e000000, v12
	v_cvt_pk_bf16_f32 v12, v0, v12
	v_lshlrev_b32_e32 v0, 16, v13
	v_and_b32_e32 v13, 0xffff0000, v13
	v_mul_f32_e32 v0, 0x3e000000, v0
	v_mul_f32_e32 v13, 0x3e000000, v13
	v_cvt_pk_bf16_f32 v13, v0, v13
	s_waitcnt vmcnt(0)
; __device__ __forceinline__ void nsa_unit(LAS unsigned char* lds, const Ctx& P, int l, int b, int hkv, int tb) {
;     ...
; #pragma unroll
;     for (int sb = 0; sb < 2; ++sb) { tq[sb] = t0 + 32 * th + 16 * sb + c; tok[sb] = (size_t)b * SEQ + tq[sb]; }
;     bf16x8 qf[2][2];
; #pragma unroll
;     for (int sb = 0; sb < 2; ++sb)
; #pragma unroll
;         for (int ks = 0; ks < 2; ++ks) qf[sb][ks] = load_q_scaled(H + tok[sb] * LDH + C_Q + hq * 64 + ks * 32 + 8 * i, 0.125f);
;     f32x4* park = (f32x4*)(P.ws + WS_PARK) + ((size_t)(blockIdx.x * 8 + wid) * 8) * 64 + lane;
;     float alpha; bf16x8 pf, pf1;
;     auto load2 = [&](const bf16_t* ksrc, const bf16_t* vsrc, size_t ld, int p0a, int p0b, bool hasb, int pmax) {
;         TileRegs ra, rb; tile_issue(ra, tid, ksrc, vsrc, ld, p0a, pmax); if (hasb) tile_issue(rb, tid, ksrc, vsrc, ld, p0b, pmax);
;         tile_commit(ra, tid, KV, KV + 4608); if (hasb) tile_commit(rb, tid, KV + 9216, KV + 9216 + 4608); };
; #pragma unroll 1
;     for (int sb = 0; sb < 2; ++sb) {
;         f32x4 o[4], oi[4]; float m = NEGBIG, lsum = 0.f;
; #pragma unroll
;         for (int dt = 0; dt < 4; ++dt) { o[dt] = (f32x4){0.f, 0.f, 0.f, 0.f}; oi[dt] = (f32x4){0.f, 0.f, 0.f, 0.f}; }
;         bf16x8 ovA[2], ovB[2];
; #pragma unroll
;         for (int st = 0; st < 2; ++st)
; #pragma unroll
;             for (int j = 0; j < 8; ++j) { const int nl = 32 * st + (j < 4 ? 4 * i + j : 16 + 4 * i + (j - 4));
;                 float a = 0.f; if ((nl >> 2) == c) a = ((nl & 3) == 3) ? 0.5f : 1.0f; else if ((nl >> 2) == c - 1 && (nl & 3) == 3) a = 0.5f;
;                 const float bb = (c == 0 && nl == 63) ? 0.5f : 0.f;
;                 ovA[st][j] = (short)(__float_as_uint(a) >> 16); ovB[st][j] = (short)(__float_as_uint(bb) >> 16); }
;         const int ntile = ((t0 >> 4) + 2) / 64 + 1;
	v_lshlrev_b32_e32 v0, 16, v14
	v_and_b32_e32 v14, 0xffff0000, v14
	v_mul_f32_e32 v0, 0x3e000000, v0
	v_mul_f32_e32 v14, 0x3e000000, v14
	v_cvt_pk_bf16_f32 v14, v0, v14
	v_lshlrev_b32_e32 v0, 16, v15
	v_and_b32_e32 v15, 0xffff0000, v15
	v_mul_f32_e32 v0, 0x3e000000, v0
	v_mul_f32_e32 v15, 0x3e000000, v15
	v_cvt_pk_bf16_f32 v15, v0, v15
	v_lshlrev_b32_e32 v0, 16, v16
	v_and_b32_e32 v16, 0xffff0000, v16
	v_mul_f32_e32 v0, 0x3e000000, v0
	v_mul_f32_e32 v16, 0x3e000000, v16
	v_cvt_pk_bf16_f32 v16, v0, v16
	v_lshlrev_b32_e32 v0, 16, v17
	v_and_b32_e32 v17, 0xffff0000, v17
	v_lshlrev_b32_e32 v20, 16, v4
	v_and_b32_e32 v4, 0xffff0000, v4
	v_lshlrev_b32_e32 v21, 16, v5
	v_and_b32_e32 v5, 0xffff0000, v5
	v_mul_f32_e32 v0, 0x3e000000, v0
	v_mul_f32_e32 v17, 0x3e000000, v17
	v_mul_f32_e32 v20, 0x3e000000, v20
	v_mul_f32_e32 v4, 0x3e000000, v4
	v_mul_f32_e32 v21, 0x3e000000, v21
	v_mul_f32_e32 v5, 0x3e000000, v5
	v_cvt_pk_bf16_f32 v17, v0, v17
	v_add_u32_e32 v0, s4, v155
	v_readlane_b32 s4, v255, 54
	v_cvt_pk_bf16_f32 v4, v20, v4
	v_cvt_pk_bf16_f32 v5, v21, v5
	v_lshlrev_b64 v[20:21], 13, v[0:1]
	v_readlane_b32 s5, v255, 55
	v_lshlrev_b32_e32 v0, 4, v99
	v_lshlrev_b32_e32 v25, 16, v8
	v_lshl_add_u64 v[20:21], s[4:5], 0, v[20:21]
	v_and_b32_e32 v8, 0xffff0000, v8
	v_lshl_add_u64 v[124:125], v[20:21], 0, v[0:1]
	v_lshlrev_b32_e32 v0, 3, v154
	v_lshlrev_b32_e32 v22, 16, v6
	v_and_b32_e32 v6, 0xffff0000, v6
	v_lshlrev_b32_e32 v23, 16, v7
	v_and_b32_e32 v7, 0xffff0000, v7
	v_mul_f32_e32 v25, 0x3e000000, v25
	v_mul_f32_e32 v8, 0x3e000000, v8
	v_and_b32_e32 v100, 56, v0
	v_lshlrev_b32_e32 v19, 16, v3
	v_and_b32_e32 v3, 0xffff0000, v3
	v_mul_f32_e32 v22, 0x3e000000, v22
	v_mul_f32_e32 v6, 0x3e000000, v6
	v_mul_f32_e32 v23, 0x3e000000, v23
	v_mul_f32_e32 v7, 0x3e000000, v7
	v_cvt_pk_bf16_f32 v8, v25, v8
	s_lshl_b32 s4, s54, 2
	s_ashr_i32 s5, s54, 31
	v_lshlrev_b32_e32 v0, 1, v100
	v_mul_lo_u32 v25, v144, s18
	v_mul_f32_e32 v19, 0x3e000000, v19
	v_mul_f32_e32 v3, 0x3e000000, v3
	v_cvt_pk_bf16_f32 v6, v22, v6
	v_cvt_pk_bf16_f32 v7, v23, v7
	s_or_b32 s16, s4, 2
	s_lshr_b32 s5, s5, 26
	v_lshl_add_u64 v[22:23], s[0:1], 0, v[0:1]
	v_mul_u32_u24_e32 v146, 0xa0, v144
	v_add_u32_e32 v146, v146, v0
	v_or_b32_e32 v0, 48, v99
	v_cvt_pk_bf16_f32 v3, v19, v3
	v_subrev_co_u32_e32 v19, vcc, 1, v97
	s_add_i32 s5, s16, s5
	v_mul_u32_u24_e32 v149, 0x90, v0
	v_lshl_add_u32 v0, v24, 6, v101
	s_ashr_i32 s17, s5, 6
	v_lshrrev_b32_e32 v156, 2, v97
	v_or_b32_e32 v156, v0, v156
	s_and_b64 vcc, vcc, s[12:13]
	v_lshlrev_b32_e32 v0, 7, v144
	v_lshl_add_u64 v[20:21], v[94:95], 1, s[0:1]
	s_cmpk_gt_i32 s16, 0xffc0
	v_lshl_add_u64 v[104:105], v[22:23], 0, v[0:1]
	v_lshlrev_b32_e32 v0, 7, v99
	s_cselect_b64 s[8:9], -1, 0
	s_addk_i32 s4, 0x41
	v_lshl_add_u64 v[24:25], v[20:21], 0, v[0:1]
	v_add_u32_e32 v0, 64, v144
	s_cmpk_gt_u32 s4, 0x7e
	s_mov_b64 s[4:5], 0x80000
	v_cmp_gt_u32_e64 s[14:15], s84, v0
	v_lshlrev_b32_e32 v0, 7, v0
	v_cndmask_b32_e32 v18, 0, v252, vcc
	v_lshl_add_u64 v[106:107], v[24:25], 0, s[4:5]
	v_lshl_add_u64 v[108:109], v[22:23], 0, v[0:1]
	s_mov_b64 s[4:5], 0x82000
	v_mov_b32_e32 v0, 0x5040100
	s_cselect_b64 s[30:31], -1, 0
	v_lshl_add_u64 v[110:111], v[24:25], 0, s[4:5]
	v_perm_b32 v21, v18, 0, v0
	s_pack_ll_b32_b16 s4, 0, 0
	s_cmpk_gt_i32 s16, 0x7f
	v_add_u32_e32 v0, 0x80, v144
	v_cmp_eq_u32_e64 s[0:1], v103, v19
	v_cmp_eq_u32_e64 s[20:21], v26, v19
	v_cmp_eq_u32_e64 s[24:25], v27, v19
	v_cmp_eq_u32_e64 s[26:27], v28, v19
	v_mov_b32_e32 v18, s4
	v_mov_b32_e32 v19, s4
	v_mov_b32_e32 v20, s4
	s_cselect_b64 s[4:5], -1, 0
	s_cmp_gt_u32 s17, 2
	v_cmp_gt_u32_e64 s[16:17], s84, v0
	v_lshlrev_b32_e32 v0, 7, v0
	v_lshl_add_u64 v[112:113], v[22:23], 0, v[0:1]
	s_mov_b64 s[18:19], 0x84000
	v_add_u32_e32 v0, 0xc0, v144
	v_lshl_add_u64 v[114:115], v[24:25], 0, s[18:19]
	v_cmp_gt_u32_e64 s[18:19], s84, v0
	v_lshlrev_b32_e32 v0, 7, v0
	v_cmp_eq_u32_e32 vcc, v103, v97
	s_cselect_b64 s[28:29], -1, 0
	v_lshl_add_u64 v[116:117], v[22:23], 0, v[0:1]
	v_cndmask_b32_e32 v0, 0, v238, vcc
	s_or_b64 vcc, vcc, s[0:1]
	v_cndmask_b32_e32 v22, 0, v252, vcc
	v_cmp_eq_u32_e32 vcc, v26, v97
	v_lshl_add_u64 v[134:135], v[24:25], 0, s[66:67]
	s_mov_b32 s0, 0x5040100
	v_cndmask_b32_e32 v24, 0, v238, vcc
	s_or_b64 vcc, vcc, s[20:21]
	v_cndmask_b32_e32 v23, 0, v252, vcc
	v_cmp_eq_u32_e32 vcc, v27, v97
	v_cmp_gt_u32_e64 s[12:13], s84, v144
	v_perm_b32 v25, v23, v24, s0
	v_cndmask_b32_e32 v26, 0, v238, vcc
	s_or_b64 vcc, vcc, s[24:25]
	v_cndmask_b32_e32 v27, 0, v252, vcc
	v_cmp_eq_u32_e32 vcc, v28, v97
	v_perm_b32 v23, v22, v0, s0
	v_perm_b32 v24, v24, v24, s0
	v_cndmask_b32_e32 v28, 0, v238, vcc
	s_or_b64 vcc, vcc, s[26:27]
	v_cndmask_b32_e32 v29, 0, v252, vcc
	v_perm_b32 v22, v0, v0, s0
	v_perm_b32 v29, v29, v28, s0
	v_perm_b32 v27, v27, v26, s0
	v_perm_b32 v28, v28, v28, s0
	v_perm_b32 v26, v26, v26, s0
	s_mov_b64 s[24:25], -1
	s_branch .LBB0_203

; __device__ __forceinline__ void nsa_unit(LAS unsigned char* lds, const Ctx& P, int l, int b, int hkv, int tb) {
;     ...
;         f32x4 o[4], oi[4]; float m = NEGBIG, lsum = 0.f;
; #pragma unroll
;         for (int dt = 0; dt < 4; ++dt) { o[dt] = (f32x4){0.f, 0.f, 0.f, 0.f}; oi[dt] = (f32x4){0.f, 0.f, 0.f, 0.f}; }
;         bf16x8 ovA[2], ovB[2];
; #pragma unroll
;         for (int st = 0; st < 2; ++st)
; #pragma unroll
;             for (int j = 0; j < 8; ++j) { const int nl = 32 * st + (j < 4 ? 4 * i + j : 16 + 4 * i + (j - 4));
;                 float a = 0.f; if ((nl >> 2) == c) a = ((nl & 3) == 3) ? 0.5f : 1.0f; else if ((nl >> 2) == c - 1 && (nl & 3) == 3) a = 0.5f;
;                 const float bb = (c == 0 && nl == 63) ? 0.5f : 0.f;
;                 ovA[st][j] = (short)(__float_as_uint(a) >> 16); ovB[st][j] = (short)(__float_as_uint(bb) >> 16); }
;         const int ntile = ((t0 >> 4) + 2) / 64 + 1;
;         const int tqs = t0 + 32 * th + 16 * sb + c;
;         bf16x8 qs[2];
; #pragma unroll
;         for (int ks = 0; ks < 2; ++ks) qs[ks] = load_q_scaled(H + ((size_t)b * SEQ + tqs) * LDH + C_Q + hq * 64 + ks * 32 + 8 * i, 0.125f);
; #pragma unroll
;         for (int pr = 0; pr < 2; ++pr) if (2 * pr < ntile) {
;             const bool hasb = 2 * pr + 1 < ntile;
;             __syncthreads();
;             load2(KC, VC, 64, 128 * pr, 128 * pr + 64, hasb, 255);
.Lcm_ld_1:
	v_add_u32_e32 v190, v150, v148
	v_lshrrev_b32_e32 v86, 2, v97
	v_lshl_add_u32 v86, v103, 2, v86
	v_mul_u32_u24_e32 v86, 0xa0, v86
	v_and_b32_e32 v87, 3, v97
	v_lshl_add_u32 v191, v87, 3, v86
	v_mov_b32_e32 v192, v190
	v_mov_b32_e32 v193, v191
	v_add_u32_e32 v194, 0xc000, v146
	v_add_u32_e32 v86, 0, v103
	v_cmp_eq_u32_e32 vcc, v86, v97
	v_mov_b32_e32 v87, 0x3f803f80
	v_add_u32_e32 v89, 1, v86
	s_nop 1
	v_cndmask_b32_e32 v160, 0, v87, vcc
	v_mov_b32_e32 v87, 0x3f80
	v_cndmask_b32_e32 v88, 0, v87, vcc
	v_cmp_eq_u32_e64 s[0:1], v89, v97
	v_mov_b32_e32 v87, 0x3f000000
	s_or_b64 vcc, vcc, s[0:1]
	s_nop 3
	v_cndmask_b32_e32 v87, 0, v87, vcc
	v_or_b32_e32 v161, v87, v88
	v_add_u32_e32 v86, 4, v103
	v_cmp_eq_u32_e32 vcc, v86, v97
	v_mov_b32_e32 v87, 0x3f803f80
	v_add_u32_e32 v89, 1, v86
	s_nop 1
	v_cndmask_b32_e32 v162, 0, v87, vcc
	v_mov_b32_e32 v87, 0x3f80
	v_cndmask_b32_e32 v88, 0, v87, vcc
	v_cmp_eq_u32_e64 s[0:1], v89, v97
	v_mov_b32_e32 v87, 0x3f000000
	s_or_b64 vcc, vcc, s[0:1]
	s_nop 3
	v_cndmask_b32_e32 v87, 0, v87, vcc
	v_or_b32_e32 v163, v87, v88
	v_add_u32_e32 v86, 8, v103
	v_cmp_eq_u32_e32 vcc, v86, v97
	v_mov_b32_e32 v87, 0x3f803f80
	v_add_u32_e32 v89, 1, v86
	s_nop 1
	v_cndmask_b32_e32 v170, 0, v87, vcc
	v_mov_b32_e32 v87, 0x3f80
	v_cndmask_b32_e32 v88, 0, v87, vcc
	v_cmp_eq_u32_e64 s[0:1], v89, v97
	v_mov_b32_e32 v87, 0x3f000000
	s_or_b64 vcc, vcc, s[0:1]
	s_nop 3
	v_cndmask_b32_e32 v87, 0, v87, vcc
	v_or_b32_e32 v171, v87, v88
	v_add_u32_e32 v86, 12, v103
	v_cmp_eq_u32_e32 vcc, v86, v97
	v_mov_b32_e32 v87, 0x3f803f80
	v_add_u32_e32 v89, 1, v86
	s_nop 1
	v_cndmask_b32_e32 v172, 0, v87, vcc
	v_mov_b32_e32 v87, 0x3f80
	v_cndmask_b32_e32 v88, 0, v87, vcc
	v_cmp_eq_u32_e64 s[0:1], v89, v97
	v_mov_b32_e32 v87, 0x3f000000
	s_or_b64 vcc, vcc, s[0:1]
	s_nop 3
	v_cndmask_b32_e32 v87, 0, v87, vcc
	v_or_b32_e32 v173, v87, v88
	v_mov_b32_e32 v230, 0
	v_mov_b32_e32 v231, 0
	v_mov_b32_e32 v232, 0
	v_cmp_eq_u32_e32 vcc, 0, v97
	v_cmp_eq_u32_e64 s[0:1], 3, v103
	v_mov_b32_e32 v87, 0x3f000000
	s_and_b64 vcc, vcc, s[0:1]
	s_nop 3
	v_cndmask_b32_e32 v233, 0, v87, vcc
	v_mov_b32_e32 v30, 0
	v_mov_b32_e32 v46, 0
	v_mov_b32_e32 v31, 0
	v_mov_b32_e32 v47, 0
	v_mov_b32_e32 v32, 0
	v_mov_b32_e32 v48, 0
	v_mov_b32_e32 v33, 0
	v_mov_b32_e32 v49, 0
	v_mov_b32_e32 v34, 0
	v_mov_b32_e32 v50, 0
	v_mov_b32_e32 v35, 0
	v_mov_b32_e32 v51, 0
	v_mov_b32_e32 v36, 0
	v_mov_b32_e32 v52, 0
	v_mov_b32_e32 v37, 0
	v_mov_b32_e32 v53, 0
	v_mov_b32_e32 v38, 0
	v_mov_b32_e32 v54, 0
	v_mov_b32_e32 v39, 0
	v_mov_b32_e32 v55, 0
	v_mov_b32_e32 v40, 0
	v_mov_b32_e32 v56, 0
	v_mov_b32_e32 v41, 0
	v_mov_b32_e32 v57, 0
	v_mov_b32_e32 v42, 0
	v_mov_b32_e32 v58, 0
	v_mov_b32_e32 v43, 0
	v_mov_b32_e32 v59, 0
	v_mov_b32_e32 v44, 0
	v_mov_b32_e32 v60, 0
	v_mov_b32_e32 v45, 0
	v_mov_b32_e32 v61, 0
	v_mov_b32_e32 v137, 0xf149f2ca
	v_mov_b32_e32 v138, 0
	v_mov_b32_e32 v174, 0
	v_mov_b32_e32 v18, 0
	v_mov_b32_e32 v175, 0
	v_mov_b32_e32 v19, 0
	v_mov_b32_e32 v176, 0
	v_mov_b32_e32 v20, 0
	v_mov_b32_e32 v177, 0
	v_mov_b32_e32 v21, 0
	v_mov_b32_e32 v178, 0
	v_mov_b32_e32 v22, 0
	v_mov_b32_e32 v179, 0
	v_mov_b32_e32 v23, 0
	v_mov_b32_e32 v180, 0
	v_mov_b32_e32 v24, 0
	v_mov_b32_e32 v181, 0
	v_mov_b32_e32 v25, 0
	v_mov_b32_e32 v182, 0
	v_mov_b32_e32 v26, 0
	v_mov_b32_e32 v183, 0
	v_mov_b32_e32 v27, 0
	v_mov_b32_e32 v184, 0
	v_mov_b32_e32 v28, 0
	v_mov_b32_e32 v185, 0
	v_mov_b32_e32 v29, 0
	v_mov_b32_e32 v186, 0
	v_mov_b32_e32 v104, 0
	v_mov_b32_e32 v187, 0
	v_mov_b32_e32 v105, 0
	v_mov_b32_e32 v188, 0
	v_mov_b32_e32 v106, 0
	v_mov_b32_e32 v189, 0
	v_mov_b32_e32 v107, 0
	v_mov_b32_e32 v195, 0xf149f2ca
	v_mov_b32_e32 v196, 0
	s_waitcnt lgkmcnt(0)
	v_readfirstlane_b32 s0, v66
	v_readfirstlane_b32 s1, v67
	s_nop 4
	s_nop 0
	global_load_dword v110, v158, s[0:1]
	s_barrier
	s_waitcnt vmcnt(0)
	ds_write_b128 v146, v[198:201] offset:16384
	ds_write_b128 v146, v[202:205] offset:26624
	s_cmp_lt_u32 s26, 2
	s_cbranch_scc1 .Lcm_wd_2
	ds_write_b128 v146, v[206:209] offset:36864
	ds_write_b128 v146, v[210:213] offset:47104
	s_cmp_lt_u32 s26, 3
	s_cbranch_scc1 .Lcm_wd_2
	ds_write_b128 v194, v[214:217] offset:8192
	ds_write_b128 v194, v[218:221] offset:18432
	s_cmp_lt_u32 s26, 4
	s_cbranch_scc1 .Lcm_wd_2
	ds_write_b128 v194, v[222:225] offset:28672
	ds_write_b128 v194, v[226:229] offset:38912

; #define LAS __attribute__((address_space(3)))
; template <int D, class SF>
; __device__ __forceinline__ void attn_step(const bf16x8 (&qf)[D / 32], const LAS bf16_t* Ks, const LAS bf16_t* Vt, f32x4 (&o)[D / 16], float& m, float& lsum, float& alpha_out, bf16x8& pf0_out, bf16x8& pf1_out, const int lane, SF sf) {
;     ...
; #pragma unroll
;     for (int t = 0; t < 4; ++t) s[t] = (f32x4){0.f, 0.f, 0.f, 0.f};
; #pragma unroll
;     for (int ks = 0; ks < D / 32; ++ks) {
; #pragma unroll
;         for (int t = 0; t < 4; ++t) { const bf16x8 kf = *(const LAS bf16x8*)(Ks + (16 * t + c) * KSTR + ks * 32 + 8 * i); s[t] = mfma16(kf, qf[ks], s[t]); }
;     }
;     float v[16];
; #pragma unroll
;     for (int t = 0; t < 4; ++t)
; #pragma unroll
;         for (int r = 0; r < 4; ++r) v[4 * t + r] = sf(16 * t + 4 * i + r, s[t][r]);
;     float mx = fmaxf(fmaxf(fmaxf(v[0], v[1]), fmaxf(v[2], v[3])), fmaxf(fmaxf(v[4], v[5]), fmaxf(v[6], v[7])));
;     mx = fmaxf(mx, fmaxf(fmaxf(fmaxf(v[8], v[9]), fmaxf(v[10], v[11])), fmaxf(fmaxf(v[12], v[13]), fmaxf(v[14], v[15]))));
;     mx = rows_max(mx);
;     const float mnew = fmaxf(m, mx);
;     const float mc = fmaxf(mnew, -1e20f);
;     const float alpha = __builtin_amdgcn_exp2f(fmaxf(m, -1e20f) - mc);
;     float p[16], rs = 0.f;
; #pragma unroll
;     for (int r = 0; r < 16; ++r) { p[r] = __builtin_amdgcn_exp2f(v[r] - mc); rs += p[r]; }
;     rs = rows_sum(rs);
;     lsum = lsum * alpha + rs; m = mnew;
;     union { u32x4 u; bf16x8 b; } pk0, pk1;
;     pk0.u.x = cvt_pk_bf16(p[0], p[1]); pk0.u.y = cvt_pk_bf16(p[2], p[3]); pk0.u.z = cvt_pk_bf16(p[4], p[5]); pk0.u.w = cvt_pk_bf16(p[6], p[7]);
;     pk1.u.x = cvt_pk_bf16(p[8], p[9]); pk1.u.y = cvt_pk_bf16(p[10], p[11]); pk1.u.z = cvt_pk_bf16(p[12], p[13]); pk1.u.w = cvt_pk_bf16(p[14], p[15]);
;     if (__builtin_amdgcn_ballot_w64(alpha != 1.0f) != 0ull) {
; #pragma unroll
;         for (int dt = 0; dt < D / 16; ++dt) o[dt] *= alpha;
;     }
; #pragma unroll
;     for (int dt = 0; dt < D / 16; ++dt) {
;         const LAS bf16_t* vp = Vt + (16 * dt + c) * 72 + 4 * i;
;         union { u32x4 u; bf16x8 b; } vf0, vf1; const u32x2 a0 = *(const LAS u32x2*)vp, a1 = *(const LAS u32x2*)(vp + 16), b0 = *(const LAS u32x2*)(vp + 32), b1 = *(const LAS u32x2*)(vp + 48);
;         vf0.u.x = a0.x; vf0.u.y = a0.y; vf0.u.z = a1.x; vf0.u.w = a1.y; vf1.u.x = b0.x; vf1.u.y = b0.y; vf1.u.z = b1.x; vf1.u.w = b1.y;
.Lcm_top_3:
	v_lshlrev_b32_e32 v86, 6, v103
	v_sub_u32_e32 v86, v130, v86
	v_subrev_u32_e32 v86, s5, v86
	v_subrev_u32_e32 v78, 0, v86
	v_min_u32_e32 v78, 0x3ff, v78
	v_lshl_add_u32 v78, v78, 2, v131
	ds_read_b32 v78, v78
	v_subrev_u32_e32 v79, 16, v86
	v_min_u32_e32 v79, 0x3ff, v79
	v_lshl_add_u32 v79, v79, 2, v131
	ds_read_b32 v79, v79
	v_subrev_u32_e32 v80, 32, v86
	v_min_u32_e32 v80, 0x3ff, v80
	v_lshl_add_u32 v80, v80, 2, v131
	ds_read_b32 v80, v80
	v_subrev_u32_e32 v81, 48, v86
	v_min_u32_e32 v81, 0x3ff, v81
	v_lshl_add_u32 v81, v81, 2, v131
	ds_read_b32 v81, v81
	v_subrev_u32_e32 v82, 256, v86
	v_min_u32_e32 v82, 0x3ff, v82
	v_lshl_add_u32 v82, v82, 2, v131
	ds_read_b32 v82, v82
	v_subrev_u32_e32 v83, 272, v86
	v_min_u32_e32 v83, 0x3ff, v83
	v_lshl_add_u32 v83, v83, 2, v131
	ds_read_b32 v83, v83
	v_subrev_u32_e32 v84, 288, v86
	v_min_u32_e32 v84, 0x3ff, v84
	v_lshl_add_u32 v84, v84, 2, v131
	ds_read_b32 v84, v84
	v_subrev_u32_e32 v85, 304, v86
	v_min_u32_e32 v85, 0x3ff, v85
	v_lshl_add_u32 v85, v85, 2, v131
	ds_read_b32 v85, v85
	ds_read_b128 v[198:201], v192 offset:16384
	ds_read_b128 v[206:209], v192 offset:18944
	ds_read_b128 v[202:205], v192 offset:16448
	ds_read_b128 v[210:213], v192 offset:19008
	ds_read_b128 v[214:217], v192 offset:21504
	ds_read_b128 v[222:225], v192 offset:24064
	ds_read_b128 v[218:221], v192 offset:21568
	ds_read_b128 v[226:229], v192 offset:24128
	s_waitcnt lgkmcnt(6)
	v_mfma_f32_16x16x32_bf16 v[62:65], v[198:201], v[2:5], 0
	v_mfma_f32_16x16x32_bf16 v[66:69], v[206:209], v[2:5], 0
	s_waitcnt lgkmcnt(4)
	v_mfma_f32_16x16x32_bf16 v[62:65], v[202:205], v[6:9], v[62:65]
	v_mfma_f32_16x16x32_bf16 v[66:69], v[210:213], v[6:9], v[66:69]
	s_waitcnt lgkmcnt(2)
	v_mfma_f32_16x16x32_bf16 v[70:73], v[214:217], v[2:5], 0
	v_mfma_f32_16x16x32_bf16 v[74:77], v[222:225], v[2:5], 0
	s_waitcnt lgkmcnt(0)
	v_mfma_f32_16x16x32_bf16 v[70:73], v[218:221], v[6:9], v[70:73]
	v_mfma_f32_16x16x32_bf16 v[74:77], v[226:229], v[6:9], v[74:77]
	ds_read_b64_tr_b16 v[198:199], v193 offset:26624
	ds_read_b64_tr_b16 v[200:201], v193 offset:29184
	ds_read_b64_tr_b16 v[202:203], v193 offset:31744
	ds_read_b64_tr_b16 v[204:205], v193 offset:34304
	ds_read_b64_tr_b16 v[206:207], v193 offset:26656
	ds_read_b64_tr_b16 v[208:209], v193 offset:29216
	ds_read_b64_tr_b16 v[210:211], v193 offset:31776
	v_fmamk_f32 v62, v62, 0x3fb8aa3b, v78
	v_fmamk_f32 v63, v63, 0x3fb8aa3b, v79
	v_fmamk_f32 v64, v64, 0x3fb8aa3b, v80
	v_fmamk_f32 v65, v65, 0x3fb8aa3b, v81
	v_fmamk_f32 v66, v66, 0x3fb8aa3b, v82
	v_fmamk_f32 v67, v67, 0x3fb8aa3b, v83
	v_fmamk_f32 v68, v68, 0x3fb8aa3b, v84
	v_fmamk_f32 v69, v69, 0x3fb8aa3b, v85
	v_cmp_le_i32_e32 vcc, 0, v86
	s_nop 1
	v_cndmask_b32_e32 v62, v243, v62, vcc
	v_cmp_le_i32_e32 vcc, 16, v86
	s_nop 1
	v_cndmask_b32_e32 v63, v243, v63, vcc
	v_cmp_le_i32_e32 vcc, 32, v86
	s_nop 1
	v_cndmask_b32_e32 v64, v243, v64, vcc
	v_cmp_le_i32_e32 vcc, 48, v86
	s_nop 1
	v_cndmask_b32_e32 v65, v243, v65, vcc
	v_cmp_le_i32_e32 vcc, 256, v86
	s_nop 1
	v_cndmask_b32_e32 v66, v243, v66, vcc
	v_cmp_le_i32_e32 vcc, 272, v86
	s_nop 1
	v_cndmask_b32_e32 v67, v243, v67, vcc
	v_cmp_le_i32_e32 vcc, 288, v86
	s_nop 1
	v_cndmask_b32_e32 v68, v243, v68, vcc
	v_cmp_le_i32_e32 vcc, 304, v86
	s_nop 1
	v_cndmask_b32_e32 v69, v243, v69, vcc
	v_subrev_u32_e32 v78, 512, v86
	v_min_u32_e32 v78, 0x3ff, v78
	v_lshl_add_u32 v78, v78, 2, v131
	ds_read_b32 v78, v78
	v_subrev_u32_e32 v79, 528, v86
	v_min_u32_e32 v79, 0x3ff, v79
	v_lshl_add_u32 v79, v79, 2, v131
	ds_read_b32 v79, v79
	v_subrev_u32_e32 v80, 544, v86
	v_min_u32_e32 v80, 0x3ff, v80
	v_lshl_add_u32 v80, v80, 2, v131
	ds_read_b32 v80, v80
	v_subrev_u32_e32 v81, 560, v86
	v_min_u32_e32 v81, 0x3ff, v81
	v_lshl_add_u32 v81, v81, 2, v131
	ds_read_b32 v81, v81
	v_subrev_u32_e32 v82, 768, v86
	v_min_u32_e32 v82, 0x3ff, v82
	v_lshl_add_u32 v82, v82, 2, v131
	ds_read_b32 v82, v82
	v_subrev_u32_e32 v83, 784, v86
	v_min_u32_e32 v83, 0x3ff, v83
	v_lshl_add_u32 v83, v83, 2, v131
	ds_read_b32 v83, v83
	v_subrev_u32_e32 v84, 800, v86
	v_min_u32_e32 v84, 0x3ff, v84
	v_lshl_add_u32 v84, v84, 2, v131
	ds_read_b32 v84, v84
	v_subrev_u32_e32 v85, 816, v86
	v_min_u32_e32 v85, 0x3ff, v85
	v_lshl_add_u32 v85, v85, 2, v131
	ds_read_b32 v85, v85
	ds_read_b64_tr_b16 v[212:213], v193 offset:34336
	ds_read_b64_tr_b16 v[214:215], v193 offset:26688
	ds_read_b64_tr_b16 v[216:217], v193 offset:29248
	ds_read_b64_tr_b16 v[218:219], v193 offset:31808
	ds_read_b64_tr_b16 v[220:221], v193 offset:34368
	ds_read_b64_tr_b16 v[222:223], v193 offset:26720
	ds_read_b64_tr_b16 v[224:225], v193 offset:29280
	ds_read_b64_tr_b16 v[226:227], v193 offset:31840
	ds_read_b64_tr_b16 v[228:229], v193 offset:34400
	s_waitcnt lgkmcnt(9)
; __device__ __forceinline__ unsigned cvt_pk_bf16(float lo, float hi) { unsigned r; asm("v_cvt_pk_bf16_f32 %0, %1, %2" : "=v"(r) : "v"(lo), "v"(hi)); return r; }
; template <int D, class SF>
; __device__ __forceinline__ void attn_step(const bf16x8 (&qf)[D / 32], const LAS bf16_t* Ks, const LAS bf16_t* Vt, f32x4 (&o)[D / 16], float& m, float& lsum, float& alpha_out, bf16x8& pf0_out, bf16x8& pf1_out, const int lane, SF sf) {
;     ...
;     float mx = fmaxf(fmaxf(fmaxf(v[0], v[1]), fmaxf(v[2], v[3])), fmaxf(fmaxf(v[4], v[5]), fmaxf(v[6], v[7])));
;     mx = fmaxf(mx, fmaxf(fmaxf(fmaxf(v[8], v[9]), fmaxf(v[10], v[11])), fmaxf(fmaxf(v[12], v[13]), fmaxf(v[14], v[15]))));
;     mx = rows_max(mx);
;     const float mnew = fmaxf(m, mx);
;     const float mc = fmaxf(mnew, -1e20f);
;     const float alpha = __builtin_amdgcn_exp2f(fmaxf(m, -1e20f) - mc);
;     float p[16], rs = 0.f;
; #pragma unroll
;     for (int r = 0; r < 16; ++r) { p[r] = __builtin_amdgcn_exp2f(v[r] - mc); rs += p[r]; }
;     rs = rows_sum(rs);
;     lsum = lsum * alpha + rs; m = mnew;
;     union { u32x4 u; bf16x8 b; } pk0, pk1;
;     pk0.u.x = cvt_pk_bf16(p[0], p[1]); pk0.u.y = cvt_pk_bf16(p[2], p[3]); pk0.u.z = cvt_pk_bf16(p[4], p[5]); pk0.u.w = cvt_pk_bf16(p[6], p[7]);
;     pk1.u.x = cvt_pk_bf16(p[8], p[9]); pk1.u.y = cvt_pk_bf16(p[10], p[11]); pk1.u.z = cvt_pk_bf16(p[12], p[13]); pk1.u.w = cvt_pk_bf16(p[14], p[15]);
;     if (__builtin_amdgcn_ballot_w64(alpha != 1.0f) != 0ull) {
; #pragma unroll
;         for (int dt = 0; dt < D / 16; ++dt) o[dt] *= alpha;
; __device__ __forceinline__ void nsa_unit(LAS unsigned char* lds, const Ctx& P, int l, int b, int hkv, int tb) {
;     ...
;                 for (int jt = 0; jt < 4; ++jt) oi[jt] *= alpha;
	v_fmamk_f32 v70, v70, 0x3fb8aa3b, v78
	v_fmamk_f32 v71, v71, 0x3fb8aa3b, v79
	v_fmamk_f32 v72, v72, 0x3fb8aa3b, v80
	v_fmamk_f32 v73, v73, 0x3fb8aa3b, v81
	v_fmamk_f32 v74, v74, 0x3fb8aa3b, v82
	v_fmamk_f32 v75, v75, 0x3fb8aa3b, v83
	v_fmamk_f32 v76, v76, 0x3fb8aa3b, v84
	v_fmamk_f32 v77, v77, 0x3fb8aa3b, v85
	v_cmp_le_i32_e32 vcc, 512, v86
	s_nop 1
	v_cndmask_b32_e32 v70, v243, v70, vcc
	v_cmp_le_i32_e32 vcc, 528, v86
	s_nop 1
	v_cndmask_b32_e32 v71, v243, v71, vcc
	v_cmp_le_i32_e32 vcc, 544, v86
	s_nop 1
	v_cndmask_b32_e32 v72, v243, v72, vcc
	v_cmp_le_i32_e32 vcc, 560, v86
	s_nop 1
	v_cndmask_b32_e32 v73, v243, v73, vcc
	v_cmp_le_i32_e32 vcc, 768, v86
	s_nop 1
	v_cndmask_b32_e32 v74, v243, v74, vcc
	v_cmp_le_i32_e32 vcc, 784, v86
	s_nop 1
	v_cndmask_b32_e32 v75, v243, v75, vcc
	v_cmp_le_i32_e32 vcc, 800, v86
	s_nop 1
	v_cndmask_b32_e32 v76, v243, v76, vcc
	v_cmp_le_i32_e32 vcc, 816, v86
	s_nop 1
	v_cndmask_b32_e32 v77, v243, v77, vcc
	v_max3_f32 v92, v62, v63, v64
	v_max3_f32 v87, v65, v66, v67
	v_max3_f32 v88, v68, v69, v70
	v_max3_f32 v89, v71, v72, v73
	v_max3_f32 v91, v74, v75, v76
	v_max3_f32 v92, v92, v87, v77
	v_max3_f32 v88, v88, v89, v91
	v_max_f32_e32 v92, v92, v88
	v_mov_b32_e32 v87, v92
	s_nop 1
	v_permlane16_swap_b32_e32 v92, v87
	v_max_f32_e32 v92, v92, v87
	v_mov_b32_e32 v87, v92
	s_nop 1
	v_permlane32_swap_b32_e32 v92, v87
	v_max_f32_e32 v92, v92, v87
	v_max_f32_e32 v88, v137, v92
	v_max_f32_e32 v90, 0xe0ad78ec, v137
	v_max_f32_e32 v89, 0xe0ad78ec, v88
	v_sub_f32_e32 v90, v90, v89
	v_mov_b32_e32 v137, v88
	v_exp_f32_e32 v90, v90
	v_sub_f32_e32 v62, v62, v89
	v_sub_f32_e32 v63, v63, v89
	v_sub_f32_e32 v64, v64, v89
	v_sub_f32_e32 v65, v65, v89
	v_exp_f32_e32 v62, v62
	v_exp_f32_e32 v63, v63
	v_exp_f32_e32 v64, v64
	v_exp_f32_e32 v65, v65
	v_sub_f32_e32 v66, v66, v89
	v_sub_f32_e32 v67, v67, v89
	v_sub_f32_e32 v68, v68, v89
	v_sub_f32_e32 v69, v69, v89
	v_exp_f32_e32 v66, v66
	v_exp_f32_e32 v67, v67
	v_exp_f32_e32 v68, v68
	v_exp_f32_e32 v69, v69
	v_sub_f32_e32 v70, v70, v89
	v_sub_f32_e32 v71, v71, v89
	v_sub_f32_e32 v72, v72, v89
	v_sub_f32_e32 v73, v73, v89
	v_exp_f32_e32 v70, v70
	v_exp_f32_e32 v71, v71
	v_exp_f32_e32 v72, v72
	v_exp_f32_e32 v73, v73
	v_sub_f32_e32 v74, v74, v89
	v_sub_f32_e32 v75, v75, v89
	v_sub_f32_e32 v76, v76, v89
	v_sub_f32_e32 v77, v77, v89
	v_exp_f32_e32 v74, v74
	v_exp_f32_e32 v75, v75
	v_exp_f32_e32 v76, v76
	v_exp_f32_e32 v77, v77
	s_nop 0
	v_add_f32_e32 v86, v62, v63
	v_add_f32_e32 v87, v64, v65
	v_add_f32_e32 v88, v66, v67
	v_add_f32_e32 v89, v68, v69
	v_add_f32_e32 v86, v86, v70
	v_add_f32_e32 v87, v87, v71
	v_add_f32_e32 v88, v88, v72
	v_add_f32_e32 v89, v89, v73
	v_add_f32_e32 v86, v86, v74
	v_add_f32_e32 v87, v87, v75
	v_add_f32_e32 v88, v88, v76
	v_add_f32_e32 v89, v89, v77
	v_add_f32_e32 v86, v86, v87
	v_add_f32_e32 v88, v88, v89
	v_add_f32_e32 v86, v86, v88
	v_cvt_pk_bf16_f32 v78, v62, v63
	v_cvt_pk_bf16_f32 v79, v64, v65
	v_cvt_pk_bf16_f32 v80, v66, v67
	v_cvt_pk_bf16_f32 v81, v68, v69
	v_cvt_pk_bf16_f32 v82, v70, v71
	v_cvt_pk_bf16_f32 v83, v72, v73
	v_cvt_pk_bf16_f32 v84, v74, v75
	v_cvt_pk_bf16_f32 v85, v76, v77
	v_mov_b32_e32 v87, v86
	s_nop 1
	v_permlane16_swap_b32_e32 v86, v87
	v_add_f32_e32 v86, v86, v87
	v_mov_b32_e32 v87, v86
	s_nop 1
	v_permlane32_swap_b32_e32 v86, v87
	v_add_f32_e32 v86, v86, v87
	v_fma_f32 v138, v138, v90, v86
	v_cmp_neq_f32_e64 s[0:1], 1.0, v90
	s_cmp_eq_u64 s[0:1], 0
	s_cbranch_scc1 .Lcm_nosc_4
	v_pk_mul_f32 v[30:31], v[30:31], v[90:91] op_sel_hi:[1,0]
	v_pk_mul_f32 v[32:33], v[32:33], v[90:91] op_sel_hi:[1,0]
	v_pk_mul_f32 v[34:35], v[34:35], v[90:91] op_sel_hi:[1,0]
	v_pk_mul_f32 v[36:37], v[36:37], v[90:91] op_sel_hi:[1,0]
	v_pk_mul_f32 v[38:39], v[38:39], v[90:91] op_sel_hi:[1,0]
	v_pk_mul_f32 v[40:41], v[40:41], v[90:91] op_sel_hi:[1,0]
	v_pk_mul_f32 v[42:43], v[42:43], v[90:91] op_sel_hi:[1,0]
	v_pk_mul_f32 v[44:45], v[44:45], v[90:91] op_sel_hi:[1,0]
	v_pk_mul_f32 v[46:47], v[46:47], v[90:91] op_sel_hi:[1,0]
	v_pk_mul_f32 v[48:49], v[48:49], v[90:91] op_sel_hi:[1,0]
	v_pk_mul_f32 v[50:51], v[50:51], v[90:91] op_sel_hi:[1,0]
	v_pk_mul_f32 v[52:53], v[52:53], v[90:91] op_sel_hi:[1,0]
	v_pk_mul_f32 v[54:55], v[54:55], v[90:91] op_sel_hi:[1,0]
	v_pk_mul_f32 v[56:57], v[56:57], v[90:91] op_sel_hi:[1,0]
	v_pk_mul_f32 v[58:59], v[58:59], v[90:91] op_sel_hi:[1,0]
	v_pk_mul_f32 v[60:61], v[60:61], v[90:91] op_sel_hi:[1,0]

; #define LAS __attribute__((address_space(3)))
; template <int D, class SF>
; __device__ __forceinline__ void attn_step(const bf16x8 (&qf)[D / 32], const LAS bf16_t* Ks, const LAS bf16_t* Vt, f32x4 (&o)[D / 16], float& m, float& lsum, float& alpha_out, bf16x8& pf0_out, bf16x8& pf1_out, const int lane, SF sf) {
;     ...
; #pragma unroll
;     for (int t = 0; t < 4; ++t) s[t] = (f32x4){0.f, 0.f, 0.f, 0.f};
; #pragma unroll
;     for (int ks = 0; ks < D / 32; ++ks) {
; #pragma unroll
;         for (int t = 0; t < 4; ++t) { const bf16x8 kf = *(const LAS bf16x8*)(Ks + (16 * t + c) * KSTR + ks * 32 + 8 * i); s[t] = mfma16(kf, qf[ks], s[t]); }
;     }
;     float v[16];
; #pragma unroll
;     for (int t = 0; t < 4; ++t)
; #pragma unroll
;         for (int r = 0; r < 4; ++r) v[4 * t + r] = sf(16 * t + 4 * i + r, s[t][r]);
;     float mx = fmaxf(fmaxf(fmaxf(v[0], v[1]), fmaxf(v[2], v[3])), fmaxf(fmaxf(v[4], v[5]), fmaxf(v[6], v[7])));
;     mx = fmaxf(mx, fmaxf(fmaxf(fmaxf(v[8], v[9]), fmaxf(v[10], v[11])), fmaxf(fmaxf(v[12], v[13]), fmaxf(v[14], v[15]))));
;     mx = rows_max(mx);
;     const float mnew = fmaxf(m, mx);
;     const float mc = fmaxf(mnew, -1e20f);
;     const float alpha = __builtin_amdgcn_exp2f(fmaxf(m, -1e20f) - mc);
;     float p[16], rs = 0.f;
; #pragma unroll
;     for (int r = 0; r < 16; ++r) { p[r] = __builtin_amdgcn_exp2f(v[r] - mc); rs += p[r]; }
;     rs = rows_sum(rs);
;     lsum = lsum * alpha + rs; m = mnew;
;     union { u32x4 u; bf16x8 b; } pk0, pk1;
;     pk0.u.x = cvt_pk_bf16(p[0], p[1]); pk0.u.y = cvt_pk_bf16(p[2], p[3]); pk0.u.z = cvt_pk_bf16(p[4], p[5]); pk0.u.w = cvt_pk_bf16(p[6], p[7]);
;     pk1.u.x = cvt_pk_bf16(p[8], p[9]); pk1.u.y = cvt_pk_bf16(p[10], p[11]); pk1.u.z = cvt_pk_bf16(p[12], p[13]); pk1.u.w = cvt_pk_bf16(p[14], p[15]);
;     if (__builtin_amdgcn_ballot_w64(alpha != 1.0f) != 0ull) {
; #pragma unroll
;         for (int dt = 0; dt < D / 16; ++dt) o[dt] *= alpha;
;     }
; #pragma unroll
;     for (int dt = 0; dt < D / 16; ++dt) {
;         const LAS bf16_t* vp = Vt + (16 * dt + c) * 72 + 4 * i;
;         union { u32x4 u; bf16x8 b; } vf0, vf1; const u32x2 a0 = *(const LAS u32x2*)vp, a1 = *(const LAS u32x2*)(vp + 16), b0 = *(const LAS u32x2*)(vp + 32), b1 = *(const LAS u32x2*)(vp + 48);
;         vf0.u.x = a0.x; vf0.u.y = a0.y; vf0.u.z = a1.x; vf0.u.w = a1.y; vf1.u.x = b0.x; vf1.u.y = b0.y; vf1.u.z = b1.x; vf1.u.w = b1.y;
.Lcm_nob_5:
	v_mfma_f32_16x16x32_bf16 v[46:49], v[170:173], v[82:85], v[46:49]
	v_lshlrev_b32_e32 v86, 6, v103
	v_sub_u32_e32 v86, v98, v86
	v_subrev_u32_e32 v86, s5, v86
	v_subrev_u32_e32 v78, 0, v86
	v_min_u32_e32 v78, 0x3ff, v78
	v_lshl_add_u32 v78, v78, 2, v131
	ds_read_b32 v78, v78
	v_subrev_u32_e32 v79, 16, v86
	v_min_u32_e32 v79, 0x3ff, v79
	v_lshl_add_u32 v79, v79, 2, v131
	ds_read_b32 v79, v79
	v_subrev_u32_e32 v80, 32, v86
	v_min_u32_e32 v80, 0x3ff, v80
	v_lshl_add_u32 v80, v80, 2, v131
	ds_read_b32 v80, v80
	v_subrev_u32_e32 v81, 48, v86
	v_min_u32_e32 v81, 0x3ff, v81
	v_lshl_add_u32 v81, v81, 2, v131
	ds_read_b32 v81, v81
	v_subrev_u32_e32 v82, 256, v86
	v_min_u32_e32 v82, 0x3ff, v82
	v_lshl_add_u32 v82, v82, 2, v131
	ds_read_b32 v82, v82
	v_subrev_u32_e32 v83, 272, v86
	v_min_u32_e32 v83, 0x3ff, v83
	v_lshl_add_u32 v83, v83, 2, v131
	ds_read_b32 v83, v83
	v_subrev_u32_e32 v84, 288, v86
	v_min_u32_e32 v84, 0x3ff, v84
	v_lshl_add_u32 v84, v84, 2, v131
	ds_read_b32 v84, v84
	v_subrev_u32_e32 v85, 304, v86
	v_min_u32_e32 v85, 0x3ff, v85
	v_lshl_add_u32 v85, v85, 2, v131
	ds_read_b32 v85, v85
	ds_read_b128 v[198:201], v192 offset:16384
	ds_read_b128 v[206:209], v192 offset:18944
	ds_read_b128 v[202:205], v192 offset:16448
	ds_read_b128 v[210:213], v192 offset:19008
	ds_read_b128 v[214:217], v192 offset:21504
	ds_read_b128 v[222:225], v192 offset:24064
	ds_read_b128 v[218:221], v192 offset:21568
	ds_read_b128 v[226:229], v192 offset:24128
	s_waitcnt lgkmcnt(6)
	v_mfma_f32_16x16x32_bf16 v[62:65], v[198:201], v[10:13], 0
	v_mfma_f32_16x16x32_bf16 v[66:69], v[206:209], v[10:13], 0
	s_waitcnt lgkmcnt(4)
	v_mfma_f32_16x16x32_bf16 v[62:65], v[202:205], v[14:17], v[62:65]
	v_mfma_f32_16x16x32_bf16 v[66:69], v[210:213], v[14:17], v[66:69]
	s_waitcnt lgkmcnt(2)
	v_mfma_f32_16x16x32_bf16 v[70:73], v[214:217], v[10:13], 0
	v_mfma_f32_16x16x32_bf16 v[74:77], v[222:225], v[10:13], 0
	s_waitcnt lgkmcnt(0)
	v_mfma_f32_16x16x32_bf16 v[70:73], v[218:221], v[14:17], v[70:73]
	v_mfma_f32_16x16x32_bf16 v[74:77], v[226:229], v[14:17], v[74:77]
	ds_read_b64_tr_b16 v[198:199], v193 offset:26624
	ds_read_b64_tr_b16 v[200:201], v193 offset:29184
	ds_read_b64_tr_b16 v[202:203], v193 offset:31744
	ds_read_b64_tr_b16 v[204:205], v193 offset:34304
	ds_read_b64_tr_b16 v[206:207], v193 offset:26656
	ds_read_b64_tr_b16 v[208:209], v193 offset:29216
	ds_read_b64_tr_b16 v[210:211], v193 offset:31776
	v_fmamk_f32 v62, v62, 0x3fb8aa3b, v78
	v_fmamk_f32 v63, v63, 0x3fb8aa3b, v79
	v_fmamk_f32 v64, v64, 0x3fb8aa3b, v80
	v_fmamk_f32 v65, v65, 0x3fb8aa3b, v81
	v_fmamk_f32 v66, v66, 0x3fb8aa3b, v82
	v_fmamk_f32 v67, v67, 0x3fb8aa3b, v83
	v_fmamk_f32 v68, v68, 0x3fb8aa3b, v84
	v_fmamk_f32 v69, v69, 0x3fb8aa3b, v85
	v_cmp_le_i32_e32 vcc, 0, v86
	s_nop 1
	v_cndmask_b32_e32 v62, v243, v62, vcc
	v_cmp_le_i32_e32 vcc, 16, v86
	s_nop 1
	v_cndmask_b32_e32 v63, v243, v63, vcc
	v_cmp_le_i32_e32 vcc, 32, v86
	s_nop 1
	v_cndmask_b32_e32 v64, v243, v64, vcc
	v_cmp_le_i32_e32 vcc, 48, v86
	s_nop 1
	v_cndmask_b32_e32 v65, v243, v65, vcc
	v_cmp_le_i32_e32 vcc, 256, v86
	s_nop 1
	v_cndmask_b32_e32 v66, v243, v66, vcc
	v_cmp_le_i32_e32 vcc, 272, v86
	s_nop 1
	v_cndmask_b32_e32 v67, v243, v67, vcc
	v_cmp_le_i32_e32 vcc, 288, v86
	s_nop 1
	v_cndmask_b32_e32 v68, v243, v68, vcc
	v_cmp_le_i32_e32 vcc, 304, v86
	s_nop 1
	v_cndmask_b32_e32 v69, v243, v69, vcc
	v_subrev_u32_e32 v78, 512, v86
	v_min_u32_e32 v78, 0x3ff, v78
	v_lshl_add_u32 v78, v78, 2, v131
	ds_read_b32 v78, v78
	v_subrev_u32_e32 v79, 528, v86
	v_min_u32_e32 v79, 0x3ff, v79
	v_lshl_add_u32 v79, v79, 2, v131
	ds_read_b32 v79, v79
	v_subrev_u32_e32 v80, 544, v86
	v_min_u32_e32 v80, 0x3ff, v80
	v_lshl_add_u32 v80, v80, 2, v131
	ds_read_b32 v80, v80
	v_subrev_u32_e32 v81, 560, v86
	v_min_u32_e32 v81, 0x3ff, v81
	v_lshl_add_u32 v81, v81, 2, v131
	ds_read_b32 v81, v81
	v_subrev_u32_e32 v82, 768, v86
	v_min_u32_e32 v82, 0x3ff, v82
	v_lshl_add_u32 v82, v82, 2, v131
	ds_read_b32 v82, v82
	v_subrev_u32_e32 v83, 784, v86
	v_min_u32_e32 v83, 0x3ff, v83
	v_lshl_add_u32 v83, v83, 2, v131
	ds_read_b32 v83, v83
	v_subrev_u32_e32 v84, 800, v86
	v_min_u32_e32 v84, 0x3ff, v84
	v_lshl_add_u32 v84, v84, 2, v131
	ds_read_b32 v84, v84
	v_subrev_u32_e32 v85, 816, v86
	v_min_u32_e32 v85, 0x3ff, v85
	v_lshl_add_u32 v85, v85, 2, v131
	ds_read_b32 v85, v85
	ds_read_b64_tr_b16 v[212:213], v193 offset:34336
	ds_read_b64_tr_b16 v[214:215], v193 offset:26688
	ds_read_b64_tr_b16 v[216:217], v193 offset:29248
	ds_read_b64_tr_b16 v[218:219], v193 offset:31808
	ds_read_b64_tr_b16 v[220:221], v193 offset:34368
	ds_read_b64_tr_b16 v[222:223], v193 offset:26720
	ds_read_b64_tr_b16 v[224:225], v193 offset:29280
	ds_read_b64_tr_b16 v[226:227], v193 offset:31840
	ds_read_b64_tr_b16 v[228:229], v193 offset:34400
	s_waitcnt lgkmcnt(9)
; __device__ __forceinline__ unsigned cvt_pk_bf16(float lo, float hi) { unsigned r; asm("v_cvt_pk_bf16_f32 %0, %1, %2" : "=v"(r) : "v"(lo), "v"(hi)); return r; }
; template <int D, class SF>
; __device__ __forceinline__ void attn_step(const bf16x8 (&qf)[D / 32], const LAS bf16_t* Ks, const LAS bf16_t* Vt, f32x4 (&o)[D / 16], float& m, float& lsum, float& alpha_out, bf16x8& pf0_out, bf16x8& pf1_out, const int lane, SF sf) {
;     ...
;     float mx = fmaxf(fmaxf(fmaxf(v[0], v[1]), fmaxf(v[2], v[3])), fmaxf(fmaxf(v[4], v[5]), fmaxf(v[6], v[7])));
;     mx = fmaxf(mx, fmaxf(fmaxf(fmaxf(v[8], v[9]), fmaxf(v[10], v[11])), fmaxf(fmaxf(v[12], v[13]), fmaxf(v[14], v[15]))));
;     mx = rows_max(mx);
;     const float mnew = fmaxf(m, mx);
;     const float mc = fmaxf(mnew, -1e20f);
;     const float alpha = __builtin_amdgcn_exp2f(fmaxf(m, -1e20f) - mc);
;     float p[16], rs = 0.f;
; #pragma unroll
;     for (int r = 0; r < 16; ++r) { p[r] = __builtin_amdgcn_exp2f(v[r] - mc); rs += p[r]; }
;     rs = rows_sum(rs);
;     lsum = lsum * alpha + rs; m = mnew;
;     union { u32x4 u; bf16x8 b; } pk0, pk1;
;     pk0.u.x = cvt_pk_bf16(p[0], p[1]); pk0.u.y = cvt_pk_bf16(p[2], p[3]); pk0.u.z = cvt_pk_bf16(p[4], p[5]); pk0.u.w = cvt_pk_bf16(p[6], p[7]);
;     pk1.u.x = cvt_pk_bf16(p[8], p[9]); pk1.u.y = cvt_pk_bf16(p[10], p[11]); pk1.u.z = cvt_pk_bf16(p[12], p[13]); pk1.u.w = cvt_pk_bf16(p[14], p[15]);
;     if (__builtin_amdgcn_ballot_w64(alpha != 1.0f) != 0ull) {
; #pragma unroll
;         for (int dt = 0; dt < D / 16; ++dt) o[dt] *= alpha;
; __device__ __forceinline__ void nsa_unit(LAS unsigned char* lds, const Ctx& P, int l, int b, int hkv, int tb) {
;     ...
;                 for (int jt = 0; jt < 4; ++jt) oi[jt] *= alpha;
	v_fmamk_f32 v70, v70, 0x3fb8aa3b, v78
	v_fmamk_f32 v71, v71, 0x3fb8aa3b, v79
	v_fmamk_f32 v72, v72, 0x3fb8aa3b, v80
	v_fmamk_f32 v73, v73, 0x3fb8aa3b, v81
	v_fmamk_f32 v74, v74, 0x3fb8aa3b, v82
	v_fmamk_f32 v75, v75, 0x3fb8aa3b, v83
	v_fmamk_f32 v76, v76, 0x3fb8aa3b, v84
	v_fmamk_f32 v77, v77, 0x3fb8aa3b, v85
	v_cmp_le_i32_e32 vcc, 512, v86
	s_nop 1
	v_cndmask_b32_e32 v70, v243, v70, vcc
	v_cmp_le_i32_e32 vcc, 528, v86
	s_nop 1
	v_cndmask_b32_e32 v71, v243, v71, vcc
	v_cmp_le_i32_e32 vcc, 544, v86
	s_nop 1
	v_cndmask_b32_e32 v72, v243, v72, vcc
	v_cmp_le_i32_e32 vcc, 560, v86
	s_nop 1
	v_cndmask_b32_e32 v73, v243, v73, vcc
	v_cmp_le_i32_e32 vcc, 768, v86
	s_nop 1
	v_cndmask_b32_e32 v74, v243, v74, vcc
	v_cmp_le_i32_e32 vcc, 784, v86
	s_nop 1
	v_cndmask_b32_e32 v75, v243, v75, vcc
	v_cmp_le_i32_e32 vcc, 800, v86
	s_nop 1
	v_cndmask_b32_e32 v76, v243, v76, vcc
	v_cmp_le_i32_e32 vcc, 816, v86
	s_nop 1
	v_cndmask_b32_e32 v77, v243, v77, vcc
	v_max3_f32 v92, v62, v63, v64
	v_max3_f32 v87, v65, v66, v67
	v_max3_f32 v88, v68, v69, v70
	v_max3_f32 v89, v71, v72, v73
	v_max3_f32 v91, v74, v75, v76
	v_max3_f32 v92, v92, v87, v77
	v_max3_f32 v88, v88, v89, v91
	v_max_f32_e32 v92, v92, v88
	v_mov_b32_e32 v87, v92
	s_nop 1
	v_permlane16_swap_b32_e32 v92, v87
	v_max_f32_e32 v92, v92, v87
	v_mov_b32_e32 v87, v92
	s_nop 1
	v_permlane32_swap_b32_e32 v92, v87
	v_max_f32_e32 v92, v92, v87
	v_max_f32_e32 v88, v195, v92
	v_max_f32_e32 v90, 0xe0ad78ec, v195
	v_max_f32_e32 v89, 0xe0ad78ec, v88
	v_sub_f32_e32 v90, v90, v89
	v_mov_b32_e32 v195, v88
	v_exp_f32_e32 v90, v90
	v_sub_f32_e32 v62, v62, v89
	v_sub_f32_e32 v63, v63, v89
	v_sub_f32_e32 v64, v64, v89
	v_sub_f32_e32 v65, v65, v89
	v_exp_f32_e32 v62, v62
	v_exp_f32_e32 v63, v63
	v_exp_f32_e32 v64, v64
	v_exp_f32_e32 v65, v65
	v_sub_f32_e32 v66, v66, v89
	v_sub_f32_e32 v67, v67, v89
	v_sub_f32_e32 v68, v68, v89
	v_sub_f32_e32 v69, v69, v89
	v_exp_f32_e32 v66, v66
	v_exp_f32_e32 v67, v67
	v_exp_f32_e32 v68, v68
	v_exp_f32_e32 v69, v69
	v_sub_f32_e32 v70, v70, v89
	v_sub_f32_e32 v71, v71, v89
	v_sub_f32_e32 v72, v72, v89
	v_sub_f32_e32 v73, v73, v89
	v_exp_f32_e32 v70, v70
	v_exp_f32_e32 v71, v71
	v_exp_f32_e32 v72, v72
	v_exp_f32_e32 v73, v73
	v_sub_f32_e32 v74, v74, v89
	v_sub_f32_e32 v75, v75, v89
	v_sub_f32_e32 v76, v76, v89
	v_sub_f32_e32 v77, v77, v89
	v_exp_f32_e32 v74, v74
	v_exp_f32_e32 v75, v75
	v_exp_f32_e32 v76, v76
	v_exp_f32_e32 v77, v77
	s_nop 0
	v_add_f32_e32 v86, v62, v63
	v_add_f32_e32 v87, v64, v65
	v_add_f32_e32 v88, v66, v67
	v_add_f32_e32 v89, v68, v69
	v_add_f32_e32 v86, v86, v70
	v_add_f32_e32 v87, v87, v71
	v_add_f32_e32 v88, v88, v72
	v_add_f32_e32 v89, v89, v73
	v_add_f32_e32 v86, v86, v74
	v_add_f32_e32 v87, v87, v75
	v_add_f32_e32 v88, v88, v76
	v_add_f32_e32 v89, v89, v77
	v_add_f32_e32 v86, v86, v87
	v_add_f32_e32 v88, v88, v89
	v_add_f32_e32 v86, v86, v88
	v_cvt_pk_bf16_f32 v78, v62, v63
	v_cvt_pk_bf16_f32 v79, v64, v65
	v_cvt_pk_bf16_f32 v80, v66, v67
	v_cvt_pk_bf16_f32 v81, v68, v69
	v_cvt_pk_bf16_f32 v82, v70, v71
	v_cvt_pk_bf16_f32 v83, v72, v73
	v_cvt_pk_bf16_f32 v84, v74, v75
	v_cvt_pk_bf16_f32 v85, v76, v77
	v_mov_b32_e32 v87, v86
	s_nop 1
	v_permlane16_swap_b32_e32 v86, v87
	v_add_f32_e32 v86, v86, v87
	v_mov_b32_e32 v87, v86
	s_nop 1
	v_permlane32_swap_b32_e32 v86, v87
	v_add_f32_e32 v86, v86, v87
	v_fma_f32 v196, v196, v90, v86
	v_cmp_neq_f32_e64 s[0:1], 1.0, v90
	s_cmp_eq_u64 s[0:1], 0
	s_cbranch_scc1 .Lcm_nosc_6
	v_pk_mul_f32 v[174:175], v[174:175], v[90:91] op_sel_hi:[1,0]
	v_pk_mul_f32 v[176:177], v[176:177], v[90:91] op_sel_hi:[1,0]
	v_pk_mul_f32 v[178:179], v[178:179], v[90:91] op_sel_hi:[1,0]
	v_pk_mul_f32 v[180:181], v[180:181], v[90:91] op_sel_hi:[1,0]
	v_pk_mul_f32 v[182:183], v[182:183], v[90:91] op_sel_hi:[1,0]
	v_pk_mul_f32 v[184:185], v[184:185], v[90:91] op_sel_hi:[1,0]
	v_pk_mul_f32 v[186:187], v[186:187], v[90:91] op_sel_hi:[1,0]
	v_pk_mul_f32 v[188:189], v[188:189], v[90:91] op_sel_hi:[1,0]
	v_pk_mul_f32 v[18:19], v[18:19], v[90:91] op_sel_hi:[1,0]
	v_pk_mul_f32 v[20:21], v[20:21], v[90:91] op_sel_hi:[1,0]
	v_pk_mul_f32 v[22:23], v[22:23], v[90:91] op_sel_hi:[1,0]
	v_pk_mul_f32 v[24:25], v[24:25], v[90:91] op_sel_hi:[1,0]
	v_pk_mul_f32 v[26:27], v[26:27], v[90:91] op_sel_hi:[1,0]
	v_pk_mul_f32 v[28:29], v[28:29], v[90:91] op_sel_hi:[1,0]
	v_pk_mul_f32 v[104:105], v[104:105], v[90:91] op_sel_hi:[1,0]
	v_pk_mul_f32 v[106:107], v[106:107], v[90:91] op_sel_hi:[1,0]

; __device__ __forceinline__ f32x4 mfma16(bf16x8 a, bf16x8 b, f32x4 c) { return __builtin_amdgcn_mfma_f32_16x16x32_bf16(a, b, c, 0, 0, 0); }
; __device__ __forceinline__ void nsa_unit(LAS unsigned char* lds, const Ctx& P, int l, int b, int hkv, int tb) {
;     ...
; #pragma unroll
;                 for (int jt = 0; jt < 4; ++jt) oi[jt] *= alpha;
;                 oi[kt] = mfma16(ovA[0], pf, oi[kt]); oi[kt] = mfma16(ovA[1], pf1, oi[kt]);
;                 if (kt + 1 < 4) { oi[kt + 1 < 4 ? kt + 1 : 3] = mfma16(ovB[0], pf, oi[kt + 1 < 4 ? kt + 1 : 3]); oi[kt + 1 < 4 ? kt + 1 : 3] = mfma16(ovB[1], pf1, oi[kt + 1 < 4 ? kt + 1 : 3]); }
;             }
.Lcm_nob_7:
	v_mfma_f32_16x16x32_bf16 v[18:21], v[170:173], v[82:85], v[18:21]
	s_nop 7
	v_swap_b32 v46, v50
	v_swap_b32 v50, v54
	v_swap_b32 v54, v58
	v_swap_b32 v47, v51
	v_swap_b32 v51, v55
	v_swap_b32 v55, v59
	v_swap_b32 v48, v52
	v_swap_b32 v52, v56
	v_swap_b32 v56, v60
	v_swap_b32 v49, v53
	v_swap_b32 v53, v57
	v_swap_b32 v57, v61
	v_swap_b32 v18, v22
	v_swap_b32 v22, v26
	v_swap_b32 v26, v104
	v_swap_b32 v19, v23
	v_swap_b32 v23, v27
	v_swap_b32 v27, v105
	v_swap_b32 v20, v24
	v_swap_b32 v24, v28
	v_swap_b32 v28, v106
	v_swap_b32 v21, v25
	v_swap_b32 v25, v29
	v_swap_b32 v29, v107
	v_add_u32_e32 v192, 0x5000, v192
	v_add_u32_e32 v193, 0x5000, v193
	s_add_i32 s4, s4, 1
	s_addk_i32 s5, 0x400
	s_cmp_lt_u32 s4, s26
	s_cbranch_scc1 .Lcm_top_3

; #define LAS __attribute__((address_space(3)))
; __device__ __forceinline__ void nsa_unit(LAS unsigned char* lds, const Ctx& P, int l, int b, int hkv, int tb) {
;     ...
;     auto load2 = [&](const bf16_t* ksrc, const bf16_t* vsrc, size_t ld, int p0a, int p0b, bool hasb, int pmax) {
;         TileRegs ra, rb; tile_issue(ra, tid, ksrc, vsrc, ld, p0a, pmax); if (hasb) tile_issue(rb, tid, ksrc, vsrc, ld, p0b, pmax);
;         tile_commit(ra, tid, KV, KV + 4608); if (hasb) tile_commit(rb, tid, KV + 9216, KV + 9216 + 4608); };
;     ...
;         const bf16_t* kb = H + (size_t)b * SEQ * LDH + C_KS + hkv * 64; const bf16_t* vb = H + (size_t)b * SEQ * LDH + C_VS + hkv * 64;
;         U &= ((2ull << qb) - 1ull);
;         unsigned long long Ur = ((unsigned long long)(unsigned)__builtin_amdgcn_readfirstlane((int)(U >> 32)) << 32) | (unsigned)__builtin_amdgcn_readfirstlane((int)U);
;         const float cfar = lut[790];
;         while (Ur != 0ull) {
;             const int ja = __builtin_ctzll(Ur); Ur &= Ur - 1ull; const bool hasb = Ur != 0ull; int jb = 0; if (hasb) { jb = __builtin_ctzll(Ur); Ur &= Ur - 1ull; }
;             __syncthreads();
;             load2(kb, vb, LDH, ja * 64, jb * 64, hasb, SEQ - 1);
;             __syncthreads();
; #pragma unroll
;             for (int sl = 0; sl < 2; ++sl) if (sl == 0 || hasb) {
;                 const int j = sl ? jb : ja; const LAS bf16_t* Ks = KV + sl * 9216; const LAS bf16_t* Vt = Ks + 4608;
.LBB0_407:
	v_add_u32_e32 v102, v150, v148
	v_lshrrev_b32_e32 v78, 2, v97
	v_lshl_add_u32 v78, v103, 2, v78
	v_mul_u32_u24_e32 v78, 0xa0, v78
	v_and_b32_e32 v79, 3, v97
	v_lshl_add_u32 v104, v79, 3, v78
	v_add_u32_e32 v192, 0xc000, v146
	s_mov_b64 s[14:15], s[0:1]
	s_mov_b32 s13, 0
	s_ff1_i32_b64 s0, s[14:15]
	s_add_u32 s4, s14, -1
	s_addc_u32 s5, s15, -1
	s_and_b64 s[14:15], s[14:15], s[4:5]
	s_mov_b32 s13, 1
	s_lshl_b32 s4, s0, 6
	v_add_u32_e32 v54, s4, v144
	v_mul_lo_u32 v54, v54, s75
	v_mov_b32_e32 v55, v1
	v_lshl_add_u64 v[54:55], v[54:55], 1, v[88:89]
	global_load_dwordx4 v[230:233], v[54:55], off
	global_load_dwordx4 v[114:117], v[54:55], off offset:512
	s_cmp_eq_u64 s[14:15], 0
	s_cbranch_scc1 .Lsl3_xd_1
	s_ff1_i32_b64 s1, s[14:15]
	s_add_u32 s4, s14, -1
	s_addc_u32 s5, s15, -1
	s_and_b64 s[14:15], s[14:15], s[4:5]
	s_mov_b32 s13, 2
	s_lshl_b32 s4, s1, 6
	v_add_u32_e32 v54, s4, v144
	v_mul_lo_u32 v54, v54, s75
	v_mov_b32_e32 v55, v1
	v_lshl_add_u64 v[54:55], v[54:55], 1, v[88:89]
	global_load_dwordx4 v[134:137], v[54:55], off
	global_load_dwordx4 v[156:159], v[54:55], off offset:512
	s_cmp_eq_u64 s[14:15], 0
	s_cbranch_scc1 .Lsl3_xd_1
	s_ff1_i32_b64 s31, s[14:15]
	s_add_u32 s4, s14, -1
	s_addc_u32 s5, s15, -1
	s_and_b64 s[14:15], s[14:15], s[4:5]
	s_mov_b32 s13, 3
	s_lshl_b32 s4, s31, 6
	v_add_u32_e32 v54, s4, v144
	v_mul_lo_u32 v54, v54, s75
	v_mov_b32_e32 v55, v1
	v_lshl_add_u64 v[54:55], v[54:55], 1, v[88:89]
	global_load_dwordx4 v[174:177], v[54:55], off
	global_load_dwordx4 v[178:181], v[54:55], off offset:512
	s_cmp_eq_u64 s[14:15], 0
	s_cbranch_scc1 .Lsl3_xd_1
	s_ff1_i32_b64 s32, s[14:15]
	s_add_u32 s4, s14, -1
	s_addc_u32 s5, s15, -1
	s_and_b64 s[14:15], s[14:15], s[4:5]
	s_mov_b32 s13, 4
	s_lshl_b32 s4, s32, 6
	v_add_u32_e32 v54, s4, v144
	v_mul_lo_u32 v54, v54, s75
	v_mov_b32_e32 v55, v1
	v_lshl_add_u64 v[54:55], v[54:55], 1, v[88:89]
	global_load_dwordx4 v[182:185], v[54:55], off
	global_load_dwordx4 v[186:189], v[54:55], off offset:512
.Lsl3_xd_1:
.Lsl3_top:
	s_mov_b32 s26, s0
	s_mov_b32 s27, s1
	s_mov_b32 s28, s31
	s_mov_b32 s29, s32
	s_mov_b32 s30, s13
	s_waitcnt lgkmcnt(0)
	s_barrier
	s_waitcnt vmcnt(0)
	ds_write_b128 v146, v[230:233] offset:16384
	ds_write_b128 v146, v[114:117] offset:26624
	s_cmp_lt_u32 s30, 2
	s_cbranch_scc1 .Lsl3_wd_2
	ds_write_b128 v146, v[134:137] offset:36864
	ds_write_b128 v146, v[156:159] offset:47104
	s_cmp_lt_u32 s30, 3
	s_cbranch_scc1 .Lsl3_wd_2
	ds_write_b128 v192, v[174:177] offset:8192
	ds_write_b128 v192, v[178:181] offset:18432
	s_cmp_lt_u32 s30, 4
	s_cbranch_scc1 .Lsl3_wd_2
	ds_write_b128 v192, v[182:185] offset:28672
	ds_write_b128 v192, v[186:189] offset:38912

; #define LAS __attribute__((address_space(3)))
; __device__ __forceinline__ void nsa_unit(LAS unsigned char* lds, const Ctx& P, int l, int b, int hkv, int tb) {
;     ...
;             for (int sl = 0; sl < 2; ++sl) if (sl == 0 || hasb) {
;                 const int j = sl ? jb : ja; const LAS bf16_t* Ks = KV + sl * 9216; const LAS bf16_t* Vt = Ks + 4608;
;                 const bool far = t0 - (64 * j + 63) >= 790;
; #pragma unroll
;                 for (int sb = 0; sb < 2; ++sb) { const bool selj = (ms[sb] >> j) & 1ull; const int tqs = tq[sb];
;                     if (far) {
;                         if (__builtin_amdgcn_ballot_w64(selj) == 0ull) continue;
;                         attn_step<64>(qf[sb], Ks, Vt, o[sb], m[sb], lsum[sb], alpha, pf, pf1, lane,
;                             [&](int, float s) { return selj ? s * LOG2E + cfar : NEGBIG; });
.Lsl3_slot_6:
	s_cmp_eq_u32 s40, 1
	s_cselect_b32 s20, s27, s26
	s_cmp_eq_u32 s40, 2
	s_cselect_b32 s20, s28, s20
	s_cmp_eq_u32 s40, 3
	s_cselect_b32 s20, s29, s20
	s_lshl_b32 s21, s20, 6
	s_mul_i32 s4, s40, 0x5000
	v_add_u32_e32 v190, s4, v102
	v_add_u32_e32 v191, s4, v104
	s_sub_i32 s4, s19, s21
	s_cmp_lt_i32 s4, 0
	s_cbranch_scc1 .Lsl3_diagx_9
	s_cmpk_lt_i32 s4, 0x316
	s_cbranch_scc1 .Lsl3_nearx_8
	v_lshrrev_b64 v[78:79], s20, v[18:19]
	v_and_b32_e32 v78, 1, v78
	v_cmp_eq_u32_e64 s[24:25], 1, v78
	s_cmp_eq_u64 s[24:25], 0
	s_cbranch_scc1 .Lsl3_skf_10
	ds_read_b128 v[198:201], v190 offset:16384
	ds_read_b128 v[206:209], v190 offset:18944
	ds_read_b128 v[202:205], v190 offset:16448
	ds_read_b128 v[210:213], v190 offset:19008
	ds_read_b128 v[214:217], v190 offset:21504
	ds_read_b128 v[222:225], v190 offset:24064
	ds_read_b128 v[218:221], v190 offset:21568
	ds_read_b128 v[226:229], v190 offset:24128
	s_waitcnt lgkmcnt(6)
	v_mfma_f32_16x16x32_bf16 v[54:57], v[198:201], v[2:5], 0
	v_mfma_f32_16x16x32_bf16 v[58:61], v[206:209], v[2:5], 0
	s_waitcnt lgkmcnt(4)
	v_mfma_f32_16x16x32_bf16 v[54:57], v[202:205], v[6:9], v[54:57]
	v_mfma_f32_16x16x32_bf16 v[58:61], v[210:213], v[6:9], v[58:61]
	s_waitcnt lgkmcnt(2)
	v_mfma_f32_16x16x32_bf16 v[62:65], v[214:217], v[2:5], 0
	v_mfma_f32_16x16x32_bf16 v[66:69], v[222:225], v[2:5], 0
	s_waitcnt lgkmcnt(0)
	v_mfma_f32_16x16x32_bf16 v[62:65], v[218:221], v[6:9], v[62:65]
	v_mfma_f32_16x16x32_bf16 v[66:69], v[226:229], v[6:9], v[66:69]
	ds_read_b64_tr_b16 v[198:199], v191 offset:26624
	ds_read_b64_tr_b16 v[200:201], v191 offset:29184
	ds_read_b64_tr_b16 v[202:203], v191 offset:31744
	ds_read_b64_tr_b16 v[204:205], v191 offset:34304
	ds_read_b64_tr_b16 v[206:207], v191 offset:26656
	ds_read_b64_tr_b16 v[208:209], v191 offset:29216
	ds_read_b64_tr_b16 v[210:211], v191 offset:31776
	ds_read_b64_tr_b16 v[212:213], v191 offset:34336
	ds_read_b64_tr_b16 v[214:215], v191 offset:26688
	ds_read_b64_tr_b16 v[216:217], v191 offset:29248
	ds_read_b64_tr_b16 v[218:219], v191 offset:31808
	ds_read_b64_tr_b16 v[220:221], v191 offset:34368
	ds_read_b64_tr_b16 v[222:223], v191 offset:26720
	ds_read_b64_tr_b16 v[224:225], v191 offset:29280
	ds_read_b64_tr_b16 v[226:227], v191 offset:31840
	ds_read_b64_tr_b16 v[228:229], v191 offset:34400
	v_max3_f32 v78, v54, v55, v56
	v_max3_f32 v79, v57, v58, v59
	v_max3_f32 v80, v60, v61, v62
	v_max3_f32 v81, v63, v64, v65
	v_max3_f32 v83, v66, v67, v68
	v_max3_f32 v78, v78, v79, v69
	v_max3_f32 v80, v80, v81, v83
	v_max_f32_e32 v78, v78, v80
	v_mov_b32_e32 v79, v78
	s_nop 1
	v_permlane16_swap_b32_e32 v78, v79
	v_max_f32_e32 v78, v78, v79
	v_mov_b32_e32 v79, v78
	s_nop 1
	v_permlane32_swap_b32_e32 v78, v79
	v_max_f32_e32 v78, v78, v79
	v_fmamk_f32 v78, v78, 0x3fb8aa3b, v92
	v_cndmask_b32_e64 v78, v243, v78, s[24:25]
	v_max_f32_e32 v80, v100, v78
	v_max_f32_e32 v82, 0xe0ad78ec, v100
	v_max_f32_e32 v81, 0xe0ad78ec, v80
	v_sub_f32_e32 v82, v82, v81
	v_mov_b32_e32 v100, v80
	v_exp_f32_e32 v82, v82
	v_sub_f32_e32 v83, v92, v81
	v_cndmask_b32_e64 v83, v243, v83, s[24:25]
	v_fmamk_f32 v54, v54, 0x3fb8aa3b, v83
	v_fmamk_f32 v55, v55, 0x3fb8aa3b, v83
	v_fmamk_f32 v56, v56, 0x3fb8aa3b, v83
	v_fmamk_f32 v57, v57, 0x3fb8aa3b, v83
	v_exp_f32_e32 v54, v54
	v_exp_f32_e32 v55, v55
	v_exp_f32_e32 v56, v56
	v_exp_f32_e32 v57, v57
	v_fmamk_f32 v58, v58, 0x3fb8aa3b, v83
	v_fmamk_f32 v59, v59, 0x3fb8aa3b, v83
	v_fmamk_f32 v60, v60, 0x3fb8aa3b, v83
	v_fmamk_f32 v61, v61, 0x3fb8aa3b, v83
	v_exp_f32_e32 v58, v58
	v_exp_f32_e32 v59, v59
	v_exp_f32_e32 v60, v60
	v_exp_f32_e32 v61, v61
	v_fmamk_f32 v62, v62, 0x3fb8aa3b, v83
	v_fmamk_f32 v63, v63, 0x3fb8aa3b, v83
	v_fmamk_f32 v64, v64, 0x3fb8aa3b, v83
	v_fmamk_f32 v65, v65, 0x3fb8aa3b, v83
	v_exp_f32_e32 v62, v62
	v_exp_f32_e32 v63, v63
	v_exp_f32_e32 v64, v64
	v_exp_f32_e32 v65, v65
	v_fmamk_f32 v66, v66, 0x3fb8aa3b, v83
	v_fmamk_f32 v67, v67, 0x3fb8aa3b, v83
	v_fmamk_f32 v68, v68, 0x3fb8aa3b, v83
	v_fmamk_f32 v69, v69, 0x3fb8aa3b, v83
	v_exp_f32_e32 v66, v66
	v_exp_f32_e32 v67, v67
	v_exp_f32_e32 v68, v68
	v_exp_f32_e32 v69, v69
	s_nop 0
	v_add_f32_e32 v78, v54, v55
	v_add_f32_e32 v79, v56, v57
	v_add_f32_e32 v80, v58, v59
	v_add_f32_e32 v81, v60, v61
	v_add_f32_e32 v78, v78, v62
	v_add_f32_e32 v79, v79, v63
	v_add_f32_e32 v80, v80, v64
	v_add_f32_e32 v81, v81, v65
	v_add_f32_e32 v78, v78, v66
	v_add_f32_e32 v79, v79, v67
	v_add_f32_e32 v80, v80, v68
	v_add_f32_e32 v81, v81, v69
	v_add_f32_e32 v78, v78, v79
	v_add_f32_e32 v80, v80, v81
	v_add_f32_e32 v78, v78, v80
	v_cvt_pk_bf16_f32 v70, v54, v55
	v_cvt_pk_bf16_f32 v71, v56, v57
	v_cvt_pk_bf16_f32 v72, v58, v59
	v_cvt_pk_bf16_f32 v73, v60, v61
	v_cvt_pk_bf16_f32 v74, v62, v63
	v_cvt_pk_bf16_f32 v75, v64, v65
	v_cvt_pk_bf16_f32 v76, v66, v67
	v_cvt_pk_bf16_f32 v77, v68, v69
	v_mov_b32_e32 v79, v78
	s_nop 1
	v_permlane16_swap_b32_e32 v78, v79
	v_add_f32_e32 v78, v78, v79
	v_mov_b32_e32 v79, v78
	s_nop 1
	v_permlane32_swap_b32_e32 v78, v79
	v_add_f32_e32 v78, v78, v79
	v_fma_f32 v106, v106, v82, v78
	v_cmp_neq_f32_e64 s[4:5], 1.0, v82
	s_cmp_eq_u64 s[4:5], 0
	s_cbranch_scc1 .Lsl3_nosc_11
	v_pk_mul_f32 v[38:39], v[38:39], v[82:83] op_sel_hi:[1,0]
	v_pk_mul_f32 v[40:41], v[40:41], v[82:83] op_sel_hi:[1,0]
	v_pk_mul_f32 v[42:43], v[42:43], v[82:83] op_sel_hi:[1,0]
	v_pk_mul_f32 v[44:45], v[44:45], v[82:83] op_sel_hi:[1,0]
	v_pk_mul_f32 v[46:47], v[46:47], v[82:83] op_sel_hi:[1,0]
	v_pk_mul_f32 v[48:49], v[48:49], v[82:83] op_sel_hi:[1,0]
	v_pk_mul_f32 v[50:51], v[50:51], v[82:83] op_sel_hi:[1,0]
	v_pk_mul_f32 v[52:53], v[52:53], v[82:83] op_sel_hi:[1,0]

; __device__ __forceinline__ void nsa_unit(LAS unsigned char* lds, const Ctx& P, int l, int b, int hkv, int tb) {
;     ...
;                 for (int sb = 0; sb < 2; ++sb) { const bool selj = (ms[sb] >> j) & 1ull; const int tqs = tq[sb];
;                     if (far) {
;                         if (__builtin_amdgcn_ballot_w64(selj) == 0ull) continue;
;                         attn_step<64>(qf[sb], Ks, Vt, o[sb], m[sb], lsum[sb], alpha, pf, pf1, lane,
;                             [&](int, float s) { return selj ? s * LOG2E + cfar : NEGBIG; });
.Lsl3_skf_10:
	v_lshrrev_b64 v[78:79], s20, v[20:21]
	v_and_b32_e32 v78, 1, v78
	v_cmp_eq_u32_e64 s[24:25], 1, v78
	s_cmp_eq_u64 s[24:25], 0
	s_cbranch_scc1 .Lsl3_skf_12
	ds_read_b128 v[198:201], v190 offset:16384
	ds_read_b128 v[206:209], v190 offset:18944
	ds_read_b128 v[202:205], v190 offset:16448
	ds_read_b128 v[210:213], v190 offset:19008
	ds_read_b128 v[214:217], v190 offset:21504
	ds_read_b128 v[222:225], v190 offset:24064
	ds_read_b128 v[218:221], v190 offset:21568
	ds_read_b128 v[226:229], v190 offset:24128
	s_waitcnt lgkmcnt(6)
	v_mfma_f32_16x16x32_bf16 v[54:57], v[198:201], v[10:13], 0
	v_mfma_f32_16x16x32_bf16 v[58:61], v[206:209], v[10:13], 0
	s_waitcnt lgkmcnt(4)
	v_mfma_f32_16x16x32_bf16 v[54:57], v[202:205], v[14:17], v[54:57]
	v_mfma_f32_16x16x32_bf16 v[58:61], v[210:213], v[14:17], v[58:61]
	s_waitcnt lgkmcnt(2)
	v_mfma_f32_16x16x32_bf16 v[62:65], v[214:217], v[10:13], 0
	v_mfma_f32_16x16x32_bf16 v[66:69], v[222:225], v[10:13], 0
	s_waitcnt lgkmcnt(0)
	v_mfma_f32_16x16x32_bf16 v[62:65], v[218:221], v[14:17], v[62:65]
	v_mfma_f32_16x16x32_bf16 v[66:69], v[226:229], v[14:17], v[66:69]
	ds_read_b64_tr_b16 v[198:199], v191 offset:26624
	ds_read_b64_tr_b16 v[200:201], v191 offset:29184
	ds_read_b64_tr_b16 v[202:203], v191 offset:31744
	ds_read_b64_tr_b16 v[204:205], v191 offset:34304
	ds_read_b64_tr_b16 v[206:207], v191 offset:26656
	ds_read_b64_tr_b16 v[208:209], v191 offset:29216
	ds_read_b64_tr_b16 v[210:211], v191 offset:31776
	ds_read_b64_tr_b16 v[212:213], v191 offset:34336
	ds_read_b64_tr_b16 v[214:215], v191 offset:26688
	ds_read_b64_tr_b16 v[216:217], v191 offset:29248
	ds_read_b64_tr_b16 v[218:219], v191 offset:31808
	ds_read_b64_tr_b16 v[220:221], v191 offset:34368
	ds_read_b64_tr_b16 v[222:223], v191 offset:26720
	ds_read_b64_tr_b16 v[224:225], v191 offset:29280
	ds_read_b64_tr_b16 v[226:227], v191 offset:31840
	ds_read_b64_tr_b16 v[228:229], v191 offset:34400
	v_max3_f32 v78, v54, v55, v56
	v_max3_f32 v79, v57, v58, v59
	v_max3_f32 v80, v60, v61, v62
	v_max3_f32 v81, v63, v64, v65
	v_max3_f32 v83, v66, v67, v68
	v_max3_f32 v78, v78, v79, v69
	v_max3_f32 v80, v80, v81, v83
	v_max_f32_e32 v78, v78, v80
	v_mov_b32_e32 v79, v78
	s_nop 1
	v_permlane16_swap_b32_e32 v78, v79
	v_max_f32_e32 v78, v78, v79
	v_mov_b32_e32 v79, v78
	s_nop 1
	v_permlane32_swap_b32_e32 v78, v79
	v_max_f32_e32 v78, v78, v79
	v_fmamk_f32 v78, v78, 0x3fb8aa3b, v92
	v_cndmask_b32_e64 v78, v243, v78, s[24:25]
	v_max_f32_e32 v80, v93, v78
	v_max_f32_e32 v82, 0xe0ad78ec, v93
	v_max_f32_e32 v81, 0xe0ad78ec, v80
	v_sub_f32_e32 v82, v82, v81
	v_mov_b32_e32 v93, v80
	v_exp_f32_e32 v82, v82
	v_sub_f32_e32 v83, v92, v81
	v_cndmask_b32_e64 v83, v243, v83, s[24:25]
	v_fmamk_f32 v54, v54, 0x3fb8aa3b, v83
	v_fmamk_f32 v55, v55, 0x3fb8aa3b, v83
	v_fmamk_f32 v56, v56, 0x3fb8aa3b, v83
	v_fmamk_f32 v57, v57, 0x3fb8aa3b, v83
	v_exp_f32_e32 v54, v54
	v_exp_f32_e32 v55, v55
	v_exp_f32_e32 v56, v56
	v_exp_f32_e32 v57, v57
	v_fmamk_f32 v58, v58, 0x3fb8aa3b, v83
	v_fmamk_f32 v59, v59, 0x3fb8aa3b, v83
	v_fmamk_f32 v60, v60, 0x3fb8aa3b, v83
	v_fmamk_f32 v61, v61, 0x3fb8aa3b, v83
	v_exp_f32_e32 v58, v58
	v_exp_f32_e32 v59, v59
	v_exp_f32_e32 v60, v60
	v_exp_f32_e32 v61, v61
	v_fmamk_f32 v62, v62, 0x3fb8aa3b, v83
	v_fmamk_f32 v63, v63, 0x3fb8aa3b, v83
	v_fmamk_f32 v64, v64, 0x3fb8aa3b, v83
	v_fmamk_f32 v65, v65, 0x3fb8aa3b, v83
	v_exp_f32_e32 v62, v62
	v_exp_f32_e32 v63, v63
	v_exp_f32_e32 v64, v64
	v_exp_f32_e32 v65, v65
	v_fmamk_f32 v66, v66, 0x3fb8aa3b, v83
	v_fmamk_f32 v67, v67, 0x3fb8aa3b, v83
	v_fmamk_f32 v68, v68, 0x3fb8aa3b, v83
	v_fmamk_f32 v69, v69, 0x3fb8aa3b, v83
	v_exp_f32_e32 v66, v66
	v_exp_f32_e32 v67, v67
	v_exp_f32_e32 v68, v68
	v_exp_f32_e32 v69, v69
	s_nop 0
	v_add_f32_e32 v78, v54, v55
	v_add_f32_e32 v79, v56, v57
	v_add_f32_e32 v80, v58, v59
	v_add_f32_e32 v81, v60, v61
	v_add_f32_e32 v78, v78, v62
	v_add_f32_e32 v79, v79, v63
	v_add_f32_e32 v80, v80, v64
	v_add_f32_e32 v81, v81, v65
	v_add_f32_e32 v78, v78, v66
	v_add_f32_e32 v79, v79, v67
	v_add_f32_e32 v80, v80, v68
	v_add_f32_e32 v81, v81, v69
	v_add_f32_e32 v78, v78, v79
	v_add_f32_e32 v80, v80, v81
	v_add_f32_e32 v78, v78, v80
	v_cvt_pk_bf16_f32 v70, v54, v55
	v_cvt_pk_bf16_f32 v71, v56, v57
	v_cvt_pk_bf16_f32 v72, v58, v59
	v_cvt_pk_bf16_f32 v73, v60, v61
	v_cvt_pk_bf16_f32 v74, v62, v63
	v_cvt_pk_bf16_f32 v75, v64, v65
	v_cvt_pk_bf16_f32 v76, v66, v67
	v_cvt_pk_bf16_f32 v77, v68, v69
	v_mov_b32_e32 v79, v78
	s_nop 1
	v_permlane16_swap_b32_e32 v78, v79
	v_add_f32_e32 v78, v78, v79
	v_mov_b32_e32 v79, v78
	s_nop 1
	v_permlane32_swap_b32_e32 v78, v79
	v_add_f32_e32 v78, v78, v79
	v_fma_f32 v105, v105, v82, v78
	v_cmp_neq_f32_e64 s[4:5], 1.0, v82
	s_cmp_eq_u64 s[4:5], 0
	s_cbranch_scc1 .Lsl3_nosc_13
	v_pk_mul_f32 v[22:23], v[22:23], v[82:83] op_sel_hi:[1,0]
	v_pk_mul_f32 v[24:25], v[24:25], v[82:83] op_sel_hi:[1,0]
	v_pk_mul_f32 v[26:27], v[26:27], v[82:83] op_sel_hi:[1,0]
	v_pk_mul_f32 v[28:29], v[28:29], v[82:83] op_sel_hi:[1,0]
	v_pk_mul_f32 v[34:35], v[34:35], v[82:83] op_sel_hi:[1,0]
	v_pk_mul_f32 v[36:37], v[36:37], v[82:83] op_sel_hi:[1,0]
	v_pk_mul_f32 v[30:31], v[30:31], v[82:83] op_sel_hi:[1,0]
	v_pk_mul_f32 v[32:33], v[32:33], v[82:83] op_sel_hi:[1,0]

; #define LAS __attribute__((address_space(3)))
; __device__ __forceinline__ f32x4 mfma16(bf16x8 a, bf16x8 b, f32x4 c) { return __builtin_amdgcn_mfma_f32_16x16x32_bf16(a, b, c, 0, 0, 0); }
; template <int D, class SF>
; __device__ __forceinline__ void attn_step(const bf16x8 (&qf)[D / 32], const LAS bf16_t* Ks, const LAS bf16_t* Vt, f32x4 (&o)[D / 16], float& m, float& lsum, float& alpha_out, bf16x8& pf0_out, bf16x8& pf1_out, const int lane, SF sf) {
;     ...
; #pragma unroll
;     for (int t = 0; t < 4; ++t) s[t] = (f32x4){0.f, 0.f, 0.f, 0.f};
; #pragma unroll
;     for (int ks = 0; ks < D / 32; ++ks) {
; #pragma unroll
;         for (int t = 0; t < 4; ++t) { const bf16x8 kf = *(const LAS bf16x8*)(Ks + (16 * t + c) * KSTR + ks * 32 + 8 * i); s[t] = mfma16(kf, qf[ks], s[t]); }
;     }
;     float v[16];
; #pragma unroll
;     for (int t = 0; t < 4; ++t)
; #pragma unroll
;         for (int r = 0; r < 4; ++r) v[4 * t + r] = sf(16 * t + 4 * i + r, s[t][r]);
;     float mx = fmaxf(fmaxf(fmaxf(v[0], v[1]), fmaxf(v[2], v[3])), fmaxf(fmaxf(v[4], v[5]), fmaxf(v[6], v[7])));
;     mx = fmaxf(mx, fmaxf(fmaxf(fmaxf(v[8], v[9]), fmaxf(v[10], v[11])), fmaxf(fmaxf(v[12], v[13]), fmaxf(v[14], v[15]))));
;     mx = rows_max(mx);
;     const float mnew = fmaxf(m, mx);
;     const float mc = fmaxf(mnew, -1e20f);
;     const float alpha = __builtin_amdgcn_exp2f(fmaxf(m, -1e20f) - mc);
;     float p[16], rs = 0.f;
; #pragma unroll
;     for (int r = 0; r < 16; ++r) { p[r] = __builtin_amdgcn_exp2f(v[r] - mc); rs += p[r]; }
;     rs = rows_sum(rs);
;     lsum = lsum * alpha + rs; m = mnew;
; __device__ __forceinline__ void nsa_unit(LAS unsigned char* lds, const Ctx& P, int l, int b, int hkv, int tb) {
;     ...
;                     } else { const int kp0 = j * 64;
;                         attn_step<64>(qf[sb], Ks, Vt, o[sb], m[sb], lsum[sb], alpha, pf, pf1, lane,
;                             [&](int kk, float s) { const int dist = tqs - (kp0 + kk); return (selj && dist >= 0) ? s * LOG2E + lut[min((unsigned)dist, 1023u)] : NEGBIG; });
.Lsl3_nearx_8:
	v_lshrrev_b64 v[78:79], s20, v[18:19]
	v_and_b32_e32 v78, 1, v78
	v_cmp_eq_u32_e64 s[24:25], 1, v78
	s_cmp_eq_u64 s[24:25], 0
	s_cbranch_scc1 .Lsl3_skn_14
	v_sub_u32_e32 v78, v130, v139
	v_subrev_u32_e32 v78, s21, v78
	v_lshl_add_u32 v79, v78, 2, v131
	v_add_u32_e32 v79, 0xffffff34, v79
	ds_read_b32 v107, v79 offset:204
	ds_read_b32 v108, v79 offset:200
	ds_read_b32 v109, v79 offset:196
	ds_read_b32 v110, v79 offset:192
	ds_read_b32 v111, v79 offset:140
	ds_read_b32 v112, v79 offset:136
	ds_read_b32 v113, v79 offset:132
	ds_read_b32 v133, v79 offset:128
	ds_read_b128 v[198:201], v190 offset:16384
	ds_read_b128 v[206:209], v190 offset:18944
	ds_read_b128 v[202:205], v190 offset:16448
	ds_read_b128 v[210:213], v190 offset:19008
	ds_read_b128 v[214:217], v190 offset:21504
	ds_read_b128 v[222:225], v190 offset:24064
	ds_read_b128 v[218:221], v190 offset:21568
	ds_read_b128 v[226:229], v190 offset:24128
	s_waitcnt lgkmcnt(6)
	v_mfma_f32_16x16x32_bf16 v[54:57], v[198:201], v[2:5], 0
	v_mfma_f32_16x16x32_bf16 v[58:61], v[206:209], v[2:5], 0
	s_waitcnt lgkmcnt(4)
	v_mfma_f32_16x16x32_bf16 v[54:57], v[202:205], v[6:9], v[54:57]
	v_mfma_f32_16x16x32_bf16 v[58:61], v[210:213], v[6:9], v[58:61]
	s_waitcnt lgkmcnt(2)
	v_mfma_f32_16x16x32_bf16 v[62:65], v[214:217], v[2:5], 0
	v_mfma_f32_16x16x32_bf16 v[66:69], v[222:225], v[2:5], 0
	s_waitcnt lgkmcnt(0)
	v_mfma_f32_16x16x32_bf16 v[62:65], v[218:221], v[6:9], v[62:65]
	v_mfma_f32_16x16x32_bf16 v[66:69], v[226:229], v[6:9], v[66:69]
	ds_read_b64_tr_b16 v[198:199], v191 offset:26624
	ds_read_b64_tr_b16 v[200:201], v191 offset:29184
	ds_read_b64_tr_b16 v[202:203], v191 offset:31744
	ds_read_b64_tr_b16 v[204:205], v191 offset:34304
	ds_read_b64_tr_b16 v[206:207], v191 offset:26656
	ds_read_b64_tr_b16 v[208:209], v191 offset:29216
	ds_read_b64_tr_b16 v[210:211], v191 offset:31776
	v_fmamk_f32 v54, v54, 0x3fb8aa3b, v107
	v_fmamk_f32 v55, v55, 0x3fb8aa3b, v108
	v_fmamk_f32 v56, v56, 0x3fb8aa3b, v109
	v_fmamk_f32 v57, v57, 0x3fb8aa3b, v110
	v_fmamk_f32 v58, v58, 0x3fb8aa3b, v111
	v_fmamk_f32 v59, v59, 0x3fb8aa3b, v112
	v_fmamk_f32 v60, v60, 0x3fb8aa3b, v113
	v_fmamk_f32 v61, v61, 0x3fb8aa3b, v133
	ds_read_b32 v107, v79 offset:76
	ds_read_b32 v108, v79 offset:72
	ds_read_b32 v109, v79 offset:68
	ds_read_b32 v110, v79 offset:64
	ds_read_b32 v111, v79 offset:12
	ds_read_b32 v112, v79 offset:8
	ds_read_b32 v113, v79 offset:4
	ds_read_b32 v133, v79 offset:0
	ds_read_b64_tr_b16 v[212:213], v191 offset:34336
	ds_read_b64_tr_b16 v[214:215], v191 offset:26688
	ds_read_b64_tr_b16 v[216:217], v191 offset:29248
	ds_read_b64_tr_b16 v[218:219], v191 offset:31808
	ds_read_b64_tr_b16 v[220:221], v191 offset:34368
	ds_read_b64_tr_b16 v[222:223], v191 offset:26720
	ds_read_b64_tr_b16 v[224:225], v191 offset:29280
	ds_read_b64_tr_b16 v[226:227], v191 offset:31840
	ds_read_b64_tr_b16 v[228:229], v191 offset:34400
	s_waitcnt lgkmcnt(9)
	v_fmamk_f32 v62, v62, 0x3fb8aa3b, v107
	v_fmamk_f32 v63, v63, 0x3fb8aa3b, v108
	v_fmamk_f32 v64, v64, 0x3fb8aa3b, v109
	v_fmamk_f32 v65, v65, 0x3fb8aa3b, v110
	v_fmamk_f32 v66, v66, 0x3fb8aa3b, v111
	v_fmamk_f32 v67, v67, 0x3fb8aa3b, v112
	v_fmamk_f32 v68, v68, 0x3fb8aa3b, v113
	v_fmamk_f32 v69, v69, 0x3fb8aa3b, v133
	v_max3_f32 v84, v54, v55, v56
	v_max3_f32 v79, v57, v58, v59
	v_max3_f32 v80, v60, v61, v62
	v_max3_f32 v81, v63, v64, v65
	v_max3_f32 v83, v66, v67, v68
	v_max3_f32 v84, v84, v79, v69
	v_max3_f32 v80, v80, v81, v83
	v_max_f32_e32 v84, v84, v80
	v_mov_b32_e32 v79, v84
	s_nop 1
	v_permlane16_swap_b32_e32 v84, v79
	v_max_f32_e32 v84, v84, v79
	v_mov_b32_e32 v79, v84
	s_nop 1
	v_permlane32_swap_b32_e32 v84, v79
	v_max_f32_e32 v84, v84, v79
	v_cndmask_b32_e64 v84, v243, v84, s[24:25]
	v_max_f32_e32 v80, v100, v84
	v_max_f32_e32 v82, 0xe0ad78ec, v100
	v_max_f32_e32 v81, 0xe0ad78ec, v80
	v_sub_f32_e32 v82, v82, v81
	v_mov_b32_e32 v100, v80
	v_exp_f32_e32 v82, v82
	v_mov_b32_e32 v83, 0x7149f2ca
	v_cndmask_b32_e64 v83, v83, v81, s[24:25]
	v_sub_f32_e32 v54, v54, v83
	v_sub_f32_e32 v55, v55, v83
	v_sub_f32_e32 v56, v56, v83
	v_sub_f32_e32 v57, v57, v83
	v_exp_f32_e32 v54, v54
	v_exp_f32_e32 v55, v55
	v_exp_f32_e32 v56, v56
	v_exp_f32_e32 v57, v57
	v_sub_f32_e32 v58, v58, v83
	v_sub_f32_e32 v59, v59, v83
	v_sub_f32_e32 v60, v60, v83
	v_sub_f32_e32 v61, v61, v83
	v_exp_f32_e32 v58, v58
	v_exp_f32_e32 v59, v59
	v_exp_f32_e32 v60, v60
	v_exp_f32_e32 v61, v61
	v_sub_f32_e32 v62, v62, v83
	v_sub_f32_e32 v63, v63, v83
	v_sub_f32_e32 v64, v64, v83
	v_sub_f32_e32 v65, v65, v83
	v_exp_f32_e32 v62, v62
	v_exp_f32_e32 v63, v63
	v_exp_f32_e32 v64, v64
	v_exp_f32_e32 v65, v65
	v_sub_f32_e32 v66, v66, v83
	v_sub_f32_e32 v67, v67, v83
	v_sub_f32_e32 v68, v68, v83
	v_sub_f32_e32 v69, v69, v83
	v_exp_f32_e32 v66, v66
	v_exp_f32_e32 v67, v67
	v_exp_f32_e32 v68, v68
	v_exp_f32_e32 v69, v69
	s_nop 0
	v_add_f32_e32 v78, v54, v55
	v_add_f32_e32 v79, v56, v57
	v_add_f32_e32 v80, v58, v59
	v_add_f32_e32 v81, v60, v61
	v_add_f32_e32 v78, v78, v62
	v_add_f32_e32 v79, v79, v63
	v_add_f32_e32 v80, v80, v64
	v_add_f32_e32 v81, v81, v65
	v_add_f32_e32 v78, v78, v66
	v_add_f32_e32 v79, v79, v67
	v_add_f32_e32 v80, v80, v68
	v_add_f32_e32 v81, v81, v69
	v_add_f32_e32 v78, v78, v79
	v_add_f32_e32 v80, v80, v81
	v_add_f32_e32 v78, v78, v80
	v_cvt_pk_bf16_f32 v70, v54, v55
	v_cvt_pk_bf16_f32 v71, v56, v57
	v_cvt_pk_bf16_f32 v72, v58, v59
	v_cvt_pk_bf16_f32 v73, v60, v61
	v_cvt_pk_bf16_f32 v74, v62, v63
	v_cvt_pk_bf16_f32 v75, v64, v65
	v_cvt_pk_bf16_f32 v76, v66, v67
	v_cvt_pk_bf16_f32 v77, v68, v69
	v_mov_b32_e32 v79, v78
	s_nop 1
	v_permlane16_swap_b32_e32 v78, v79
	v_add_f32_e32 v78, v78, v79
	v_mov_b32_e32 v79, v78
	s_nop 1
	v_permlane32_swap_b32_e32 v78, v79
	v_add_f32_e32 v78, v78, v79
	v_fma_f32 v106, v106, v82, v78
	v_cmp_neq_f32_e64 s[4:5], 1.0, v82
	s_cmp_eq_u64 s[4:5], 0
	s_cbranch_scc1 .Lsl3_nosc_15
	v_pk_mul_f32 v[38:39], v[38:39], v[82:83] op_sel_hi:[1,0]
	v_pk_mul_f32 v[40:41], v[40:41], v[82:83] op_sel_hi:[1,0]
	v_pk_mul_f32 v[42:43], v[42:43], v[82:83] op_sel_hi:[1,0]
	v_pk_mul_f32 v[44:45], v[44:45], v[82:83] op_sel_hi:[1,0]
	v_pk_mul_f32 v[46:47], v[46:47], v[82:83] op_sel_hi:[1,0]
	v_pk_mul_f32 v[48:49], v[48:49], v[82:83] op_sel_hi:[1,0]
	v_pk_mul_f32 v[50:51], v[50:51], v[82:83] op_sel_hi:[1,0]
	v_pk_mul_f32 v[52:53], v[52:53], v[82:83] op_sel_hi:[1,0]

; #define LAS __attribute__((address_space(3)))
; __device__ __forceinline__ f32x4 mfma16(bf16x8 a, bf16x8 b, f32x4 c) { return __builtin_amdgcn_mfma_f32_16x16x32_bf16(a, b, c, 0, 0, 0); }
; template <int D, class SF>
; __device__ __forceinline__ void attn_step(const bf16x8 (&qf)[D / 32], const LAS bf16_t* Ks, const LAS bf16_t* Vt, f32x4 (&o)[D / 16], float& m, float& lsum, float& alpha_out, bf16x8& pf0_out, bf16x8& pf1_out, const int lane, SF sf) {
;     ...
; #pragma unroll
;     for (int t = 0; t < 4; ++t) s[t] = (f32x4){0.f, 0.f, 0.f, 0.f};
; #pragma unroll
;     for (int ks = 0; ks < D / 32; ++ks) {
; #pragma unroll
;         for (int t = 0; t < 4; ++t) { const bf16x8 kf = *(const LAS bf16x8*)(Ks + (16 * t + c) * KSTR + ks * 32 + 8 * i); s[t] = mfma16(kf, qf[ks], s[t]); }
;     }
;     float v[16];
; #pragma unroll
;     for (int t = 0; t < 4; ++t)
; #pragma unroll
;         for (int r = 0; r < 4; ++r) v[4 * t + r] = sf(16 * t + 4 * i + r, s[t][r]);
;     float mx = fmaxf(fmaxf(fmaxf(v[0], v[1]), fmaxf(v[2], v[3])), fmaxf(fmaxf(v[4], v[5]), fmaxf(v[6], v[7])));
;     mx = fmaxf(mx, fmaxf(fmaxf(fmaxf(v[8], v[9]), fmaxf(v[10], v[11])), fmaxf(fmaxf(v[12], v[13]), fmaxf(v[14], v[15]))));
;     mx = rows_max(mx);
;     const float mnew = fmaxf(m, mx);
;     const float mc = fmaxf(mnew, -1e20f);
;     const float alpha = __builtin_amdgcn_exp2f(fmaxf(m, -1e20f) - mc);
;     float p[16], rs = 0.f;
; #pragma unroll
;     for (int r = 0; r < 16; ++r) { p[r] = __builtin_amdgcn_exp2f(v[r] - mc); rs += p[r]; }
;     rs = rows_sum(rs);
;     lsum = lsum * alpha + rs; m = mnew;
; __device__ __forceinline__ void nsa_unit(LAS unsigned char* lds, const Ctx& P, int l, int b, int hkv, int tb) {
;     ...
;                     } else { const int kp0 = j * 64;
;                         attn_step<64>(qf[sb], Ks, Vt, o[sb], m[sb], lsum[sb], alpha, pf, pf1, lane,
;                             [&](int kk, float s) { const int dist = tqs - (kp0 + kk); return (selj && dist >= 0) ? s * LOG2E + lut[min((unsigned)dist, 1023u)] : NEGBIG; });
.Lsl3_skn_14:
	v_lshrrev_b64 v[78:79], s20, v[20:21]
	v_and_b32_e32 v78, 1, v78
	v_cmp_eq_u32_e64 s[24:25], 1, v78
	s_cmp_eq_u64 s[24:25], 0
	s_cbranch_scc1 .Lsl3_skn_16
	v_sub_u32_e32 v78, v98, v139
	v_subrev_u32_e32 v78, s21, v78
	v_lshl_add_u32 v79, v78, 2, v131
	v_add_u32_e32 v79, 0xffffff34, v79
	ds_read_b32 v107, v79 offset:204
	ds_read_b32 v108, v79 offset:200
	ds_read_b32 v109, v79 offset:196
	ds_read_b32 v110, v79 offset:192
	ds_read_b32 v111, v79 offset:140
	ds_read_b32 v112, v79 offset:136
	ds_read_b32 v113, v79 offset:132
	ds_read_b32 v133, v79 offset:128
	ds_read_b128 v[198:201], v190 offset:16384
	ds_read_b128 v[206:209], v190 offset:18944
	ds_read_b128 v[202:205], v190 offset:16448
	ds_read_b128 v[210:213], v190 offset:19008
	ds_read_b128 v[214:217], v190 offset:21504
	ds_read_b128 v[222:225], v190 offset:24064
	ds_read_b128 v[218:221], v190 offset:21568
	ds_read_b128 v[226:229], v190 offset:24128
	s_waitcnt lgkmcnt(6)
	v_mfma_f32_16x16x32_bf16 v[54:57], v[198:201], v[10:13], 0
	v_mfma_f32_16x16x32_bf16 v[58:61], v[206:209], v[10:13], 0
	s_waitcnt lgkmcnt(4)
	v_mfma_f32_16x16x32_bf16 v[54:57], v[202:205], v[14:17], v[54:57]
	v_mfma_f32_16x16x32_bf16 v[58:61], v[210:213], v[14:17], v[58:61]
	s_waitcnt lgkmcnt(2)
	v_mfma_f32_16x16x32_bf16 v[62:65], v[214:217], v[10:13], 0
	v_mfma_f32_16x16x32_bf16 v[66:69], v[222:225], v[10:13], 0
	s_waitcnt lgkmcnt(0)
	v_mfma_f32_16x16x32_bf16 v[62:65], v[218:221], v[14:17], v[62:65]
	v_mfma_f32_16x16x32_bf16 v[66:69], v[226:229], v[14:17], v[66:69]
	ds_read_b64_tr_b16 v[198:199], v191 offset:26624
	ds_read_b64_tr_b16 v[200:201], v191 offset:29184
	ds_read_b64_tr_b16 v[202:203], v191 offset:31744
	ds_read_b64_tr_b16 v[204:205], v191 offset:34304
	ds_read_b64_tr_b16 v[206:207], v191 offset:26656
	ds_read_b64_tr_b16 v[208:209], v191 offset:29216
	ds_read_b64_tr_b16 v[210:211], v191 offset:31776
	v_fmamk_f32 v54, v54, 0x3fb8aa3b, v107
	v_fmamk_f32 v55, v55, 0x3fb8aa3b, v108
	v_fmamk_f32 v56, v56, 0x3fb8aa3b, v109
	v_fmamk_f32 v57, v57, 0x3fb8aa3b, v110
	v_fmamk_f32 v58, v58, 0x3fb8aa3b, v111
	v_fmamk_f32 v59, v59, 0x3fb8aa3b, v112
	v_fmamk_f32 v60, v60, 0x3fb8aa3b, v113
	v_fmamk_f32 v61, v61, 0x3fb8aa3b, v133
	ds_read_b32 v107, v79 offset:76
	ds_read_b32 v108, v79 offset:72
	ds_read_b32 v109, v79 offset:68
	ds_read_b32 v110, v79 offset:64
	ds_read_b32 v111, v79 offset:12
	ds_read_b32 v112, v79 offset:8
	ds_read_b32 v113, v79 offset:4
	ds_read_b32 v133, v79 offset:0
	ds_read_b64_tr_b16 v[212:213], v191 offset:34336
	ds_read_b64_tr_b16 v[214:215], v191 offset:26688
	ds_read_b64_tr_b16 v[216:217], v191 offset:29248
	ds_read_b64_tr_b16 v[218:219], v191 offset:31808
	ds_read_b64_tr_b16 v[220:221], v191 offset:34368
	ds_read_b64_tr_b16 v[222:223], v191 offset:26720
	ds_read_b64_tr_b16 v[224:225], v191 offset:29280
	ds_read_b64_tr_b16 v[226:227], v191 offset:31840
	ds_read_b64_tr_b16 v[228:229], v191 offset:34400
	s_waitcnt lgkmcnt(9)
	v_fmamk_f32 v62, v62, 0x3fb8aa3b, v107
	v_fmamk_f32 v63, v63, 0x3fb8aa3b, v108
	v_fmamk_f32 v64, v64, 0x3fb8aa3b, v109
	v_fmamk_f32 v65, v65, 0x3fb8aa3b, v110
	v_fmamk_f32 v66, v66, 0x3fb8aa3b, v111
	v_fmamk_f32 v67, v67, 0x3fb8aa3b, v112
	v_fmamk_f32 v68, v68, 0x3fb8aa3b, v113
	v_fmamk_f32 v69, v69, 0x3fb8aa3b, v133
	v_max3_f32 v84, v54, v55, v56
	v_max3_f32 v79, v57, v58, v59
	v_max3_f32 v80, v60, v61, v62
	v_max3_f32 v81, v63, v64, v65
	v_max3_f32 v83, v66, v67, v68
	v_max3_f32 v84, v84, v79, v69
	v_max3_f32 v80, v80, v81, v83
	v_max_f32_e32 v84, v84, v80
	v_mov_b32_e32 v79, v84
	s_nop 1
	v_permlane16_swap_b32_e32 v84, v79
	v_max_f32_e32 v84, v84, v79
	v_mov_b32_e32 v79, v84
	s_nop 1
	v_permlane32_swap_b32_e32 v84, v79
	v_max_f32_e32 v84, v84, v79
	v_cndmask_b32_e64 v84, v243, v84, s[24:25]
	v_max_f32_e32 v80, v93, v84
	v_max_f32_e32 v82, 0xe0ad78ec, v93
	v_max_f32_e32 v81, 0xe0ad78ec, v80
	v_sub_f32_e32 v82, v82, v81
	v_mov_b32_e32 v93, v80
	v_exp_f32_e32 v82, v82
	v_mov_b32_e32 v83, 0x7149f2ca
	v_cndmask_b32_e64 v83, v83, v81, s[24:25]
	v_sub_f32_e32 v54, v54, v83
	v_sub_f32_e32 v55, v55, v83
	v_sub_f32_e32 v56, v56, v83
	v_sub_f32_e32 v57, v57, v83
	v_exp_f32_e32 v54, v54
	v_exp_f32_e32 v55, v55
	v_exp_f32_e32 v56, v56
	v_exp_f32_e32 v57, v57
	v_sub_f32_e32 v58, v58, v83
	v_sub_f32_e32 v59, v59, v83
	v_sub_f32_e32 v60, v60, v83
	v_sub_f32_e32 v61, v61, v83
	v_exp_f32_e32 v58, v58
	v_exp_f32_e32 v59, v59
	v_exp_f32_e32 v60, v60
	v_exp_f32_e32 v61, v61
	v_sub_f32_e32 v62, v62, v83
	v_sub_f32_e32 v63, v63, v83
	v_sub_f32_e32 v64, v64, v83
	v_sub_f32_e32 v65, v65, v83
	v_exp_f32_e32 v62, v62
	v_exp_f32_e32 v63, v63
	v_exp_f32_e32 v64, v64
	v_exp_f32_e32 v65, v65
	v_sub_f32_e32 v66, v66, v83
	v_sub_f32_e32 v67, v67, v83
	v_sub_f32_e32 v68, v68, v83
	v_sub_f32_e32 v69, v69, v83
	v_exp_f32_e32 v66, v66
	v_exp_f32_e32 v67, v67
	v_exp_f32_e32 v68, v68
	v_exp_f32_e32 v69, v69
	s_nop 0
	v_add_f32_e32 v78, v54, v55
	v_add_f32_e32 v79, v56, v57
	v_add_f32_e32 v80, v58, v59
	v_add_f32_e32 v81, v60, v61
	v_add_f32_e32 v78, v78, v62
	v_add_f32_e32 v79, v79, v63
	v_add_f32_e32 v80, v80, v64
	v_add_f32_e32 v81, v81, v65
	v_add_f32_e32 v78, v78, v66
	v_add_f32_e32 v79, v79, v67
	v_add_f32_e32 v80, v80, v68
	v_add_f32_e32 v81, v81, v69
	v_add_f32_e32 v78, v78, v79
	v_add_f32_e32 v80, v80, v81
	v_add_f32_e32 v78, v78, v80
	v_cvt_pk_bf16_f32 v70, v54, v55
	v_cvt_pk_bf16_f32 v71, v56, v57
	v_cvt_pk_bf16_f32 v72, v58, v59
	v_cvt_pk_bf16_f32 v73, v60, v61
	v_cvt_pk_bf16_f32 v74, v62, v63
	v_cvt_pk_bf16_f32 v75, v64, v65
	v_cvt_pk_bf16_f32 v76, v66, v67
	v_cvt_pk_bf16_f32 v77, v68, v69
	v_mov_b32_e32 v79, v78
	s_nop 1
	v_permlane16_swap_b32_e32 v78, v79
	v_add_f32_e32 v78, v78, v79
	v_mov_b32_e32 v79, v78
	s_nop 1
	v_permlane32_swap_b32_e32 v78, v79
	v_add_f32_e32 v78, v78, v79
	v_fma_f32 v105, v105, v82, v78
	v_cmp_neq_f32_e64 s[4:5], 1.0, v82
	s_cmp_eq_u64 s[4:5], 0
	s_cbranch_scc1 .Lsl3_nosc_17
	v_pk_mul_f32 v[22:23], v[22:23], v[82:83] op_sel_hi:[1,0]
	v_pk_mul_f32 v[24:25], v[24:25], v[82:83] op_sel_hi:[1,0]
	v_pk_mul_f32 v[26:27], v[26:27], v[82:83] op_sel_hi:[1,0]
	v_pk_mul_f32 v[28:29], v[28:29], v[82:83] op_sel_hi:[1,0]
	v_pk_mul_f32 v[34:35], v[34:35], v[82:83] op_sel_hi:[1,0]
	v_pk_mul_f32 v[36:37], v[36:37], v[82:83] op_sel_hi:[1,0]
	v_pk_mul_f32 v[30:31], v[30:31], v[82:83] op_sel_hi:[1,0]
	v_pk_mul_f32 v[32:33], v[32:33], v[82:83] op_sel_hi:[1,0]

; #define LAS __attribute__((address_space(3)))
; __device__ __forceinline__ f32x4 mfma16(bf16x8 a, bf16x8 b, f32x4 c) { return __builtin_amdgcn_mfma_f32_16x16x32_bf16(a, b, c, 0, 0, 0); }
; template <int D, class SF>
; __device__ __forceinline__ void attn_step(const bf16x8 (&qf)[D / 32], const LAS bf16_t* Ks, const LAS bf16_t* Vt, f32x4 (&o)[D / 16], float& m, float& lsum, float& alpha_out, bf16x8& pf0_out, bf16x8& pf1_out, const int lane, SF sf) {
;     ...
; #pragma unroll
;     for (int t = 0; t < 4; ++t) s[t] = (f32x4){0.f, 0.f, 0.f, 0.f};
; #pragma unroll
;     for (int ks = 0; ks < D / 32; ++ks) {
; #pragma unroll
;         for (int t = 0; t < 4; ++t) { const bf16x8 kf = *(const LAS bf16x8*)(Ks + (16 * t + c) * KSTR + ks * 32 + 8 * i); s[t] = mfma16(kf, qf[ks], s[t]); }
;     }
;     float v[16];
; #pragma unroll
;     for (int t = 0; t < 4; ++t)
; #pragma unroll
;         for (int r = 0; r < 4; ++r) v[4 * t + r] = sf(16 * t + 4 * i + r, s[t][r]);
;     float mx = fmaxf(fmaxf(fmaxf(v[0], v[1]), fmaxf(v[2], v[3])), fmaxf(fmaxf(v[4], v[5]), fmaxf(v[6], v[7])));
;     mx = fmaxf(mx, fmaxf(fmaxf(fmaxf(v[8], v[9]), fmaxf(v[10], v[11])), fmaxf(fmaxf(v[12], v[13]), fmaxf(v[14], v[15]))));
;     mx = rows_max(mx);
;     const float mnew = fmaxf(m, mx);
;     const float mc = fmaxf(mnew, -1e20f);
;     const float alpha = __builtin_amdgcn_exp2f(fmaxf(m, -1e20f) - mc);
; __device__ __forceinline__ void nsa_unit(LAS unsigned char* lds, const Ctx& P, int l, int b, int hkv, int tb) {
;     ...
;                     } else { const int kp0 = j * 64;
;                         attn_step<64>(qf[sb], Ks, Vt, o[sb], m[sb], lsum[sb], alpha, pf, pf1, lane,
;                             [&](int kk, float s) { const int dist = tqs - (kp0 + kk); return (selj && dist >= 0) ? s * LOG2E + lut[min((unsigned)dist, 1023u)] : NEGBIG; });
.Lsl3_diagx_9:
	v_lshrrev_b64 v[78:79], s20, v[18:19]
	v_and_b32_e32 v78, 1, v78
	v_cmp_eq_u32_e64 s[24:25], 1, v78
	s_cmp_eq_u64 s[24:25], 0
	s_cbranch_scc1 .Lsl3_skd_18
	v_sub_u32_e32 v78, v130, v139
	v_subrev_u32_e32 v78, s21, v78
	v_subrev_u32_e32 v107, 0, v78
	v_min_u32_e32 v107, 0x3ff, v107
	v_lshl_add_u32 v107, v107, 2, v131
	ds_read_b32 v107, v107
	v_subrev_u32_e32 v108, 1, v78
	v_min_u32_e32 v108, 0x3ff, v108
	v_lshl_add_u32 v108, v108, 2, v131
	ds_read_b32 v108, v108
	v_subrev_u32_e32 v109, 2, v78
	v_min_u32_e32 v109, 0x3ff, v109
	v_lshl_add_u32 v109, v109, 2, v131
	ds_read_b32 v109, v109
	v_subrev_u32_e32 v110, 3, v78
	v_min_u32_e32 v110, 0x3ff, v110
	v_lshl_add_u32 v110, v110, 2, v131
	ds_read_b32 v110, v110
	v_subrev_u32_e32 v111, 16, v78
	v_min_u32_e32 v111, 0x3ff, v111
	v_lshl_add_u32 v111, v111, 2, v131
	ds_read_b32 v111, v111
	v_subrev_u32_e32 v112, 17, v78
	v_min_u32_e32 v112, 0x3ff, v112
	v_lshl_add_u32 v112, v112, 2, v131
	ds_read_b32 v112, v112
	v_subrev_u32_e32 v113, 18, v78
	v_min_u32_e32 v113, 0x3ff, v113
	v_lshl_add_u32 v113, v113, 2, v131
	ds_read_b32 v113, v113
	v_subrev_u32_e32 v133, 19, v78
	v_min_u32_e32 v133, 0x3ff, v133
	v_lshl_add_u32 v133, v133, 2, v131
	ds_read_b32 v133, v133
	ds_read_b128 v[198:201], v190 offset:16384
	ds_read_b128 v[206:209], v190 offset:18944
	ds_read_b128 v[202:205], v190 offset:16448
	ds_read_b128 v[210:213], v190 offset:19008
	ds_read_b128 v[214:217], v190 offset:21504
	ds_read_b128 v[222:225], v190 offset:24064
	ds_read_b128 v[218:221], v190 offset:21568
	ds_read_b128 v[226:229], v190 offset:24128
	s_waitcnt lgkmcnt(6)
	v_mfma_f32_16x16x32_bf16 v[54:57], v[198:201], v[2:5], 0
	v_mfma_f32_16x16x32_bf16 v[58:61], v[206:209], v[2:5], 0
	s_waitcnt lgkmcnt(4)
	v_mfma_f32_16x16x32_bf16 v[54:57], v[202:205], v[6:9], v[54:57]
	v_mfma_f32_16x16x32_bf16 v[58:61], v[210:213], v[6:9], v[58:61]
	s_waitcnt lgkmcnt(2)
	v_mfma_f32_16x16x32_bf16 v[62:65], v[214:217], v[2:5], 0
	v_mfma_f32_16x16x32_bf16 v[66:69], v[222:225], v[2:5], 0
	s_waitcnt lgkmcnt(0)
	v_mfma_f32_16x16x32_bf16 v[62:65], v[218:221], v[6:9], v[62:65]
	v_mfma_f32_16x16x32_bf16 v[66:69], v[226:229], v[6:9], v[66:69]
	ds_read_b64_tr_b16 v[198:199], v191 offset:26624
	ds_read_b64_tr_b16 v[200:201], v191 offset:29184
	ds_read_b64_tr_b16 v[202:203], v191 offset:31744
	ds_read_b64_tr_b16 v[204:205], v191 offset:34304
	ds_read_b64_tr_b16 v[206:207], v191 offset:26656
	ds_read_b64_tr_b16 v[208:209], v191 offset:29216
	ds_read_b64_tr_b16 v[210:211], v191 offset:31776
	v_fmamk_f32 v54, v54, 0x3fb8aa3b, v107
	v_fmamk_f32 v55, v55, 0x3fb8aa3b, v108
	v_fmamk_f32 v56, v56, 0x3fb8aa3b, v109
	v_fmamk_f32 v57, v57, 0x3fb8aa3b, v110
	v_fmamk_f32 v58, v58, 0x3fb8aa3b, v111
	v_fmamk_f32 v59, v59, 0x3fb8aa3b, v112
	v_fmamk_f32 v60, v60, 0x3fb8aa3b, v113
	v_fmamk_f32 v61, v61, 0x3fb8aa3b, v133
	v_cmp_le_i32_e32 vcc, 0, v78
	s_nop 1
	v_cndmask_b32_e32 v54, v243, v54, vcc
	v_cmp_le_i32_e32 vcc, 1, v78
	s_nop 1
	v_cndmask_b32_e32 v55, v243, v55, vcc
	v_cmp_le_i32_e32 vcc, 2, v78
	s_nop 1
	v_cndmask_b32_e32 v56, v243, v56, vcc
	v_cmp_le_i32_e32 vcc, 3, v78
	s_nop 1
	v_cndmask_b32_e32 v57, v243, v57, vcc
	v_cmp_le_i32_e32 vcc, 16, v78
	s_nop 1
	v_cndmask_b32_e32 v58, v243, v58, vcc
	v_cmp_le_i32_e32 vcc, 17, v78
	s_nop 1
	v_cndmask_b32_e32 v59, v243, v59, vcc
	v_cmp_le_i32_e32 vcc, 18, v78
	s_nop 1
	v_cndmask_b32_e32 v60, v243, v60, vcc
	v_cmp_le_i32_e32 vcc, 19, v78
	s_nop 1
	v_cndmask_b32_e32 v61, v243, v61, vcc
	v_subrev_u32_e32 v107, 32, v78
	v_min_u32_e32 v107, 0x3ff, v107
	v_lshl_add_u32 v107, v107, 2, v131
	ds_read_b32 v107, v107
	v_subrev_u32_e32 v108, 33, v78
	v_min_u32_e32 v108, 0x3ff, v108
	v_lshl_add_u32 v108, v108, 2, v131
	ds_read_b32 v108, v108
	v_subrev_u32_e32 v109, 34, v78
	v_min_u32_e32 v109, 0x3ff, v109
	v_lshl_add_u32 v109, v109, 2, v131
	ds_read_b32 v109, v109
	v_subrev_u32_e32 v110, 35, v78
	v_min_u32_e32 v110, 0x3ff, v110
	v_lshl_add_u32 v110, v110, 2, v131
	ds_read_b32 v110, v110
	v_subrev_u32_e32 v111, 48, v78
	v_min_u32_e32 v111, 0x3ff, v111
	v_lshl_add_u32 v111, v111, 2, v131
	ds_read_b32 v111, v111
	v_subrev_u32_e32 v112, 49, v78
	v_min_u32_e32 v112, 0x3ff, v112
	v_lshl_add_u32 v112, v112, 2, v131
	ds_read_b32 v112, v112
	v_subrev_u32_e32 v113, 50, v78
	v_min_u32_e32 v113, 0x3ff, v113
	v_lshl_add_u32 v113, v113, 2, v131
	ds_read_b32 v113, v113
	v_subrev_u32_e32 v133, 51, v78
	v_min_u32_e32 v133, 0x3ff, v133
	v_lshl_add_u32 v133, v133, 2, v131
	ds_read_b32 v133, v133
	ds_read_b64_tr_b16 v[212:213], v191 offset:34336
	ds_read_b64_tr_b16 v[214:215], v191 offset:26688
	ds_read_b64_tr_b16 v[216:217], v191 offset:29248
	ds_read_b64_tr_b16 v[218:219], v191 offset:31808
	ds_read_b64_tr_b16 v[220:221], v191 offset:34368
	ds_read_b64_tr_b16 v[222:223], v191 offset:26720
	ds_read_b64_tr_b16 v[224:225], v191 offset:29280
	ds_read_b64_tr_b16 v[226:227], v191 offset:31840
	ds_read_b64_tr_b16 v[228:229], v191 offset:34400
	s_waitcnt lgkmcnt(9)
; __device__ __forceinline__ unsigned cvt_pk_bf16(float lo, float hi) { unsigned r; asm("v_cvt_pk_bf16_f32 %0, %1, %2" : "=v"(r) : "v"(lo), "v"(hi)); return r; }
; template <int D, class SF>
; __device__ __forceinline__ void attn_step(const bf16x8 (&qf)[D / 32], const LAS bf16_t* Ks, const LAS bf16_t* Vt, f32x4 (&o)[D / 16], float& m, float& lsum, float& alpha_out, bf16x8& pf0_out, bf16x8& pf1_out, const int lane, SF sf) {
;     ...
;     for (int t = 0; t < 4; ++t)
; #pragma unroll
;         for (int r = 0; r < 4; ++r) v[4 * t + r] = sf(16 * t + 4 * i + r, s[t][r]);
;     float mx = fmaxf(fmaxf(fmaxf(v[0], v[1]), fmaxf(v[2], v[3])), fmaxf(fmaxf(v[4], v[5]), fmaxf(v[6], v[7])));
;     mx = fmaxf(mx, fmaxf(fmaxf(fmaxf(v[8], v[9]), fmaxf(v[10], v[11])), fmaxf(fmaxf(v[12], v[13]), fmaxf(v[14], v[15]))));
;     mx = rows_max(mx);
;     const float mnew = fmaxf(m, mx);
;     const float mc = fmaxf(mnew, -1e20f);
;     const float alpha = __builtin_amdgcn_exp2f(fmaxf(m, -1e20f) - mc);
;     float p[16], rs = 0.f;
; #pragma unroll
;     for (int r = 0; r < 16; ++r) { p[r] = __builtin_amdgcn_exp2f(v[r] - mc); rs += p[r]; }
;     rs = rows_sum(rs);
;     lsum = lsum * alpha + rs; m = mnew;
;     union { u32x4 u; bf16x8 b; } pk0, pk1;
;     pk0.u.x = cvt_pk_bf16(p[0], p[1]); pk0.u.y = cvt_pk_bf16(p[2], p[3]); pk0.u.z = cvt_pk_bf16(p[4], p[5]); pk0.u.w = cvt_pk_bf16(p[6], p[7]);
;     pk1.u.x = cvt_pk_bf16(p[8], p[9]); pk1.u.y = cvt_pk_bf16(p[10], p[11]); pk1.u.z = cvt_pk_bf16(p[12], p[13]); pk1.u.w = cvt_pk_bf16(p[14], p[15]);
;     if (__builtin_amdgcn_ballot_w64(alpha != 1.0f) != 0ull) {
; #pragma unroll
;         for (int dt = 0; dt < D / 16; ++dt) o[dt] *= alpha;
	v_fmamk_f32 v62, v62, 0x3fb8aa3b, v107
	v_fmamk_f32 v63, v63, 0x3fb8aa3b, v108
	v_fmamk_f32 v64, v64, 0x3fb8aa3b, v109
	v_fmamk_f32 v65, v65, 0x3fb8aa3b, v110
	v_fmamk_f32 v66, v66, 0x3fb8aa3b, v111
	v_fmamk_f32 v67, v67, 0x3fb8aa3b, v112
	v_fmamk_f32 v68, v68, 0x3fb8aa3b, v113
	v_fmamk_f32 v69, v69, 0x3fb8aa3b, v133
	v_cmp_le_i32_e32 vcc, 32, v78
	s_nop 1
	v_cndmask_b32_e32 v62, v243, v62, vcc
	v_cmp_le_i32_e32 vcc, 33, v78
	s_nop 1
	v_cndmask_b32_e32 v63, v243, v63, vcc
	v_cmp_le_i32_e32 vcc, 34, v78
	s_nop 1
	v_cndmask_b32_e32 v64, v243, v64, vcc
	v_cmp_le_i32_e32 vcc, 35, v78
	s_nop 1
	v_cndmask_b32_e32 v65, v243, v65, vcc
	v_cmp_le_i32_e32 vcc, 48, v78
	s_nop 1
	v_cndmask_b32_e32 v66, v243, v66, vcc
	v_cmp_le_i32_e32 vcc, 49, v78
	s_nop 1
	v_cndmask_b32_e32 v67, v243, v67, vcc
	v_cmp_le_i32_e32 vcc, 50, v78
	s_nop 1
	v_cndmask_b32_e32 v68, v243, v68, vcc
	v_cmp_le_i32_e32 vcc, 51, v78
	s_nop 1
	v_cndmask_b32_e32 v69, v243, v69, vcc
	v_max3_f32 v84, v54, v55, v56
	v_max3_f32 v79, v57, v58, v59
	v_max3_f32 v80, v60, v61, v62
	v_max3_f32 v81, v63, v64, v65
	v_max3_f32 v83, v66, v67, v68
	v_max3_f32 v84, v84, v79, v69
	v_max3_f32 v80, v80, v81, v83
	v_max_f32_e32 v84, v84, v80
	v_mov_b32_e32 v79, v84
	s_nop 1
	v_permlane16_swap_b32_e32 v84, v79
	v_max_f32_e32 v84, v84, v79
	v_mov_b32_e32 v79, v84
	s_nop 1
	v_permlane32_swap_b32_e32 v84, v79
	v_max_f32_e32 v84, v84, v79
	v_cndmask_b32_e64 v84, v243, v84, s[24:25]
	v_max_f32_e32 v80, v100, v84
	v_max_f32_e32 v82, 0xe0ad78ec, v100
	v_max_f32_e32 v81, 0xe0ad78ec, v80
	v_sub_f32_e32 v82, v82, v81
	v_mov_b32_e32 v100, v80
	v_exp_f32_e32 v82, v82
	v_mov_b32_e32 v83, 0x7149f2ca
	v_cndmask_b32_e64 v83, v83, v81, s[24:25]
	v_sub_f32_e32 v54, v54, v83
	v_sub_f32_e32 v55, v55, v83
	v_sub_f32_e32 v56, v56, v83
	v_sub_f32_e32 v57, v57, v83
	v_exp_f32_e32 v54, v54
	v_exp_f32_e32 v55, v55
	v_exp_f32_e32 v56, v56
	v_exp_f32_e32 v57, v57
	v_sub_f32_e32 v58, v58, v83
	v_sub_f32_e32 v59, v59, v83
	v_sub_f32_e32 v60, v60, v83
	v_sub_f32_e32 v61, v61, v83
	v_exp_f32_e32 v58, v58
	v_exp_f32_e32 v59, v59
	v_exp_f32_e32 v60, v60
	v_exp_f32_e32 v61, v61
	v_sub_f32_e32 v62, v62, v83
	v_sub_f32_e32 v63, v63, v83
	v_sub_f32_e32 v64, v64, v83
	v_sub_f32_e32 v65, v65, v83
	v_exp_f32_e32 v62, v62
	v_exp_f32_e32 v63, v63
	v_exp_f32_e32 v64, v64
	v_exp_f32_e32 v65, v65
	v_sub_f32_e32 v66, v66, v83
	v_sub_f32_e32 v67, v67, v83
	v_sub_f32_e32 v68, v68, v83
	v_sub_f32_e32 v69, v69, v83
	v_exp_f32_e32 v66, v66
	v_exp_f32_e32 v67, v67
	v_exp_f32_e32 v68, v68
	v_exp_f32_e32 v69, v69
	s_nop 0
	v_add_f32_e32 v78, v54, v55
	v_add_f32_e32 v79, v56, v57
	v_add_f32_e32 v80, v58, v59
	v_add_f32_e32 v81, v60, v61
	v_add_f32_e32 v78, v78, v62
	v_add_f32_e32 v79, v79, v63
	v_add_f32_e32 v80, v80, v64
	v_add_f32_e32 v81, v81, v65
	v_add_f32_e32 v78, v78, v66
	v_add_f32_e32 v79, v79, v67
	v_add_f32_e32 v80, v80, v68
	v_add_f32_e32 v81, v81, v69
	v_add_f32_e32 v78, v78, v79
	v_add_f32_e32 v80, v80, v81
	v_add_f32_e32 v78, v78, v80
	v_cvt_pk_bf16_f32 v70, v54, v55
	v_cvt_pk_bf16_f32 v71, v56, v57
	v_cvt_pk_bf16_f32 v72, v58, v59
	v_cvt_pk_bf16_f32 v73, v60, v61
	v_cvt_pk_bf16_f32 v74, v62, v63
	v_cvt_pk_bf16_f32 v75, v64, v65
	v_cvt_pk_bf16_f32 v76, v66, v67
	v_cvt_pk_bf16_f32 v77, v68, v69
	v_mov_b32_e32 v79, v78
	s_nop 1
	v_permlane16_swap_b32_e32 v78, v79
	v_add_f32_e32 v78, v78, v79
	v_mov_b32_e32 v79, v78
	s_nop 1
	v_permlane32_swap_b32_e32 v78, v79
	v_add_f32_e32 v78, v78, v79
	v_fma_f32 v106, v106, v82, v78
	v_cmp_neq_f32_e64 s[4:5], 1.0, v82
	s_cmp_eq_u64 s[4:5], 0
	s_cbranch_scc1 .Lsl3_nosc_19
	v_pk_mul_f32 v[38:39], v[38:39], v[82:83] op_sel_hi:[1,0]
	v_pk_mul_f32 v[40:41], v[40:41], v[82:83] op_sel_hi:[1,0]
	v_pk_mul_f32 v[42:43], v[42:43], v[82:83] op_sel_hi:[1,0]
	v_pk_mul_f32 v[44:45], v[44:45], v[82:83] op_sel_hi:[1,0]
	v_pk_mul_f32 v[46:47], v[46:47], v[82:83] op_sel_hi:[1,0]
	v_pk_mul_f32 v[48:49], v[48:49], v[82:83] op_sel_hi:[1,0]
	v_pk_mul_f32 v[50:51], v[50:51], v[82:83] op_sel_hi:[1,0]
	v_pk_mul_f32 v[52:53], v[52:53], v[82:83] op_sel_hi:[1,0]

; #define LAS __attribute__((address_space(3)))
; __device__ __forceinline__ f32x4 mfma16(bf16x8 a, bf16x8 b, f32x4 c) { return __builtin_amdgcn_mfma_f32_16x16x32_bf16(a, b, c, 0, 0, 0); }
; template <int D, class SF>
; __device__ __forceinline__ void attn_step(const bf16x8 (&qf)[D / 32], const LAS bf16_t* Ks, const LAS bf16_t* Vt, f32x4 (&o)[D / 16], float& m, float& lsum, float& alpha_out, bf16x8& pf0_out, bf16x8& pf1_out, const int lane, SF sf) {
;     ...
; #pragma unroll
;     for (int t = 0; t < 4; ++t) s[t] = (f32x4){0.f, 0.f, 0.f, 0.f};
; #pragma unroll
;     for (int ks = 0; ks < D / 32; ++ks) {
; #pragma unroll
;         for (int t = 0; t < 4; ++t) { const bf16x8 kf = *(const LAS bf16x8*)(Ks + (16 * t + c) * KSTR + ks * 32 + 8 * i); s[t] = mfma16(kf, qf[ks], s[t]); }
;     }
;     float v[16];
; #pragma unroll
;     for (int t = 0; t < 4; ++t)
; #pragma unroll
;         for (int r = 0; r < 4; ++r) v[4 * t + r] = sf(16 * t + 4 * i + r, s[t][r]);
;     float mx = fmaxf(fmaxf(fmaxf(v[0], v[1]), fmaxf(v[2], v[3])), fmaxf(fmaxf(v[4], v[5]), fmaxf(v[6], v[7])));
;     mx = fmaxf(mx, fmaxf(fmaxf(fmaxf(v[8], v[9]), fmaxf(v[10], v[11])), fmaxf(fmaxf(v[12], v[13]), fmaxf(v[14], v[15]))));
;     mx = rows_max(mx);
;     const float mnew = fmaxf(m, mx);
;     const float mc = fmaxf(mnew, -1e20f);
;     const float alpha = __builtin_amdgcn_exp2f(fmaxf(m, -1e20f) - mc);
; __device__ __forceinline__ void nsa_unit(LAS unsigned char* lds, const Ctx& P, int l, int b, int hkv, int tb) {
;     ...
;                     } else { const int kp0 = j * 64;
;                         attn_step<64>(qf[sb], Ks, Vt, o[sb], m[sb], lsum[sb], alpha, pf, pf1, lane,
;                             [&](int kk, float s) { const int dist = tqs - (kp0 + kk); return (selj && dist >= 0) ? s * LOG2E + lut[min((unsigned)dist, 1023u)] : NEGBIG; });
.Lsl3_skd_18:
	v_lshrrev_b64 v[78:79], s20, v[20:21]
	v_and_b32_e32 v78, 1, v78
	v_cmp_eq_u32_e64 s[24:25], 1, v78
	s_cmp_eq_u64 s[24:25], 0
	s_cbranch_scc1 .Lsl3_skd_20
	v_sub_u32_e32 v78, v98, v139
	v_subrev_u32_e32 v78, s21, v78
	v_subrev_u32_e32 v107, 0, v78
	v_min_u32_e32 v107, 0x3ff, v107
	v_lshl_add_u32 v107, v107, 2, v131
	ds_read_b32 v107, v107
	v_subrev_u32_e32 v108, 1, v78
	v_min_u32_e32 v108, 0x3ff, v108
	v_lshl_add_u32 v108, v108, 2, v131
	ds_read_b32 v108, v108
	v_subrev_u32_e32 v109, 2, v78
	v_min_u32_e32 v109, 0x3ff, v109
	v_lshl_add_u32 v109, v109, 2, v131
	ds_read_b32 v109, v109
	v_subrev_u32_e32 v110, 3, v78
	v_min_u32_e32 v110, 0x3ff, v110
	v_lshl_add_u32 v110, v110, 2, v131
	ds_read_b32 v110, v110
	v_subrev_u32_e32 v111, 16, v78
	v_min_u32_e32 v111, 0x3ff, v111
	v_lshl_add_u32 v111, v111, 2, v131
	ds_read_b32 v111, v111
	v_subrev_u32_e32 v112, 17, v78
	v_min_u32_e32 v112, 0x3ff, v112
	v_lshl_add_u32 v112, v112, 2, v131
	ds_read_b32 v112, v112
	v_subrev_u32_e32 v113, 18, v78
	v_min_u32_e32 v113, 0x3ff, v113
	v_lshl_add_u32 v113, v113, 2, v131
	ds_read_b32 v113, v113
	v_subrev_u32_e32 v133, 19, v78
	v_min_u32_e32 v133, 0x3ff, v133
	v_lshl_add_u32 v133, v133, 2, v131
	ds_read_b32 v133, v133
	ds_read_b128 v[198:201], v190 offset:16384
	ds_read_b128 v[206:209], v190 offset:18944
	ds_read_b128 v[202:205], v190 offset:16448
	ds_read_b128 v[210:213], v190 offset:19008
	ds_read_b128 v[214:217], v190 offset:21504
	ds_read_b128 v[222:225], v190 offset:24064
	ds_read_b128 v[218:221], v190 offset:21568
	ds_read_b128 v[226:229], v190 offset:24128
	s_waitcnt lgkmcnt(6)
	v_mfma_f32_16x16x32_bf16 v[54:57], v[198:201], v[10:13], 0
	v_mfma_f32_16x16x32_bf16 v[58:61], v[206:209], v[10:13], 0
	s_waitcnt lgkmcnt(4)
	v_mfma_f32_16x16x32_bf16 v[54:57], v[202:205], v[14:17], v[54:57]
	v_mfma_f32_16x16x32_bf16 v[58:61], v[210:213], v[14:17], v[58:61]
	s_waitcnt lgkmcnt(2)
	v_mfma_f32_16x16x32_bf16 v[62:65], v[214:217], v[10:13], 0
	v_mfma_f32_16x16x32_bf16 v[66:69], v[222:225], v[10:13], 0
	s_waitcnt lgkmcnt(0)
	v_mfma_f32_16x16x32_bf16 v[62:65], v[218:221], v[14:17], v[62:65]
	v_mfma_f32_16x16x32_bf16 v[66:69], v[226:229], v[14:17], v[66:69]
	ds_read_b64_tr_b16 v[198:199], v191 offset:26624
	ds_read_b64_tr_b16 v[200:201], v191 offset:29184
	ds_read_b64_tr_b16 v[202:203], v191 offset:31744
	ds_read_b64_tr_b16 v[204:205], v191 offset:34304
	ds_read_b64_tr_b16 v[206:207], v191 offset:26656
	ds_read_b64_tr_b16 v[208:209], v191 offset:29216
	ds_read_b64_tr_b16 v[210:211], v191 offset:31776
	v_fmamk_f32 v54, v54, 0x3fb8aa3b, v107
	v_fmamk_f32 v55, v55, 0x3fb8aa3b, v108
	v_fmamk_f32 v56, v56, 0x3fb8aa3b, v109
	v_fmamk_f32 v57, v57, 0x3fb8aa3b, v110
	v_fmamk_f32 v58, v58, 0x3fb8aa3b, v111
	v_fmamk_f32 v59, v59, 0x3fb8aa3b, v112
	v_fmamk_f32 v60, v60, 0x3fb8aa3b, v113
	v_fmamk_f32 v61, v61, 0x3fb8aa3b, v133
	v_cmp_le_i32_e32 vcc, 0, v78
	s_nop 1
	v_cndmask_b32_e32 v54, v243, v54, vcc
	v_cmp_le_i32_e32 vcc, 1, v78
	s_nop 1
	v_cndmask_b32_e32 v55, v243, v55, vcc
	v_cmp_le_i32_e32 vcc, 2, v78
	s_nop 1
	v_cndmask_b32_e32 v56, v243, v56, vcc
	v_cmp_le_i32_e32 vcc, 3, v78
	s_nop 1
	v_cndmask_b32_e32 v57, v243, v57, vcc
	v_cmp_le_i32_e32 vcc, 16, v78
	s_nop 1
	v_cndmask_b32_e32 v58, v243, v58, vcc
	v_cmp_le_i32_e32 vcc, 17, v78
	s_nop 1
	v_cndmask_b32_e32 v59, v243, v59, vcc
	v_cmp_le_i32_e32 vcc, 18, v78
	s_nop 1
	v_cndmask_b32_e32 v60, v243, v60, vcc
	v_cmp_le_i32_e32 vcc, 19, v78
	s_nop 1
	v_cndmask_b32_e32 v61, v243, v61, vcc
	v_subrev_u32_e32 v107, 32, v78
	v_min_u32_e32 v107, 0x3ff, v107
	v_lshl_add_u32 v107, v107, 2, v131
	ds_read_b32 v107, v107
	v_subrev_u32_e32 v108, 33, v78
	v_min_u32_e32 v108, 0x3ff, v108
	v_lshl_add_u32 v108, v108, 2, v131
	ds_read_b32 v108, v108
	v_subrev_u32_e32 v109, 34, v78
	v_min_u32_e32 v109, 0x3ff, v109
	v_lshl_add_u32 v109, v109, 2, v131
	ds_read_b32 v109, v109
	v_subrev_u32_e32 v110, 35, v78
	v_min_u32_e32 v110, 0x3ff, v110
	v_lshl_add_u32 v110, v110, 2, v131
	ds_read_b32 v110, v110
	v_subrev_u32_e32 v111, 48, v78
	v_min_u32_e32 v111, 0x3ff, v111
	v_lshl_add_u32 v111, v111, 2, v131
	ds_read_b32 v111, v111
	v_subrev_u32_e32 v112, 49, v78
	v_min_u32_e32 v112, 0x3ff, v112
	v_lshl_add_u32 v112, v112, 2, v131
	ds_read_b32 v112, v112
	v_subrev_u32_e32 v113, 50, v78
	v_min_u32_e32 v113, 0x3ff, v113
	v_lshl_add_u32 v113, v113, 2, v131
	ds_read_b32 v113, v113
	v_subrev_u32_e32 v133, 51, v78
	v_min_u32_e32 v133, 0x3ff, v133
	v_lshl_add_u32 v133, v133, 2, v131
	ds_read_b32 v133, v133
	ds_read_b64_tr_b16 v[212:213], v191 offset:34336
	ds_read_b64_tr_b16 v[214:215], v191 offset:26688
	ds_read_b64_tr_b16 v[216:217], v191 offset:29248
	ds_read_b64_tr_b16 v[218:219], v191 offset:31808
	ds_read_b64_tr_b16 v[220:221], v191 offset:34368
	ds_read_b64_tr_b16 v[222:223], v191 offset:26720
	ds_read_b64_tr_b16 v[224:225], v191 offset:29280
	ds_read_b64_tr_b16 v[226:227], v191 offset:31840
	ds_read_b64_tr_b16 v[228:229], v191 offset:34400
	s_waitcnt lgkmcnt(9)
; __device__ __forceinline__ unsigned cvt_pk_bf16(float lo, float hi) { unsigned r; asm("v_cvt_pk_bf16_f32 %0, %1, %2" : "=v"(r) : "v"(lo), "v"(hi)); return r; }
; template <int D, class SF>
; __device__ __forceinline__ void attn_step(const bf16x8 (&qf)[D / 32], const LAS bf16_t* Ks, const LAS bf16_t* Vt, f32x4 (&o)[D / 16], float& m, float& lsum, float& alpha_out, bf16x8& pf0_out, bf16x8& pf1_out, const int lane, SF sf) {
;     ...
;     for (int t = 0; t < 4; ++t)
; #pragma unroll
;         for (int r = 0; r < 4; ++r) v[4 * t + r] = sf(16 * t + 4 * i + r, s[t][r]);
;     float mx = fmaxf(fmaxf(fmaxf(v[0], v[1]), fmaxf(v[2], v[3])), fmaxf(fmaxf(v[4], v[5]), fmaxf(v[6], v[7])));
;     mx = fmaxf(mx, fmaxf(fmaxf(fmaxf(v[8], v[9]), fmaxf(v[10], v[11])), fmaxf(fmaxf(v[12], v[13]), fmaxf(v[14], v[15]))));
;     mx = rows_max(mx);
;     const float mnew = fmaxf(m, mx);
;     const float mc = fmaxf(mnew, -1e20f);
;     const float alpha = __builtin_amdgcn_exp2f(fmaxf(m, -1e20f) - mc);
;     float p[16], rs = 0.f;
; #pragma unroll
;     for (int r = 0; r < 16; ++r) { p[r] = __builtin_amdgcn_exp2f(v[r] - mc); rs += p[r]; }
;     rs = rows_sum(rs);
;     lsum = lsum * alpha + rs; m = mnew;
;     union { u32x4 u; bf16x8 b; } pk0, pk1;
;     pk0.u.x = cvt_pk_bf16(p[0], p[1]); pk0.u.y = cvt_pk_bf16(p[2], p[3]); pk0.u.z = cvt_pk_bf16(p[4], p[5]); pk0.u.w = cvt_pk_bf16(p[6], p[7]);
;     pk1.u.x = cvt_pk_bf16(p[8], p[9]); pk1.u.y = cvt_pk_bf16(p[10], p[11]); pk1.u.z = cvt_pk_bf16(p[12], p[13]); pk1.u.w = cvt_pk_bf16(p[14], p[15]);
;     if (__builtin_amdgcn_ballot_w64(alpha != 1.0f) != 0ull) {
; #pragma unroll
;         for (int dt = 0; dt < D / 16; ++dt) o[dt] *= alpha;
	v_fmamk_f32 v62, v62, 0x3fb8aa3b, v107
	v_fmamk_f32 v63, v63, 0x3fb8aa3b, v108
	v_fmamk_f32 v64, v64, 0x3fb8aa3b, v109
	v_fmamk_f32 v65, v65, 0x3fb8aa3b, v110
	v_fmamk_f32 v66, v66, 0x3fb8aa3b, v111
	v_fmamk_f32 v67, v67, 0x3fb8aa3b, v112
	v_fmamk_f32 v68, v68, 0x3fb8aa3b, v113
	v_fmamk_f32 v69, v69, 0x3fb8aa3b, v133
	v_cmp_le_i32_e32 vcc, 32, v78
	s_nop 1
	v_cndmask_b32_e32 v62, v243, v62, vcc
	v_cmp_le_i32_e32 vcc, 33, v78
	s_nop 1
	v_cndmask_b32_e32 v63, v243, v63, vcc
	v_cmp_le_i32_e32 vcc, 34, v78
	s_nop 1
	v_cndmask_b32_e32 v64, v243, v64, vcc
	v_cmp_le_i32_e32 vcc, 35, v78
	s_nop 1
	v_cndmask_b32_e32 v65, v243, v65, vcc
	v_cmp_le_i32_e32 vcc, 48, v78
	s_nop 1
	v_cndmask_b32_e32 v66, v243, v66, vcc
	v_cmp_le_i32_e32 vcc, 49, v78
	s_nop 1
	v_cndmask_b32_e32 v67, v243, v67, vcc
	v_cmp_le_i32_e32 vcc, 50, v78
	s_nop 1
	v_cndmask_b32_e32 v68, v243, v68, vcc
	v_cmp_le_i32_e32 vcc, 51, v78
	s_nop 1
	v_cndmask_b32_e32 v69, v243, v69, vcc
	v_max3_f32 v84, v54, v55, v56
	v_max3_f32 v79, v57, v58, v59
	v_max3_f32 v80, v60, v61, v62
	v_max3_f32 v81, v63, v64, v65
	v_max3_f32 v83, v66, v67, v68
	v_max3_f32 v84, v84, v79, v69
	v_max3_f32 v80, v80, v81, v83
	v_max_f32_e32 v84, v84, v80
	v_mov_b32_e32 v79, v84
	s_nop 1
	v_permlane16_swap_b32_e32 v84, v79
	v_max_f32_e32 v84, v84, v79
	v_mov_b32_e32 v79, v84
	s_nop 1
	v_permlane32_swap_b32_e32 v84, v79
	v_max_f32_e32 v84, v84, v79
	v_cndmask_b32_e64 v84, v243, v84, s[24:25]
	v_max_f32_e32 v80, v93, v84
	v_max_f32_e32 v82, 0xe0ad78ec, v93
	v_max_f32_e32 v81, 0xe0ad78ec, v80
	v_sub_f32_e32 v82, v82, v81
	v_mov_b32_e32 v93, v80
	v_exp_f32_e32 v82, v82
	v_mov_b32_e32 v83, 0x7149f2ca
	v_cndmask_b32_e64 v83, v83, v81, s[24:25]
	v_sub_f32_e32 v54, v54, v83
	v_sub_f32_e32 v55, v55, v83
	v_sub_f32_e32 v56, v56, v83
	v_sub_f32_e32 v57, v57, v83
	v_exp_f32_e32 v54, v54
	v_exp_f32_e32 v55, v55
	v_exp_f32_e32 v56, v56
	v_exp_f32_e32 v57, v57
	v_sub_f32_e32 v58, v58, v83
	v_sub_f32_e32 v59, v59, v83
	v_sub_f32_e32 v60, v60, v83
	v_sub_f32_e32 v61, v61, v83
	v_exp_f32_e32 v58, v58
	v_exp_f32_e32 v59, v59
	v_exp_f32_e32 v60, v60
	v_exp_f32_e32 v61, v61
	v_sub_f32_e32 v62, v62, v83
	v_sub_f32_e32 v63, v63, v83
	v_sub_f32_e32 v64, v64, v83
	v_sub_f32_e32 v65, v65, v83
	v_exp_f32_e32 v62, v62
	v_exp_f32_e32 v63, v63
	v_exp_f32_e32 v64, v64
	v_exp_f32_e32 v65, v65
	v_sub_f32_e32 v66, v66, v83
	v_sub_f32_e32 v67, v67, v83
	v_sub_f32_e32 v68, v68, v83
	v_sub_f32_e32 v69, v69, v83
	v_exp_f32_e32 v66, v66
	v_exp_f32_e32 v67, v67
	v_exp_f32_e32 v68, v68
	v_exp_f32_e32 v69, v69
	s_nop 0
	v_add_f32_e32 v78, v54, v55
	v_add_f32_e32 v79, v56, v57
	v_add_f32_e32 v80, v58, v59
	v_add_f32_e32 v81, v60, v61
	v_add_f32_e32 v78, v78, v62
	v_add_f32_e32 v79, v79, v63
	v_add_f32_e32 v80, v80, v64
	v_add_f32_e32 v81, v81, v65
	v_add_f32_e32 v78, v78, v66
	v_add_f32_e32 v79, v79, v67
	v_add_f32_e32 v80, v80, v68
	v_add_f32_e32 v81, v81, v69
	v_add_f32_e32 v78, v78, v79
	v_add_f32_e32 v80, v80, v81
	v_add_f32_e32 v78, v78, v80
	v_cvt_pk_bf16_f32 v70, v54, v55
	v_cvt_pk_bf16_f32 v71, v56, v57
	v_cvt_pk_bf16_f32 v72, v58, v59
	v_cvt_pk_bf16_f32 v73, v60, v61
	v_cvt_pk_bf16_f32 v74, v62, v63
	v_cvt_pk_bf16_f32 v75, v64, v65
	v_cvt_pk_bf16_f32 v76, v66, v67
	v_cvt_pk_bf16_f32 v77, v68, v69
	v_mov_b32_e32 v79, v78
	s_nop 1
	v_permlane16_swap_b32_e32 v78, v79
	v_add_f32_e32 v78, v78, v79
	v_mov_b32_e32 v79, v78
	s_nop 1
	v_permlane32_swap_b32_e32 v78, v79
	v_add_f32_e32 v78, v78, v79
	v_fma_f32 v105, v105, v82, v78
	v_cmp_neq_f32_e64 s[4:5], 1.0, v82
	s_cmp_eq_u64 s[4:5], 0
	s_cbranch_scc1 .Lsl3_nosc_21
	v_pk_mul_f32 v[22:23], v[22:23], v[82:83] op_sel_hi:[1,0]
	v_pk_mul_f32 v[24:25], v[24:25], v[82:83] op_sel_hi:[1,0]
	v_pk_mul_f32 v[26:27], v[26:27], v[82:83] op_sel_hi:[1,0]
	v_pk_mul_f32 v[28:29], v[28:29], v[82:83] op_sel_hi:[1,0]
	v_pk_mul_f32 v[34:35], v[34:35], v[82:83] op_sel_hi:[1,0]
	v_pk_mul_f32 v[36:37], v[36:37], v[82:83] op_sel_hi:[1,0]
	v_pk_mul_f32 v[30:31], v[30:31], v[82:83] op_sel_hi:[1,0]
	v_pk_mul_f32 v[32:33], v[32:33], v[82:83] op_sel_hi:[1,0]

; __device__ __forceinline__ void nsa_unit(LAS unsigned char* lds, const Ctx& P, int l, int b, int hkv, int tb) {
;     ...
;         const bf16_t* kb = H + (size_t)b * SEQ * LDH + C_KW + hkv * 64; const bf16_t* vb = H + (size_t)b * SEQ * LDH + C_VW + hkv * 64;
;         const int kfirst = (t0 >= 256) ? 0 : (256 - t0) / 64;
;         for (int k = kfirst; k < 5; k += 2) { const int p0 = t0 - 256 + 64 * k; const bool hasb = k + 1 < 5;
;             __syncthreads();
;             load2(kb, vb, LDH, p0, p0 + 64, hasb, SEQ - 1);
;             __syncthreads();
.LBB0_601:
	s_add_i32 s20, s44, 2
	s_add_i32 s12, s55, 0xffffff00
	v_add_u32_e32 v178, v150, v148
	v_lshrrev_b32_e32 v90, 2, v97
	v_lshl_add_u32 v90, v103, 2, v90
	v_mul_u32_u24_e32 v90, 0xa0, v90
	v_and_b32_e32 v91, 3, v97
	v_lshl_add_u32 v179, v91, 3, v90
	v_mov_b32_e32 v180, v98
	v_add_u32_e32 v116, 0xe000, v178
	v_add_u32_e32 v117, 0xe000, v179
	v_add_u32_e32 v181, 0xe000, v146
	s_cmp_gt_u32 s20, 0
	s_cbranch_scc1 .Lwn_wl_1
	s_add_i32 s4, s12, 0
	v_add_u32_e32 v92, s4, v144
	v_mul_lo_u32 v92, v92, s75
	v_mov_b32_e32 v93, v1
	v_lshl_add_u64 v[92:93], v[92:93], 1, v[134:135]
	global_load_dwordx4 v[50:53], v[92:93], off
	global_load_dwordx4 v[54:57], v[92:93], off offset:512

; #define LAS __attribute__((address_space(3)))
; __device__ __forceinline__ f32x4 mfma16(bf16x8 a, bf16x8 b, f32x4 c) { return __builtin_amdgcn_mfma_f32_16x16x32_bf16(a, b, c, 0, 0, 0); }
; template <int D, class SF>
; __device__ __forceinline__ void attn_step(const bf16x8 (&qf)[D / 32], const LAS bf16_t* Ks, const LAS bf16_t* Vt, f32x4 (&o)[D / 16], float& m, float& lsum, float& alpha_out, bf16x8& pf0_out, bf16x8& pf1_out, const int lane, SF sf) {
;     ...
; #pragma unroll
;     for (int t = 0; t < 4; ++t) s[t] = (f32x4){0.f, 0.f, 0.f, 0.f};
; #pragma unroll
;     for (int ks = 0; ks < D / 32; ++ks) {
; #pragma unroll
;         for (int t = 0; t < 4; ++t) { const bf16x8 kf = *(const LAS bf16x8*)(Ks + (16 * t + c) * KSTR + ks * 32 + 8 * i); s[t] = mfma16(kf, qf[ks], s[t]); }
;     }
; __device__ __forceinline__ void nsa_unit(LAS unsigned char* lds, const Ctx& P, int l, int b, int hkv, int tb) {
;     ...
;         for (int k = kfirst; k < 5; k += 2) { const int p0 = t0 - 256 + 64 * k; const bool hasb = k + 1 < 5;
;             __syncthreads();
;             load2(kb, vb, LDH, p0, p0 + 64, hasb, SEQ - 1);
;             __syncthreads();
; #pragma unroll
;             for (int sl = 0; sl < 2; ++sl) if (sl == 0 || hasb) { const LAS bf16_t* Ks = KV + sl * 9216; const LAS bf16_t* Vt = Ks + 4608; const int kp0 = p0 + sl * 64;
; #pragma unroll
;                 for (int sb = 0; sb < 2; ++sb) { const int tqs = tq[sb];
;                     attn_step<64>(qf[sb], Ks, Vt, o[sb], m[sb], lsum[sb], alpha, pf, pf1, lane,
;                         [&](int kk, float s) { const int kpos = kp0 + kk, dist = tqs - kpos; return (dist >= 0 && dist < 256 && kpos >= 0) ? s * LOG2E + lut[min((unsigned)dist, 1023u)] : NEGBIG; }); }
.Lwn_wl_5:
	s_waitcnt lgkmcnt(0)
	s_barrier
	s_waitcnt vmcnt(0)
	s_cmp_gt_u32 s20, 0
	s_cbranch_scc1 .Lwn_ww_6
	ds_write_b128 v146, v[50:53] offset:16384
	ds_write_b128 v146, v[54:57] offset:26624
.Lwn_ww_6:
	s_cmp_gt_u32 s20, 1
	s_cbranch_scc1 .Lwn_ww_7
	ds_write_b128 v146, v[58:61] offset:36864
	ds_write_b128 v146, v[62:65] offset:47104
.Lwn_ww_7:
	s_cmp_gt_u32 s20, 2
	s_cbranch_scc1 .Lwn_ww_8
	ds_write_b128 v181, v[66:69] offset:0
	ds_write_b128 v181, v[70:73] offset:10240
.Lwn_ww_8:
	s_cmp_gt_u32 s20, 3
	s_cbranch_scc1 .Lwn_ww_9
	ds_write_b128 v181, v[74:77] offset:20480
	ds_write_b128 v181, v[78:81] offset:30720
.Lwn_ww_9:
	s_cmp_gt_u32 s20, 4
	s_cbranch_scc1 .Lwn_ww_10
	ds_write_b128 v181, v[100:103] offset:40960
	ds_write_b128 v181, v[104:107] offset:51200
.Lwn_ww_10:
	s_waitcnt lgkmcnt(0)
	s_barrier
	s_mov_b64 s[24:25], -1
	s_cmp_gt_u32 s20, 0
	s_cbranch_scc1 .Lwn_wc_11
	s_add_i32 s21, s12, 0
	v_sub_u32_e32 v90, v130, v139
	v_subrev_u32_e32 v90, s21, v90
	v_lshl_add_u32 v91, v90, 2, v131
	v_add_u32_e32 v91, 0xffffff34, v91
	v_add_u32_e32 v97, 0xffffff01, v90
	ds_read_b32 v170, v91 offset:204
	ds_read_b32 v171, v91 offset:200
	ds_read_b32 v172, v91 offset:196
	ds_read_b32 v173, v91 offset:192
	ds_read_b32 v174, v91 offset:140
	ds_read_b32 v175, v91 offset:136
	ds_read_b32 v176, v91 offset:132
	ds_read_b32 v177, v91 offset:128
	ds_read_b128 v[50:53], v178 offset:16384
	ds_read_b128 v[58:61], v178 offset:18944
	ds_read_b128 v[54:57], v178 offset:16448
	ds_read_b128 v[62:65], v178 offset:19008
	ds_read_b128 v[66:69], v178 offset:21504
	ds_read_b128 v[74:77], v178 offset:24064
	ds_read_b128 v[70:73], v178 offset:21568
	ds_read_b128 v[78:81], v178 offset:24128
	s_waitcnt lgkmcnt(6)
	v_mfma_f32_16x16x32_bf16 v[100:103], v[50:53], v[2:5], 0
	v_mfma_f32_16x16x32_bf16 v[104:107], v[58:61], v[2:5], 0
	s_waitcnt lgkmcnt(4)
	v_mfma_f32_16x16x32_bf16 v[100:103], v[54:57], v[6:9], v[100:103]
	v_mfma_f32_16x16x32_bf16 v[104:107], v[62:65], v[6:9], v[104:107]
	s_waitcnt lgkmcnt(2)
	v_mfma_f32_16x16x32_bf16 v[108:111], v[66:69], v[2:5], 0
	v_mfma_f32_16x16x32_bf16 v[112:115], v[74:77], v[2:5], 0
	s_waitcnt lgkmcnt(0)
	v_mfma_f32_16x16x32_bf16 v[108:111], v[70:73], v[6:9], v[108:111]
	v_mfma_f32_16x16x32_bf16 v[112:115], v[78:81], v[6:9], v[112:115]
	ds_read_b64_tr_b16 v[50:51], v179 offset:26624
	ds_read_b64_tr_b16 v[52:53], v179 offset:29184
	ds_read_b64_tr_b16 v[54:55], v179 offset:31744
	ds_read_b64_tr_b16 v[56:57], v179 offset:34304
	ds_read_b64_tr_b16 v[58:59], v179 offset:26656
	ds_read_b64_tr_b16 v[60:61], v179 offset:29216
	ds_read_b64_tr_b16 v[62:63], v179 offset:31776
	v_fmamk_f32 v100, v100, 0x3fb8aa3b, v170
	v_fmamk_f32 v101, v101, 0x3fb8aa3b, v171
	v_fmamk_f32 v102, v102, 0x3fb8aa3b, v172
	v_fmamk_f32 v103, v103, 0x3fb8aa3b, v173
	v_fmamk_f32 v104, v104, 0x3fb8aa3b, v174
	v_fmamk_f32 v105, v105, 0x3fb8aa3b, v175
	v_fmamk_f32 v106, v106, 0x3fb8aa3b, v176
	v_fmamk_f32 v107, v107, 0x3fb8aa3b, v177
	v_cmp_ge_i32_e32 vcc, 0, v97
	s_nop 1
	v_cndmask_b32_e32 v100, v243, v100, vcc
	v_cmp_ge_i32_e32 vcc, 1, v97
	s_nop 1
	v_cndmask_b32_e32 v101, v243, v101, vcc
	v_cmp_ge_i32_e32 vcc, 2, v97
	s_nop 1
	v_cndmask_b32_e32 v102, v243, v102, vcc
	v_cmp_ge_i32_e32 vcc, 3, v97
	s_nop 1
	v_cndmask_b32_e32 v103, v243, v103, vcc
	v_cmp_ge_i32_e32 vcc, 16, v97
	s_nop 1
	v_cndmask_b32_e32 v104, v243, v104, vcc
	v_cmp_ge_i32_e32 vcc, 17, v97
	s_nop 1
	v_cndmask_b32_e32 v105, v243, v105, vcc
	v_cmp_ge_i32_e32 vcc, 18, v97
	s_nop 1
	v_cndmask_b32_e32 v106, v243, v106, vcc
	v_cmp_ge_i32_e32 vcc, 19, v97
	s_nop 1
	v_cndmask_b32_e32 v107, v243, v107, vcc
	ds_read_b32 v170, v91 offset:76
	ds_read_b32 v171, v91 offset:72
	ds_read_b32 v172, v91 offset:68
	ds_read_b32 v173, v91 offset:64
	ds_read_b32 v174, v91 offset:12
	ds_read_b32 v175, v91 offset:8
	ds_read_b32 v176, v91 offset:4
	ds_read_b32 v177, v91 offset:0
	ds_read_b64_tr_b16 v[64:65], v179 offset:34336
	ds_read_b64_tr_b16 v[66:67], v179 offset:26688
	ds_read_b64_tr_b16 v[68:69], v179 offset:29248
	ds_read_b64_tr_b16 v[70:71], v179 offset:31808
	ds_read_b64_tr_b16 v[72:73], v179 offset:34368
	ds_read_b64_tr_b16 v[74:75], v179 offset:26720
	ds_read_b64_tr_b16 v[76:77], v179 offset:29280
	ds_read_b64_tr_b16 v[78:79], v179 offset:31840
	ds_read_b64_tr_b16 v[80:81], v179 offset:34400
	s_waitcnt lgkmcnt(9)
; #define LAS __attribute__((address_space(3)))
; template <int D, class SF>
; __device__ __forceinline__ void attn_step(const bf16x8 (&qf)[D / 32], const LAS bf16_t* Ks, const LAS bf16_t* Vt, f32x4 (&o)[D / 16], float& m, float& lsum, float& alpha_out, bf16x8& pf0_out, bf16x8& pf1_out, const int lane, SF sf) {
;     ...
;     for (int t = 0; t < 4; ++t)
; #pragma unroll
;         for (int r = 0; r < 4; ++r) v[4 * t + r] = sf(16 * t + 4 * i + r, s[t][r]);
;     float mx = fmaxf(fmaxf(fmaxf(v[0], v[1]), fmaxf(v[2], v[3])), fmaxf(fmaxf(v[4], v[5]), fmaxf(v[6], v[7])));
;     mx = fmaxf(mx, fmaxf(fmaxf(fmaxf(v[8], v[9]), fmaxf(v[10], v[11])), fmaxf(fmaxf(v[12], v[13]), fmaxf(v[14], v[15]))));
;     mx = rows_max(mx);
;     const float mnew = fmaxf(m, mx);
;     const float mc = fmaxf(mnew, -1e20f);
;     const float alpha = __builtin_amdgcn_exp2f(fmaxf(m, -1e20f) - mc);
;     float p[16], rs = 0.f;
; #pragma unroll
;     for (int r = 0; r < 16; ++r) { p[r] = __builtin_amdgcn_exp2f(v[r] - mc); rs += p[r]; }
;     rs = rows_sum(rs);
;     lsum = lsum * alpha + rs; m = mnew;
;     union { u32x4 u; bf16x8 b; } pk0, pk1;
;     pk0.u.x = cvt_pk_bf16(p[0], p[1]); pk0.u.y = cvt_pk_bf16(p[2], p[3]); pk0.u.z = cvt_pk_bf16(p[4], p[5]); pk0.u.w = cvt_pk_bf16(p[6], p[7]);
;     pk1.u.x = cvt_pk_bf16(p[8], p[9]); pk1.u.y = cvt_pk_bf16(p[10], p[11]); pk1.u.z = cvt_pk_bf16(p[12], p[13]); pk1.u.w = cvt_pk_bf16(p[14], p[15]);
;     if (__builtin_amdgcn_ballot_w64(alpha != 1.0f) != 0ull) {
; #pragma unroll
;         for (int dt = 0; dt < D / 16; ++dt) o[dt] *= alpha;
;     }
; #pragma unroll
;     for (int dt = 0; dt < D / 16; ++dt) {
;         const LAS bf16_t* vp = Vt + (16 * dt + c) * 72 + 4 * i;
;         union { u32x4 u; bf16x8 b; } vf0, vf1; const u32x2 a0 = *(const LAS u32x2*)vp, a1 = *(const LAS u32x2*)(vp + 16), b0 = *(const LAS u32x2*)(vp + 32), b1 = *(const LAS u32x2*)(vp + 48);
;         vf0.u.x = a0.x; vf0.u.y = a0.y; vf0.u.z = a1.x; vf0.u.w = a1.y; vf1.u.x = b0.x; vf1.u.y = b0.y; vf1.u.z = b1.x; vf1.u.w = b1.y;
;         o[dt] = mfma16(vf0.b, pk0.b, o[dt]); o[dt] = mfma16(vf1.b, pk1.b, o[dt]);
; __device__ __forceinline__ void nsa_unit(LAS unsigned char* lds, const Ctx& P, int l, int b, int hkv, int tb) {
;     ...
;                 for (int sb = 0; sb < 2; ++sb) { const int tqs = tq[sb];
;                     attn_step<64>(qf[sb], Ks, Vt, o[sb], m[sb], lsum[sb], alpha, pf, pf1, lane,
	v_fmamk_f32 v108, v108, 0x3fb8aa3b, v170
	v_fmamk_f32 v109, v109, 0x3fb8aa3b, v171
	v_fmamk_f32 v110, v110, 0x3fb8aa3b, v172
	v_fmamk_f32 v111, v111, 0x3fb8aa3b, v173
	v_fmamk_f32 v112, v112, 0x3fb8aa3b, v174
	v_fmamk_f32 v113, v113, 0x3fb8aa3b, v175
	v_fmamk_f32 v114, v114, 0x3fb8aa3b, v176
	v_fmamk_f32 v115, v115, 0x3fb8aa3b, v177
	v_cmp_ge_i32_e32 vcc, 32, v97
	s_nop 1
	v_cndmask_b32_e32 v108, v243, v108, vcc
	v_cmp_ge_i32_e32 vcc, 33, v97
	s_nop 1
	v_cndmask_b32_e32 v109, v243, v109, vcc
	v_cmp_ge_i32_e32 vcc, 34, v97
	s_nop 1
	v_cndmask_b32_e32 v110, v243, v110, vcc
	v_cmp_ge_i32_e32 vcc, 35, v97
	s_nop 1
	v_cndmask_b32_e32 v111, v243, v111, vcc
	v_cmp_ge_i32_e32 vcc, 48, v97
	s_nop 1
	v_cndmask_b32_e32 v112, v243, v112, vcc
	v_cmp_ge_i32_e32 vcc, 49, v97
	s_nop 1
	v_cndmask_b32_e32 v113, v243, v113, vcc
	v_cmp_ge_i32_e32 vcc, 50, v97
	s_nop 1
	v_cndmask_b32_e32 v114, v243, v114, vcc
	v_cmp_ge_i32_e32 vcc, 51, v97
	s_nop 1
	v_cndmask_b32_e32 v115, v243, v115, vcc
	v_max3_f32 v96, v100, v101, v102
	v_max3_f32 v91, v103, v104, v105
	v_max3_f32 v92, v106, v107, v108
	v_max3_f32 v93, v109, v110, v111
	v_max3_f32 v95, v112, v113, v114
	v_max3_f32 v96, v96, v91, v115
	v_max3_f32 v92, v92, v93, v95
	v_max_f32_e32 v96, v96, v92
	v_mov_b32_e32 v91, v96
	s_nop 1
	v_permlane16_swap_b32_e32 v96, v91
	v_max_f32_e32 v96, v96, v91
	v_mov_b32_e32 v91, v96
	s_nop 1
	v_permlane32_swap_b32_e32 v96, v91
	v_max_f32_e32 v96, v96, v91
	v_max_f32_e32 v92, v162, v96
	v_max_f32_e32 v94, 0xe0ad78ec, v162
	v_max_f32_e32 v93, 0xe0ad78ec, v92
	v_sub_f32_e32 v94, v94, v93
	v_mov_b32_e32 v162, v92
	v_exp_f32_e32 v94, v94
	v_sub_f32_e32 v100, v100, v93
	v_sub_f32_e32 v101, v101, v93
	v_sub_f32_e32 v102, v102, v93
	v_sub_f32_e32 v103, v103, v93
	v_exp_f32_e32 v100, v100
	v_exp_f32_e32 v101, v101
	v_exp_f32_e32 v102, v102
	v_exp_f32_e32 v103, v103
	v_sub_f32_e32 v104, v104, v93
	v_sub_f32_e32 v105, v105, v93
	v_sub_f32_e32 v106, v106, v93
	v_sub_f32_e32 v107, v107, v93
	v_exp_f32_e32 v104, v104
	v_exp_f32_e32 v105, v105
	v_exp_f32_e32 v106, v106
	v_exp_f32_e32 v107, v107
	v_sub_f32_e32 v108, v108, v93
	v_sub_f32_e32 v109, v109, v93
	v_sub_f32_e32 v110, v110, v93
	v_sub_f32_e32 v111, v111, v93
	v_exp_f32_e32 v108, v108
	v_exp_f32_e32 v109, v109
	v_exp_f32_e32 v110, v110
	v_exp_f32_e32 v111, v111
	v_sub_f32_e32 v112, v112, v93
	v_sub_f32_e32 v113, v113, v93
	v_sub_f32_e32 v114, v114, v93
	v_sub_f32_e32 v115, v115, v93
	v_exp_f32_e32 v112, v112
	v_exp_f32_e32 v113, v113
	v_exp_f32_e32 v114, v114
	v_exp_f32_e32 v115, v115
	s_nop 0
	v_add_f32_e32 v90, v100, v101
	v_add_f32_e32 v91, v102, v103
	v_add_f32_e32 v92, v104, v105
	v_add_f32_e32 v93, v106, v107
	v_add_f32_e32 v90, v90, v108
	v_add_f32_e32 v91, v91, v109
	v_add_f32_e32 v92, v92, v110
	v_add_f32_e32 v93, v93, v111
	v_add_f32_e32 v90, v90, v112
	v_add_f32_e32 v91, v91, v113
	v_add_f32_e32 v92, v92, v114
	v_add_f32_e32 v93, v93, v115
	v_add_f32_e32 v90, v90, v91
	v_add_f32_e32 v92, v92, v93
	v_add_f32_e32 v90, v90, v92
	v_cvt_pk_bf16_f32 v82, v100, v101
	v_cvt_pk_bf16_f32 v83, v102, v103
	v_cvt_pk_bf16_f32 v84, v104, v105
	v_cvt_pk_bf16_f32 v85, v106, v107
	v_cvt_pk_bf16_f32 v86, v108, v109
	v_cvt_pk_bf16_f32 v87, v110, v111
	v_cvt_pk_bf16_f32 v88, v112, v113
	v_cvt_pk_bf16_f32 v89, v114, v115
	v_mov_b32_e32 v91, v90
	s_nop 1
	v_permlane16_swap_b32_e32 v90, v91
	v_add_f32_e32 v90, v90, v91
	v_mov_b32_e32 v91, v90
	s_nop 1
	v_permlane32_swap_b32_e32 v90, v91
	v_add_f32_e32 v90, v90, v91
	v_fma_f32 v161, v161, v94, v90
	v_cmp_neq_f32_e64 s[4:5], 1.0, v94
	s_cmp_eq_u64 s[4:5], 0
	s_cbranch_scc1 .Lwn_nosc_12
	v_pk_mul_f32 v[46:47], v[46:47], v[94:95] op_sel_hi:[1,0]
	v_pk_mul_f32 v[48:49], v[48:49], v[94:95] op_sel_hi:[1,0]
	v_pk_mul_f32 v[42:43], v[42:43], v[94:95] op_sel_hi:[1,0]
	v_pk_mul_f32 v[44:45], v[44:45], v[94:95] op_sel_hi:[1,0]
	v_pk_mul_f32 v[38:39], v[38:39], v[94:95] op_sel_hi:[1,0]
	v_pk_mul_f32 v[40:41], v[40:41], v[94:95] op_sel_hi:[1,0]
	v_pk_mul_f32 v[34:35], v[34:35], v[94:95] op_sel_hi:[1,0]
	v_pk_mul_f32 v[36:37], v[36:37], v[94:95] op_sel_hi:[1,0]
.Lwn_nosc_12:
	s_waitcnt lgkmcnt(0)
	s_nop 1
	v_mfma_f32_16x16x32_bf16 v[46:49], v[50:53], v[82:85], v[46:49]
	v_mfma_f32_16x16x32_bf16 v[42:45], v[58:61], v[82:85], v[42:45]
	v_mfma_f32_16x16x32_bf16 v[38:41], v[66:69], v[82:85], v[38:41]
	v_mfma_f32_16x16x32_bf16 v[34:37], v[74:77], v[82:85], v[34:37]
	v_mfma_f32_16x16x32_bf16 v[46:49], v[54:57], v[86:89], v[46:49]
	v_mfma_f32_16x16x32_bf16 v[42:45], v[62:65], v[86:89], v[42:45]
	v_mfma_f32_16x16x32_bf16 v[38:41], v[70:73], v[86:89], v[38:41]
	v_mfma_f32_16x16x32_bf16 v[34:37], v[78:81], v[86:89], v[34:37]
	v_sub_u32_e32 v90, v180, v139
	v_subrev_u32_e32 v90, s21, v90
	v_lshl_add_u32 v91, v90, 2, v131
	v_add_u32_e32 v91, 0xffffff34, v91
	v_add_u32_e32 v97, 0xffffff01, v90
	ds_read_b32 v170, v91 offset:204
	ds_read_b32 v171, v91 offset:200
	ds_read_b32 v172, v91 offset:196
	ds_read_b32 v173, v91 offset:192
	ds_read_b32 v174, v91 offset:140
	ds_read_b32 v175, v91 offset:136
	ds_read_b32 v176, v91 offset:132
	ds_read_b32 v177, v91 offset:128
	ds_read_b128 v[50:53], v178 offset:16384
	ds_read_b128 v[58:61], v178 offset:18944
	ds_read_b128 v[54:57], v178 offset:16448
	ds_read_b128 v[62:65], v178 offset:19008
	ds_read_b128 v[66:69], v178 offset:21504
	ds_read_b128 v[74:77], v178 offset:24064
	ds_read_b128 v[70:73], v178 offset:21568
	ds_read_b128 v[78:81], v178 offset:24128
	s_waitcnt lgkmcnt(6)
	v_mfma_f32_16x16x32_bf16 v[100:103], v[50:53], v[10:13], 0
	v_mfma_f32_16x16x32_bf16 v[104:107], v[58:61], v[10:13], 0
	s_waitcnt lgkmcnt(4)
; template <int D, class SF>
; __device__ __forceinline__ void attn_step(const bf16x8 (&qf)[D / 32], const LAS bf16_t* Ks, const LAS bf16_t* Vt, f32x4 (&o)[D / 16], float& m, float& lsum, float& alpha_out, bf16x8& pf0_out, bf16x8& pf1_out, const int lane, SF sf) {
;     ...
; #pragma unroll
;     for (int t = 0; t < 4; ++t) s[t] = (f32x4){0.f, 0.f, 0.f, 0.f};
; #pragma unroll
;     for (int ks = 0; ks < D / 32; ++ks) {
; #pragma unroll
;         for (int t = 0; t < 4; ++t) { const bf16x8 kf = *(const LAS bf16x8*)(Ks + (16 * t + c) * KSTR + ks * 32 + 8 * i); s[t] = mfma16(kf, qf[ks], s[t]); }
;     }
;     float v[16];
; #pragma unroll
;     for (int t = 0; t < 4; ++t)
; #pragma unroll
;         for (int r = 0; r < 4; ++r) v[4 * t + r] = sf(16 * t + 4 * i + r, s[t][r]);
;     float mx = fmaxf(fmaxf(fmaxf(v[0], v[1]), fmaxf(v[2], v[3])), fmaxf(fmaxf(v[4], v[5]), fmaxf(v[6], v[7])));
;     mx = fmaxf(mx, fmaxf(fmaxf(fmaxf(v[8], v[9]), fmaxf(v[10], v[11])), fmaxf(fmaxf(v[12], v[13]), fmaxf(v[14], v[15]))));
;     mx = rows_max(mx);
;     const float mnew = fmaxf(m, mx);
;     const float mc = fmaxf(mnew, -1e20f);
;     const float alpha = __builtin_amdgcn_exp2f(fmaxf(m, -1e20f) - mc);
;     float p[16], rs = 0.f;
; #pragma unroll
;     for (int r = 0; r < 16; ++r) { p[r] = __builtin_amdgcn_exp2f(v[r] - mc); rs += p[r]; }
;     rs = rows_sum(rs);
;     lsum = lsum * alpha + rs; m = mnew;
;     union { u32x4 u; bf16x8 b; } pk0, pk1;
;     pk0.u.x = cvt_pk_bf16(p[0], p[1]); pk0.u.y = cvt_pk_bf16(p[2], p[3]); pk0.u.z = cvt_pk_bf16(p[4], p[5]); pk0.u.w = cvt_pk_bf16(p[6], p[7]);
;     pk1.u.x = cvt_pk_bf16(p[8], p[9]); pk1.u.y = cvt_pk_bf16(p[10], p[11]); pk1.u.z = cvt_pk_bf16(p[12], p[13]); pk1.u.w = cvt_pk_bf16(p[14], p[15]);
;     if (__builtin_amdgcn_ballot_w64(alpha != 1.0f) != 0ull) {
; #pragma unroll
;         for (int dt = 0; dt < D / 16; ++dt) o[dt] *= alpha;
;     }
; __device__ __forceinline__ void nsa_unit(LAS unsigned char* lds, const Ctx& P, int l, int b, int hkv, int tb) {
;     ...
;                 for (int sb = 0; sb < 2; ++sb) { const int tqs = tq[sb];
;                     attn_step<64>(qf[sb], Ks, Vt, o[sb], m[sb], lsum[sb], alpha, pf, pf1, lane,
;                         [&](int kk, float s) { const int kpos = kp0 + kk, dist = tqs - kpos; return (dist >= 0 && dist < 256 && kpos >= 0) ? s * LOG2E + lut[min((unsigned)dist, 1023u)] : NEGBIG; }); }
	v_mfma_f32_16x16x32_bf16 v[100:103], v[54:57], v[14:17], v[100:103]
	v_mfma_f32_16x16x32_bf16 v[104:107], v[62:65], v[14:17], v[104:107]
	s_waitcnt lgkmcnt(2)
	v_mfma_f32_16x16x32_bf16 v[108:111], v[66:69], v[10:13], 0
	v_mfma_f32_16x16x32_bf16 v[112:115], v[74:77], v[10:13], 0
	s_waitcnt lgkmcnt(0)
	v_mfma_f32_16x16x32_bf16 v[108:111], v[70:73], v[14:17], v[108:111]
	v_mfma_f32_16x16x32_bf16 v[112:115], v[78:81], v[14:17], v[112:115]
	ds_read_b64_tr_b16 v[50:51], v179 offset:26624
	ds_read_b64_tr_b16 v[52:53], v179 offset:29184
	ds_read_b64_tr_b16 v[54:55], v179 offset:31744
	ds_read_b64_tr_b16 v[56:57], v179 offset:34304
	ds_read_b64_tr_b16 v[58:59], v179 offset:26656
	ds_read_b64_tr_b16 v[60:61], v179 offset:29216
	ds_read_b64_tr_b16 v[62:63], v179 offset:31776
	v_fmamk_f32 v100, v100, 0x3fb8aa3b, v170
	v_fmamk_f32 v101, v101, 0x3fb8aa3b, v171
	v_fmamk_f32 v102, v102, 0x3fb8aa3b, v172
	v_fmamk_f32 v103, v103, 0x3fb8aa3b, v173
	v_fmamk_f32 v104, v104, 0x3fb8aa3b, v174
	v_fmamk_f32 v105, v105, 0x3fb8aa3b, v175
	v_fmamk_f32 v106, v106, 0x3fb8aa3b, v176
	v_fmamk_f32 v107, v107, 0x3fb8aa3b, v177
	v_cmp_ge_i32_e32 vcc, 0, v97
	s_nop 1
	v_cndmask_b32_e32 v100, v243, v100, vcc
	v_cmp_ge_i32_e32 vcc, 1, v97
	s_nop 1
	v_cndmask_b32_e32 v101, v243, v101, vcc
	v_cmp_ge_i32_e32 vcc, 2, v97
	s_nop 1
	v_cndmask_b32_e32 v102, v243, v102, vcc
	v_cmp_ge_i32_e32 vcc, 3, v97
	s_nop 1
	v_cndmask_b32_e32 v103, v243, v103, vcc
	v_cmp_ge_i32_e32 vcc, 16, v97
	s_nop 1
	v_cndmask_b32_e32 v104, v243, v104, vcc
	v_cmp_ge_i32_e32 vcc, 17, v97
	s_nop 1
	v_cndmask_b32_e32 v105, v243, v105, vcc
	v_cmp_ge_i32_e32 vcc, 18, v97
	s_nop 1
	v_cndmask_b32_e32 v106, v243, v106, vcc
	v_cmp_ge_i32_e32 vcc, 19, v97
	s_nop 1
	v_cndmask_b32_e32 v107, v243, v107, vcc
	ds_read_b32 v170, v91 offset:76
	ds_read_b32 v171, v91 offset:72
	ds_read_b32 v172, v91 offset:68
	ds_read_b32 v173, v91 offset:64
	ds_read_b32 v174, v91 offset:12
	ds_read_b32 v175, v91 offset:8
	ds_read_b32 v176, v91 offset:4
	ds_read_b32 v177, v91 offset:0
	ds_read_b64_tr_b16 v[64:65], v179 offset:34336
	ds_read_b64_tr_b16 v[66:67], v179 offset:26688
	ds_read_b64_tr_b16 v[68:69], v179 offset:29248
	ds_read_b64_tr_b16 v[70:71], v179 offset:31808
	ds_read_b64_tr_b16 v[72:73], v179 offset:34368
	ds_read_b64_tr_b16 v[74:75], v179 offset:26720
	ds_read_b64_tr_b16 v[76:77], v179 offset:29280
	ds_read_b64_tr_b16 v[78:79], v179 offset:31840
	ds_read_b64_tr_b16 v[80:81], v179 offset:34400
	s_waitcnt lgkmcnt(9)
	v_fmamk_f32 v108, v108, 0x3fb8aa3b, v170
	v_fmamk_f32 v109, v109, 0x3fb8aa3b, v171
	v_fmamk_f32 v110, v110, 0x3fb8aa3b, v172
	v_fmamk_f32 v111, v111, 0x3fb8aa3b, v173
	v_fmamk_f32 v112, v112, 0x3fb8aa3b, v174
	v_fmamk_f32 v113, v113, 0x3fb8aa3b, v175
	v_fmamk_f32 v114, v114, 0x3fb8aa3b, v176
	v_fmamk_f32 v115, v115, 0x3fb8aa3b, v177
	v_cmp_ge_i32_e32 vcc, 32, v97
	s_nop 1
	v_cndmask_b32_e32 v108, v243, v108, vcc
	v_cmp_ge_i32_e32 vcc, 33, v97
	s_nop 1
	v_cndmask_b32_e32 v109, v243, v109, vcc
	v_cmp_ge_i32_e32 vcc, 34, v97
	s_nop 1
	v_cndmask_b32_e32 v110, v243, v110, vcc
	v_cmp_ge_i32_e32 vcc, 35, v97
	s_nop 1
	v_cndmask_b32_e32 v111, v243, v111, vcc
	v_cmp_ge_i32_e32 vcc, 48, v97
	s_nop 1
	v_cndmask_b32_e32 v112, v243, v112, vcc
	v_cmp_ge_i32_e32 vcc, 49, v97
	s_nop 1
	v_cndmask_b32_e32 v113, v243, v113, vcc
	v_cmp_ge_i32_e32 vcc, 50, v97
	s_nop 1
	v_cndmask_b32_e32 v114, v243, v114, vcc
	v_cmp_ge_i32_e32 vcc, 51, v97
	s_nop 1
	v_cndmask_b32_e32 v115, v243, v115, vcc
	v_max3_f32 v96, v100, v101, v102
	v_max3_f32 v91, v103, v104, v105
	v_max3_f32 v92, v106, v107, v108
	v_max3_f32 v93, v109, v110, v111
	v_max3_f32 v95, v112, v113, v114
	v_max3_f32 v96, v96, v91, v115
	v_max3_f32 v92, v92, v93, v95
	v_max_f32_e32 v96, v96, v92
	v_mov_b32_e32 v91, v96
	s_nop 1
	v_permlane16_swap_b32_e32 v96, v91
	v_max_f32_e32 v96, v96, v91
	v_mov_b32_e32 v91, v96
	s_nop 1
	v_permlane32_swap_b32_e32 v96, v91
	v_max_f32_e32 v96, v96, v91
	v_max_f32_e32 v92, v160, v96
	v_max_f32_e32 v94, 0xe0ad78ec, v160
	v_max_f32_e32 v93, 0xe0ad78ec, v92
	v_sub_f32_e32 v94, v94, v93
	v_mov_b32_e32 v160, v92
	v_exp_f32_e32 v94, v94
	v_sub_f32_e32 v100, v100, v93
	v_sub_f32_e32 v101, v101, v93
	v_sub_f32_e32 v102, v102, v93
	v_sub_f32_e32 v103, v103, v93
	v_exp_f32_e32 v100, v100
	v_exp_f32_e32 v101, v101
	v_exp_f32_e32 v102, v102
	v_exp_f32_e32 v103, v103
	v_sub_f32_e32 v104, v104, v93
	v_sub_f32_e32 v105, v105, v93
	v_sub_f32_e32 v106, v106, v93
	v_sub_f32_e32 v107, v107, v93
	v_exp_f32_e32 v104, v104
	v_exp_f32_e32 v105, v105
	v_exp_f32_e32 v106, v106
	v_exp_f32_e32 v107, v107
	v_sub_f32_e32 v108, v108, v93
	v_sub_f32_e32 v109, v109, v93
	v_sub_f32_e32 v110, v110, v93
	v_sub_f32_e32 v111, v111, v93
	v_exp_f32_e32 v108, v108
	v_exp_f32_e32 v109, v109
	v_exp_f32_e32 v110, v110
	v_exp_f32_e32 v111, v111
	v_sub_f32_e32 v112, v112, v93
	v_sub_f32_e32 v113, v113, v93
	v_sub_f32_e32 v114, v114, v93
	v_sub_f32_e32 v115, v115, v93
	v_exp_f32_e32 v112, v112
	v_exp_f32_e32 v113, v113
	v_exp_f32_e32 v114, v114
	v_exp_f32_e32 v115, v115
	s_nop 0
	v_add_f32_e32 v90, v100, v101
	v_add_f32_e32 v91, v102, v103
	v_add_f32_e32 v92, v104, v105
	v_add_f32_e32 v93, v106, v107
	v_add_f32_e32 v90, v90, v108
	v_add_f32_e32 v91, v91, v109
	v_add_f32_e32 v92, v92, v110
	v_add_f32_e32 v93, v93, v111
	v_add_f32_e32 v90, v90, v112
	v_add_f32_e32 v91, v91, v113
	v_add_f32_e32 v92, v92, v114
	v_add_f32_e32 v93, v93, v115
	v_add_f32_e32 v90, v90, v91
	v_add_f32_e32 v92, v92, v93
	v_add_f32_e32 v90, v90, v92
	v_cvt_pk_bf16_f32 v82, v100, v101
	v_cvt_pk_bf16_f32 v83, v102, v103
	v_cvt_pk_bf16_f32 v84, v104, v105
	v_cvt_pk_bf16_f32 v85, v106, v107
	v_cvt_pk_bf16_f32 v86, v108, v109
	v_cvt_pk_bf16_f32 v87, v110, v111
	v_cvt_pk_bf16_f32 v88, v112, v113
	v_cvt_pk_bf16_f32 v89, v114, v115
	v_mov_b32_e32 v91, v90
	s_nop 1
	v_permlane16_swap_b32_e32 v90, v91
	v_add_f32_e32 v90, v90, v91
	v_mov_b32_e32 v91, v90
	s_nop 1
	v_permlane32_swap_b32_e32 v90, v91
	v_add_f32_e32 v90, v90, v91
	v_fma_f32 v159, v159, v94, v90
	v_cmp_neq_f32_e64 s[4:5], 1.0, v94
	s_cmp_eq_u64 s[4:5], 0
	s_cbranch_scc1 .Lwn_nosc_13
	v_pk_mul_f32 v[30:31], v[30:31], v[94:95] op_sel_hi:[1,0]
	v_pk_mul_f32 v[32:33], v[32:33], v[94:95] op_sel_hi:[1,0]
	v_pk_mul_f32 v[26:27], v[26:27], v[94:95] op_sel_hi:[1,0]
	v_pk_mul_f32 v[28:29], v[28:29], v[94:95] op_sel_hi:[1,0]
	v_pk_mul_f32 v[22:23], v[22:23], v[94:95] op_sel_hi:[1,0]
	v_pk_mul_f32 v[24:25], v[24:25], v[94:95] op_sel_hi:[1,0]
	v_pk_mul_f32 v[18:19], v[18:19], v[94:95] op_sel_hi:[1,0]
	v_pk_mul_f32 v[20:21], v[20:21], v[94:95] op_sel_hi:[1,0]

; template <int D, class SF>
; __device__ __forceinline__ void attn_step(const bf16x8 (&qf)[D / 32], const LAS bf16_t* Ks, const LAS bf16_t* Vt, f32x4 (&o)[D / 16], float& m, float& lsum, float& alpha_out, bf16x8& pf0_out, bf16x8& pf1_out, const int lane, SF sf) {
;     ...
; #pragma unroll
;     for (int t = 0; t < 4; ++t) s[t] = (f32x4){0.f, 0.f, 0.f, 0.f};
; #pragma unroll
;     for (int ks = 0; ks < D / 32; ++ks) {
; #pragma unroll
;         for (int t = 0; t < 4; ++t) { const bf16x8 kf = *(const LAS bf16x8*)(Ks + (16 * t + c) * KSTR + ks * 32 + 8 * i); s[t] = mfma16(kf, qf[ks], s[t]); }
;     }
;     float v[16];
; #pragma unroll
;     for (int t = 0; t < 4; ++t)
; #pragma unroll
;         for (int r = 0; r < 4; ++r) v[4 * t + r] = sf(16 * t + 4 * i + r, s[t][r]);
;     float mx = fmaxf(fmaxf(fmaxf(v[0], v[1]), fmaxf(v[2], v[3])), fmaxf(fmaxf(v[4], v[5]), fmaxf(v[6], v[7])));
;     mx = fmaxf(mx, fmaxf(fmaxf(fmaxf(v[8], v[9]), fmaxf(v[10], v[11])), fmaxf(fmaxf(v[12], v[13]), fmaxf(v[14], v[15]))));
;     mx = rows_max(mx);
;     const float mnew = fmaxf(m, mx);
;     const float mc = fmaxf(mnew, -1e20f);
;     const float alpha = __builtin_amdgcn_exp2f(fmaxf(m, -1e20f) - mc);
;     float p[16], rs = 0.f;
; #pragma unroll
;     for (int r = 0; r < 16; ++r) { p[r] = __builtin_amdgcn_exp2f(v[r] - mc); rs += p[r]; }
;     rs = rows_sum(rs);
;     lsum = lsum * alpha + rs; m = mnew;
;     union { u32x4 u; bf16x8 b; } pk0, pk1;
;     pk0.u.x = cvt_pk_bf16(p[0], p[1]); pk0.u.y = cvt_pk_bf16(p[2], p[3]); pk0.u.z = cvt_pk_bf16(p[4], p[5]); pk0.u.w = cvt_pk_bf16(p[6], p[7]);
;     pk1.u.x = cvt_pk_bf16(p[8], p[9]); pk1.u.y = cvt_pk_bf16(p[10], p[11]); pk1.u.z = cvt_pk_bf16(p[12], p[13]); pk1.u.w = cvt_pk_bf16(p[14], p[15]);
;     if (__builtin_amdgcn_ballot_w64(alpha != 1.0f) != 0ull) {
; #pragma unroll
;         for (int dt = 0; dt < D / 16; ++dt) o[dt] *= alpha;
;     }
; __device__ __forceinline__ void nsa_unit(LAS unsigned char* lds, const Ctx& P, int l, int b, int hkv, int tb) {
;     ...
;             for (int sl = 0; sl < 2; ++sl) if (sl == 0 || hasb) { const LAS bf16_t* Ks = KV + sl * 9216; const LAS bf16_t* Vt = Ks + 4608; const int kp0 = p0 + sl * 64;
; #pragma unroll
;                 for (int sb = 0; sb < 2; ++sb) { const int tqs = tq[sb];
;                     attn_step<64>(qf[sb], Ks, Vt, o[sb], m[sb], lsum[sb], alpha, pf, pf1, lane,
.Lwn_wc_11:
	s_cmp_gt_u32 s20, 1
	s_cbranch_scc1 .Lwn_wc_14
	s_add_i32 s21, s12, 64
	v_sub_u32_e32 v90, v130, v139
	v_subrev_u32_e32 v90, s21, v90
	v_lshl_add_u32 v91, v90, 2, v131
	v_add_u32_e32 v91, 0xffffff34, v91
	ds_read_b32 v170, v91 offset:204
	ds_read_b32 v171, v91 offset:200
	ds_read_b32 v172, v91 offset:196
	ds_read_b32 v173, v91 offset:192
	ds_read_b32 v174, v91 offset:140
	ds_read_b32 v175, v91 offset:136
	ds_read_b32 v176, v91 offset:132
	ds_read_b32 v177, v91 offset:128
	ds_read_b128 v[50:53], v178 offset:36864
	ds_read_b128 v[58:61], v178 offset:39424
	ds_read_b128 v[54:57], v178 offset:36928
	ds_read_b128 v[62:65], v178 offset:39488
	ds_read_b128 v[66:69], v178 offset:41984
	ds_read_b128 v[74:77], v178 offset:44544
	ds_read_b128 v[70:73], v178 offset:42048
	ds_read_b128 v[78:81], v178 offset:44608
	s_waitcnt lgkmcnt(6)
	v_mfma_f32_16x16x32_bf16 v[100:103], v[50:53], v[2:5], 0
	v_mfma_f32_16x16x32_bf16 v[104:107], v[58:61], v[2:5], 0
	s_waitcnt lgkmcnt(4)
	v_mfma_f32_16x16x32_bf16 v[100:103], v[54:57], v[6:9], v[100:103]
	v_mfma_f32_16x16x32_bf16 v[104:107], v[62:65], v[6:9], v[104:107]
	s_waitcnt lgkmcnt(2)
	v_mfma_f32_16x16x32_bf16 v[108:111], v[66:69], v[2:5], 0
	v_mfma_f32_16x16x32_bf16 v[112:115], v[74:77], v[2:5], 0
	s_waitcnt lgkmcnt(0)
	v_mfma_f32_16x16x32_bf16 v[108:111], v[70:73], v[6:9], v[108:111]
	v_mfma_f32_16x16x32_bf16 v[112:115], v[78:81], v[6:9], v[112:115]
	ds_read_b64_tr_b16 v[50:51], v179 offset:47104
	ds_read_b64_tr_b16 v[52:53], v179 offset:49664
	ds_read_b64_tr_b16 v[54:55], v179 offset:52224
	ds_read_b64_tr_b16 v[56:57], v179 offset:54784
	ds_read_b64_tr_b16 v[58:59], v179 offset:47136
	ds_read_b64_tr_b16 v[60:61], v179 offset:49696
	ds_read_b64_tr_b16 v[62:63], v179 offset:52256
	v_fmamk_f32 v100, v100, 0x3fb8aa3b, v170
	v_fmamk_f32 v101, v101, 0x3fb8aa3b, v171
	v_fmamk_f32 v102, v102, 0x3fb8aa3b, v172
	v_fmamk_f32 v103, v103, 0x3fb8aa3b, v173
	v_fmamk_f32 v104, v104, 0x3fb8aa3b, v174
	v_fmamk_f32 v105, v105, 0x3fb8aa3b, v175
	v_fmamk_f32 v106, v106, 0x3fb8aa3b, v176
	v_fmamk_f32 v107, v107, 0x3fb8aa3b, v177
	ds_read_b32 v170, v91 offset:76
	ds_read_b32 v171, v91 offset:72
	ds_read_b32 v172, v91 offset:68
	ds_read_b32 v173, v91 offset:64
	ds_read_b32 v174, v91 offset:12
	ds_read_b32 v175, v91 offset:8
	ds_read_b32 v176, v91 offset:4
	ds_read_b32 v177, v91 offset:0
	ds_read_b64_tr_b16 v[64:65], v179 offset:54816
	ds_read_b64_tr_b16 v[66:67], v179 offset:47168
	ds_read_b64_tr_b16 v[68:69], v179 offset:49728
	ds_read_b64_tr_b16 v[70:71], v179 offset:52288
	ds_read_b64_tr_b16 v[72:73], v179 offset:54848
	ds_read_b64_tr_b16 v[74:75], v179 offset:47200
	ds_read_b64_tr_b16 v[76:77], v179 offset:49760
	ds_read_b64_tr_b16 v[78:79], v179 offset:52320
	ds_read_b64_tr_b16 v[80:81], v179 offset:54880
	s_waitcnt lgkmcnt(9)
	v_fmamk_f32 v108, v108, 0x3fb8aa3b, v170
	v_fmamk_f32 v109, v109, 0x3fb8aa3b, v171
	v_fmamk_f32 v110, v110, 0x3fb8aa3b, v172
	v_fmamk_f32 v111, v111, 0x3fb8aa3b, v173
	v_fmamk_f32 v112, v112, 0x3fb8aa3b, v174
	v_fmamk_f32 v113, v113, 0x3fb8aa3b, v175
	v_fmamk_f32 v114, v114, 0x3fb8aa3b, v176
	v_fmamk_f32 v115, v115, 0x3fb8aa3b, v177
	v_max3_f32 v96, v100, v101, v102
	v_max3_f32 v91, v103, v104, v105
	v_max3_f32 v92, v106, v107, v108
	v_max3_f32 v93, v109, v110, v111
	v_max3_f32 v95, v112, v113, v114
	v_max3_f32 v96, v96, v91, v115
	v_max3_f32 v92, v92, v93, v95
	v_max_f32_e32 v96, v96, v92
	v_mov_b32_e32 v91, v96
	s_nop 1
	v_permlane16_swap_b32_e32 v96, v91
	v_max_f32_e32 v96, v96, v91
	v_mov_b32_e32 v91, v96
	s_nop 1
	v_permlane32_swap_b32_e32 v96, v91
	v_max_f32_e32 v96, v96, v91
	v_max_f32_e32 v92, v162, v96
	v_max_f32_e32 v94, 0xe0ad78ec, v162
	v_max_f32_e32 v93, 0xe0ad78ec, v92
	v_sub_f32_e32 v94, v94, v93
	v_mov_b32_e32 v162, v92
	v_exp_f32_e32 v94, v94
	v_sub_f32_e32 v100, v100, v93
	v_sub_f32_e32 v101, v101, v93
	v_sub_f32_e32 v102, v102, v93
	v_sub_f32_e32 v103, v103, v93
	v_exp_f32_e32 v100, v100
	v_exp_f32_e32 v101, v101
	v_exp_f32_e32 v102, v102
	v_exp_f32_e32 v103, v103
	v_sub_f32_e32 v104, v104, v93
	v_sub_f32_e32 v105, v105, v93
	v_sub_f32_e32 v106, v106, v93
	v_sub_f32_e32 v107, v107, v93
	v_exp_f32_e32 v104, v104
	v_exp_f32_e32 v105, v105
	v_exp_f32_e32 v106, v106
	v_exp_f32_e32 v107, v107
	v_sub_f32_e32 v108, v108, v93
	v_sub_f32_e32 v109, v109, v93
	v_sub_f32_e32 v110, v110, v93
	v_sub_f32_e32 v111, v111, v93
	v_exp_f32_e32 v108, v108
	v_exp_f32_e32 v109, v109
	v_exp_f32_e32 v110, v110
	v_exp_f32_e32 v111, v111
	v_sub_f32_e32 v112, v112, v93
	v_sub_f32_e32 v113, v113, v93
	v_sub_f32_e32 v114, v114, v93
	v_sub_f32_e32 v115, v115, v93
	v_exp_f32_e32 v112, v112
	v_exp_f32_e32 v113, v113
	v_exp_f32_e32 v114, v114
	v_exp_f32_e32 v115, v115
	s_nop 0
	v_add_f32_e32 v90, v100, v101
	v_add_f32_e32 v91, v102, v103
	v_add_f32_e32 v92, v104, v105
	v_add_f32_e32 v93, v106, v107
	v_add_f32_e32 v90, v90, v108
	v_add_f32_e32 v91, v91, v109
	v_add_f32_e32 v92, v92, v110
	v_add_f32_e32 v93, v93, v111
	v_add_f32_e32 v90, v90, v112
	v_add_f32_e32 v91, v91, v113
	v_add_f32_e32 v92, v92, v114
	v_add_f32_e32 v93, v93, v115
	v_add_f32_e32 v90, v90, v91
	v_add_f32_e32 v92, v92, v93
	v_add_f32_e32 v90, v90, v92
	v_cvt_pk_bf16_f32 v82, v100, v101
	v_cvt_pk_bf16_f32 v83, v102, v103
	v_cvt_pk_bf16_f32 v84, v104, v105
	v_cvt_pk_bf16_f32 v85, v106, v107
	v_cvt_pk_bf16_f32 v86, v108, v109
	v_cvt_pk_bf16_f32 v87, v110, v111
	v_cvt_pk_bf16_f32 v88, v112, v113
	v_cvt_pk_bf16_f32 v89, v114, v115
	v_mov_b32_e32 v91, v90
	s_nop 1
	v_permlane16_swap_b32_e32 v90, v91
	v_add_f32_e32 v90, v90, v91
	v_mov_b32_e32 v91, v90
	s_nop 1
	v_permlane32_swap_b32_e32 v90, v91
	v_add_f32_e32 v90, v90, v91
	v_fma_f32 v161, v161, v94, v90
	v_cmp_neq_f32_e64 s[4:5], 1.0, v94
	s_cmp_eq_u64 s[4:5], 0
	s_cbranch_scc1 .Lwn_nosc_15
	v_pk_mul_f32 v[46:47], v[46:47], v[94:95] op_sel_hi:[1,0]
	v_pk_mul_f32 v[48:49], v[48:49], v[94:95] op_sel_hi:[1,0]
	v_pk_mul_f32 v[42:43], v[42:43], v[94:95] op_sel_hi:[1,0]
	v_pk_mul_f32 v[44:45], v[44:45], v[94:95] op_sel_hi:[1,0]
	v_pk_mul_f32 v[38:39], v[38:39], v[94:95] op_sel_hi:[1,0]
	v_pk_mul_f32 v[40:41], v[40:41], v[94:95] op_sel_hi:[1,0]
	v_pk_mul_f32 v[34:35], v[34:35], v[94:95] op_sel_hi:[1,0]
	v_pk_mul_f32 v[36:37], v[36:37], v[94:95] op_sel_hi:[1,0]
; #define LAS __attribute__((address_space(3)))
; template <int D, class SF>
; __device__ __forceinline__ void attn_step(const bf16x8 (&qf)[D / 32], const LAS bf16_t* Ks, const LAS bf16_t* Vt, f32x4 (&o)[D / 16], float& m, float& lsum, float& alpha_out, bf16x8& pf0_out, bf16x8& pf1_out, const int lane, SF sf) {
;     ...
; #pragma unroll
;     for (int t = 0; t < 4; ++t) s[t] = (f32x4){0.f, 0.f, 0.f, 0.f};
; #pragma unroll
;     for (int ks = 0; ks < D / 32; ++ks) {
; #pragma unroll
;         for (int t = 0; t < 4; ++t) { const bf16x8 kf = *(const LAS bf16x8*)(Ks + (16 * t + c) * KSTR + ks * 32 + 8 * i); s[t] = mfma16(kf, qf[ks], s[t]); }
;     }
;     float v[16];
; #pragma unroll
;     for (int t = 0; t < 4; ++t)
; #pragma unroll
;         for (int r = 0; r < 4; ++r) v[4 * t + r] = sf(16 * t + 4 * i + r, s[t][r]);
;     float mx = fmaxf(fmaxf(fmaxf(v[0], v[1]), fmaxf(v[2], v[3])), fmaxf(fmaxf(v[4], v[5]), fmaxf(v[6], v[7])));
;     mx = fmaxf(mx, fmaxf(fmaxf(fmaxf(v[8], v[9]), fmaxf(v[10], v[11])), fmaxf(fmaxf(v[12], v[13]), fmaxf(v[14], v[15]))));
;     mx = rows_max(mx);
;     const float mnew = fmaxf(m, mx);
;     const float mc = fmaxf(mnew, -1e20f);
;     const float alpha = __builtin_amdgcn_exp2f(fmaxf(m, -1e20f) - mc);
;     float p[16], rs = 0.f;
; #pragma unroll
;     for (int r = 0; r < 16; ++r) { p[r] = __builtin_amdgcn_exp2f(v[r] - mc); rs += p[r]; }
;     rs = rows_sum(rs);
;     lsum = lsum * alpha + rs; m = mnew;
;     union { u32x4 u; bf16x8 b; } pk0, pk1;
;     pk0.u.x = cvt_pk_bf16(p[0], p[1]); pk0.u.y = cvt_pk_bf16(p[2], p[3]); pk0.u.z = cvt_pk_bf16(p[4], p[5]); pk0.u.w = cvt_pk_bf16(p[6], p[7]);
;     pk1.u.x = cvt_pk_bf16(p[8], p[9]); pk1.u.y = cvt_pk_bf16(p[10], p[11]); pk1.u.z = cvt_pk_bf16(p[12], p[13]); pk1.u.w = cvt_pk_bf16(p[14], p[15]);
;     if (__builtin_amdgcn_ballot_w64(alpha != 1.0f) != 0ull) {
; #pragma unroll
;         for (int dt = 0; dt < D / 16; ++dt) o[dt] *= alpha;
;     }
; #pragma unroll
;     for (int dt = 0; dt < D / 16; ++dt) {
;         const LAS bf16_t* vp = Vt + (16 * dt + c) * 72 + 4 * i;
;         union { u32x4 u; bf16x8 b; } vf0, vf1; const u32x2 a0 = *(const LAS u32x2*)vp, a1 = *(const LAS u32x2*)(vp + 16), b0 = *(const LAS u32x2*)(vp + 32), b1 = *(const LAS u32x2*)(vp + 48);
;         vf0.u.x = a0.x; vf0.u.y = a0.y; vf0.u.z = a1.x; vf0.u.w = a1.y; vf1.u.x = b0.x; vf1.u.y = b0.y; vf1.u.z = b1.x; vf1.u.w = b1.y;
.Lwn_nosc_15:
	s_waitcnt lgkmcnt(0)
	s_nop 1
	v_mfma_f32_16x16x32_bf16 v[46:49], v[50:53], v[82:85], v[46:49]
	v_mfma_f32_16x16x32_bf16 v[42:45], v[58:61], v[82:85], v[42:45]
	v_mfma_f32_16x16x32_bf16 v[38:41], v[66:69], v[82:85], v[38:41]
	v_mfma_f32_16x16x32_bf16 v[34:37], v[74:77], v[82:85], v[34:37]
	v_mfma_f32_16x16x32_bf16 v[46:49], v[54:57], v[86:89], v[46:49]
	v_mfma_f32_16x16x32_bf16 v[42:45], v[62:65], v[86:89], v[42:45]
	v_mfma_f32_16x16x32_bf16 v[38:41], v[70:73], v[86:89], v[38:41]
	v_mfma_f32_16x16x32_bf16 v[34:37], v[78:81], v[86:89], v[34:37]
	v_sub_u32_e32 v90, v180, v139
	v_subrev_u32_e32 v90, s21, v90
	v_lshl_add_u32 v91, v90, 2, v131
	v_add_u32_e32 v91, 0xffffff34, v91
	ds_read_b32 v170, v91 offset:204
	ds_read_b32 v171, v91 offset:200
	ds_read_b32 v172, v91 offset:196
	ds_read_b32 v173, v91 offset:192
	ds_read_b32 v174, v91 offset:140
	ds_read_b32 v175, v91 offset:136
	ds_read_b32 v176, v91 offset:132
	ds_read_b32 v177, v91 offset:128
	ds_read_b128 v[50:53], v178 offset:36864
	ds_read_b128 v[58:61], v178 offset:39424
	ds_read_b128 v[54:57], v178 offset:36928
	ds_read_b128 v[62:65], v178 offset:39488
	ds_read_b128 v[66:69], v178 offset:41984
	ds_read_b128 v[74:77], v178 offset:44544
	ds_read_b128 v[70:73], v178 offset:42048
	ds_read_b128 v[78:81], v178 offset:44608
	s_waitcnt lgkmcnt(6)
	v_mfma_f32_16x16x32_bf16 v[100:103], v[50:53], v[10:13], 0
	v_mfma_f32_16x16x32_bf16 v[104:107], v[58:61], v[10:13], 0
	s_waitcnt lgkmcnt(4)
	v_mfma_f32_16x16x32_bf16 v[100:103], v[54:57], v[14:17], v[100:103]
	v_mfma_f32_16x16x32_bf16 v[104:107], v[62:65], v[14:17], v[104:107]
	s_waitcnt lgkmcnt(2)
	v_mfma_f32_16x16x32_bf16 v[108:111], v[66:69], v[10:13], 0
	v_mfma_f32_16x16x32_bf16 v[112:115], v[74:77], v[10:13], 0
	s_waitcnt lgkmcnt(0)
	v_mfma_f32_16x16x32_bf16 v[108:111], v[70:73], v[14:17], v[108:111]
	v_mfma_f32_16x16x32_bf16 v[112:115], v[78:81], v[14:17], v[112:115]
	ds_read_b64_tr_b16 v[50:51], v179 offset:47104
	ds_read_b64_tr_b16 v[52:53], v179 offset:49664
	ds_read_b64_tr_b16 v[54:55], v179 offset:52224
	ds_read_b64_tr_b16 v[56:57], v179 offset:54784
	ds_read_b64_tr_b16 v[58:59], v179 offset:47136
	ds_read_b64_tr_b16 v[60:61], v179 offset:49696
	ds_read_b64_tr_b16 v[62:63], v179 offset:52256
	v_fmamk_f32 v100, v100, 0x3fb8aa3b, v170
	v_fmamk_f32 v101, v101, 0x3fb8aa3b, v171
	v_fmamk_f32 v102, v102, 0x3fb8aa3b, v172
	v_fmamk_f32 v103, v103, 0x3fb8aa3b, v173
	v_fmamk_f32 v104, v104, 0x3fb8aa3b, v174
	v_fmamk_f32 v105, v105, 0x3fb8aa3b, v175
	v_fmamk_f32 v106, v106, 0x3fb8aa3b, v176
	v_fmamk_f32 v107, v107, 0x3fb8aa3b, v177
	ds_read_b32 v170, v91 offset:76
	ds_read_b32 v171, v91 offset:72
	ds_read_b32 v172, v91 offset:68
	ds_read_b32 v173, v91 offset:64
	ds_read_b32 v174, v91 offset:12
	ds_read_b32 v175, v91 offset:8
	ds_read_b32 v176, v91 offset:4
	ds_read_b32 v177, v91 offset:0
	ds_read_b64_tr_b16 v[64:65], v179 offset:54816
	ds_read_b64_tr_b16 v[66:67], v179 offset:47168
	ds_read_b64_tr_b16 v[68:69], v179 offset:49728
	ds_read_b64_tr_b16 v[70:71], v179 offset:52288
	ds_read_b64_tr_b16 v[72:73], v179 offset:54848
	ds_read_b64_tr_b16 v[74:75], v179 offset:47200
	ds_read_b64_tr_b16 v[76:77], v179 offset:49760
	ds_read_b64_tr_b16 v[78:79], v179 offset:52320
	ds_read_b64_tr_b16 v[80:81], v179 offset:54880
	s_waitcnt lgkmcnt(9)
	v_fmamk_f32 v108, v108, 0x3fb8aa3b, v170
	v_fmamk_f32 v109, v109, 0x3fb8aa3b, v171
	v_fmamk_f32 v110, v110, 0x3fb8aa3b, v172
	v_fmamk_f32 v111, v111, 0x3fb8aa3b, v173
	v_fmamk_f32 v112, v112, 0x3fb8aa3b, v174
	v_fmamk_f32 v113, v113, 0x3fb8aa3b, v175
	v_fmamk_f32 v114, v114, 0x3fb8aa3b, v176
	v_fmamk_f32 v115, v115, 0x3fb8aa3b, v177
	v_max3_f32 v96, v100, v101, v102
	v_max3_f32 v91, v103, v104, v105
	v_max3_f32 v92, v106, v107, v108
	v_max3_f32 v93, v109, v110, v111
	v_max3_f32 v95, v112, v113, v114
	v_max3_f32 v96, v96, v91, v115
	v_max3_f32 v92, v92, v93, v95
	v_max_f32_e32 v96, v96, v92
	v_mov_b32_e32 v91, v96
	s_nop 1
	v_permlane16_swap_b32_e32 v96, v91
	v_max_f32_e32 v96, v96, v91
	v_mov_b32_e32 v91, v96
	s_nop 1
	v_permlane32_swap_b32_e32 v96, v91
	v_max_f32_e32 v96, v96, v91
	v_max_f32_e32 v92, v160, v96
	v_max_f32_e32 v94, 0xe0ad78ec, v160
	v_max_f32_e32 v93, 0xe0ad78ec, v92
	v_sub_f32_e32 v94, v94, v93
	v_mov_b32_e32 v160, v92
	v_exp_f32_e32 v94, v94
	v_sub_f32_e32 v100, v100, v93
	v_sub_f32_e32 v101, v101, v93
	v_sub_f32_e32 v102, v102, v93
	v_sub_f32_e32 v103, v103, v93
	v_exp_f32_e32 v100, v100
	v_exp_f32_e32 v101, v101
	v_exp_f32_e32 v102, v102
	v_exp_f32_e32 v103, v103
	v_sub_f32_e32 v104, v104, v93
	v_sub_f32_e32 v105, v105, v93
	v_sub_f32_e32 v106, v106, v93
	v_sub_f32_e32 v107, v107, v93
	v_exp_f32_e32 v104, v104
	v_exp_f32_e32 v105, v105
	v_exp_f32_e32 v106, v106
	v_exp_f32_e32 v107, v107
	v_sub_f32_e32 v108, v108, v93
	v_sub_f32_e32 v109, v109, v93
	v_sub_f32_e32 v110, v110, v93
	v_sub_f32_e32 v111, v111, v93
	v_exp_f32_e32 v108, v108
	v_exp_f32_e32 v109, v109
	v_exp_f32_e32 v110, v110
	v_exp_f32_e32 v111, v111
	v_sub_f32_e32 v112, v112, v93
	v_sub_f32_e32 v113, v113, v93
	v_sub_f32_e32 v114, v114, v93
	v_sub_f32_e32 v115, v115, v93
	v_exp_f32_e32 v112, v112
	v_exp_f32_e32 v113, v113
	v_exp_f32_e32 v114, v114
	v_exp_f32_e32 v115, v115
	s_nop 0
	v_add_f32_e32 v90, v100, v101
	v_add_f32_e32 v91, v102, v103
	v_add_f32_e32 v92, v104, v105
	v_add_f32_e32 v93, v106, v107
	v_add_f32_e32 v90, v90, v108
	v_add_f32_e32 v91, v91, v109
	v_add_f32_e32 v92, v92, v110
	v_add_f32_e32 v93, v93, v111
	v_add_f32_e32 v90, v90, v112
	v_add_f32_e32 v91, v91, v113
	v_add_f32_e32 v92, v92, v114
	v_add_f32_e32 v93, v93, v115
	v_add_f32_e32 v90, v90, v91
	v_add_f32_e32 v92, v92, v93
	v_add_f32_e32 v90, v90, v92
	v_cvt_pk_bf16_f32 v82, v100, v101
	v_cvt_pk_bf16_f32 v83, v102, v103
	v_cvt_pk_bf16_f32 v84, v104, v105
	v_cvt_pk_bf16_f32 v85, v106, v107
	v_cvt_pk_bf16_f32 v86, v108, v109
	v_cvt_pk_bf16_f32 v87, v110, v111
	v_cvt_pk_bf16_f32 v88, v112, v113
	v_cvt_pk_bf16_f32 v89, v114, v115
	v_mov_b32_e32 v91, v90
	s_nop 1
	v_permlane16_swap_b32_e32 v90, v91
	v_add_f32_e32 v90, v90, v91
	v_mov_b32_e32 v91, v90
	s_nop 1
	v_permlane32_swap_b32_e32 v90, v91
	v_add_f32_e32 v90, v90, v91
	v_fma_f32 v159, v159, v94, v90
	v_cmp_neq_f32_e64 s[4:5], 1.0, v94
	s_cmp_eq_u64 s[4:5], 0
	s_cbranch_scc1 .Lwn_nosc_16
	v_pk_mul_f32 v[30:31], v[30:31], v[94:95] op_sel_hi:[1,0]
	v_pk_mul_f32 v[32:33], v[32:33], v[94:95] op_sel_hi:[1,0]
	v_pk_mul_f32 v[26:27], v[26:27], v[94:95] op_sel_hi:[1,0]
	v_pk_mul_f32 v[28:29], v[28:29], v[94:95] op_sel_hi:[1,0]
	v_pk_mul_f32 v[22:23], v[22:23], v[94:95] op_sel_hi:[1,0]
	v_pk_mul_f32 v[24:25], v[24:25], v[94:95] op_sel_hi:[1,0]
	v_pk_mul_f32 v[18:19], v[18:19], v[94:95] op_sel_hi:[1,0]
	v_pk_mul_f32 v[20:21], v[20:21], v[94:95] op_sel_hi:[1,0]

; template <int D, class SF>
; __device__ __forceinline__ void attn_step(const bf16x8 (&qf)[D / 32], const LAS bf16_t* Ks, const LAS bf16_t* Vt, f32x4 (&o)[D / 16], float& m, float& lsum, float& alpha_out, bf16x8& pf0_out, bf16x8& pf1_out, const int lane, SF sf) {
;     ...
; #pragma unroll
;     for (int t = 0; t < 4; ++t) s[t] = (f32x4){0.f, 0.f, 0.f, 0.f};
; #pragma unroll
;     for (int ks = 0; ks < D / 32; ++ks) {
; #pragma unroll
;         for (int t = 0; t < 4; ++t) { const bf16x8 kf = *(const LAS bf16x8*)(Ks + (16 * t + c) * KSTR + ks * 32 + 8 * i); s[t] = mfma16(kf, qf[ks], s[t]); }
;     }
;     float v[16];
; #pragma unroll
;     for (int t = 0; t < 4; ++t)
; #pragma unroll
;         for (int r = 0; r < 4; ++r) v[4 * t + r] = sf(16 * t + 4 * i + r, s[t][r]);
;     float mx = fmaxf(fmaxf(fmaxf(v[0], v[1]), fmaxf(v[2], v[3])), fmaxf(fmaxf(v[4], v[5]), fmaxf(v[6], v[7])));
;     mx = fmaxf(mx, fmaxf(fmaxf(fmaxf(v[8], v[9]), fmaxf(v[10], v[11])), fmaxf(fmaxf(v[12], v[13]), fmaxf(v[14], v[15]))));
;     mx = rows_max(mx);
;     const float mnew = fmaxf(m, mx);
;     const float mc = fmaxf(mnew, -1e20f);
;     const float alpha = __builtin_amdgcn_exp2f(fmaxf(m, -1e20f) - mc);
;     float p[16], rs = 0.f;
; #pragma unroll
;     for (int r = 0; r < 16; ++r) { p[r] = __builtin_amdgcn_exp2f(v[r] - mc); rs += p[r]; }
;     rs = rows_sum(rs);
;     lsum = lsum * alpha + rs; m = mnew;
;     union { u32x4 u; bf16x8 b; } pk0, pk1;
;     pk0.u.x = cvt_pk_bf16(p[0], p[1]); pk0.u.y = cvt_pk_bf16(p[2], p[3]); pk0.u.z = cvt_pk_bf16(p[4], p[5]); pk0.u.w = cvt_pk_bf16(p[6], p[7]);
;     pk1.u.x = cvt_pk_bf16(p[8], p[9]); pk1.u.y = cvt_pk_bf16(p[10], p[11]); pk1.u.z = cvt_pk_bf16(p[12], p[13]); pk1.u.w = cvt_pk_bf16(p[14], p[15]);
;     if (__builtin_amdgcn_ballot_w64(alpha != 1.0f) != 0ull) {
; #pragma unroll
;         for (int dt = 0; dt < D / 16; ++dt) o[dt] *= alpha;
;     }
; __device__ __forceinline__ void nsa_unit(LAS unsigned char* lds, const Ctx& P, int l, int b, int hkv, int tb) {
;     ...
;             for (int sl = 0; sl < 2; ++sl) if (sl == 0 || hasb) { const LAS bf16_t* Ks = KV + sl * 9216; const LAS bf16_t* Vt = Ks + 4608; const int kp0 = p0 + sl * 64;
; #pragma unroll
;                 for (int sb = 0; sb < 2; ++sb) { const int tqs = tq[sb];
;                     attn_step<64>(qf[sb], Ks, Vt, o[sb], m[sb], lsum[sb], alpha, pf, pf1, lane,
.Lwn_wc_14:
	s_cmp_gt_u32 s20, 2
	s_cbranch_scc1 .Lwn_wc_17
	s_add_i32 s21, s12, 128
	v_sub_u32_e32 v90, v130, v139
	v_subrev_u32_e32 v90, s21, v90
	v_lshl_add_u32 v91, v90, 2, v131
	v_add_u32_e32 v91, 0xffffff34, v91
	ds_read_b32 v170, v91 offset:204
	ds_read_b32 v171, v91 offset:200
	ds_read_b32 v172, v91 offset:196
	ds_read_b32 v173, v91 offset:192
	ds_read_b32 v174, v91 offset:140
	ds_read_b32 v175, v91 offset:136
	ds_read_b32 v176, v91 offset:132
	ds_read_b32 v177, v91 offset:128
	ds_read_b128 v[50:53], v116 offset:0
	ds_read_b128 v[58:61], v116 offset:2560
	ds_read_b128 v[54:57], v116 offset:64
	ds_read_b128 v[62:65], v116 offset:2624
	ds_read_b128 v[66:69], v116 offset:5120
	ds_read_b128 v[74:77], v116 offset:7680
	ds_read_b128 v[70:73], v116 offset:5184
	ds_read_b128 v[78:81], v116 offset:7744
	s_waitcnt lgkmcnt(6)
	v_mfma_f32_16x16x32_bf16 v[100:103], v[50:53], v[2:5], 0
	v_mfma_f32_16x16x32_bf16 v[104:107], v[58:61], v[2:5], 0
	s_waitcnt lgkmcnt(4)
	v_mfma_f32_16x16x32_bf16 v[100:103], v[54:57], v[6:9], v[100:103]
	v_mfma_f32_16x16x32_bf16 v[104:107], v[62:65], v[6:9], v[104:107]
	s_waitcnt lgkmcnt(2)
	v_mfma_f32_16x16x32_bf16 v[108:111], v[66:69], v[2:5], 0
	v_mfma_f32_16x16x32_bf16 v[112:115], v[74:77], v[2:5], 0
	s_waitcnt lgkmcnt(0)
	v_mfma_f32_16x16x32_bf16 v[108:111], v[70:73], v[6:9], v[108:111]
	v_mfma_f32_16x16x32_bf16 v[112:115], v[78:81], v[6:9], v[112:115]
	ds_read_b64_tr_b16 v[50:51], v117 offset:10240
	ds_read_b64_tr_b16 v[52:53], v117 offset:12800
	ds_read_b64_tr_b16 v[54:55], v117 offset:15360
	ds_read_b64_tr_b16 v[56:57], v117 offset:17920
	ds_read_b64_tr_b16 v[58:59], v117 offset:10272
	ds_read_b64_tr_b16 v[60:61], v117 offset:12832
	ds_read_b64_tr_b16 v[62:63], v117 offset:15392
	v_fmamk_f32 v100, v100, 0x3fb8aa3b, v170
	v_fmamk_f32 v101, v101, 0x3fb8aa3b, v171
	v_fmamk_f32 v102, v102, 0x3fb8aa3b, v172
	v_fmamk_f32 v103, v103, 0x3fb8aa3b, v173
	v_fmamk_f32 v104, v104, 0x3fb8aa3b, v174
	v_fmamk_f32 v105, v105, 0x3fb8aa3b, v175
	v_fmamk_f32 v106, v106, 0x3fb8aa3b, v176
	v_fmamk_f32 v107, v107, 0x3fb8aa3b, v177
	ds_read_b32 v170, v91 offset:76
	ds_read_b32 v171, v91 offset:72
	ds_read_b32 v172, v91 offset:68
	ds_read_b32 v173, v91 offset:64
	ds_read_b32 v174, v91 offset:12
	ds_read_b32 v175, v91 offset:8
	ds_read_b32 v176, v91 offset:4
	ds_read_b32 v177, v91 offset:0
	ds_read_b64_tr_b16 v[64:65], v117 offset:17952
	ds_read_b64_tr_b16 v[66:67], v117 offset:10304
	ds_read_b64_tr_b16 v[68:69], v117 offset:12864
	ds_read_b64_tr_b16 v[70:71], v117 offset:15424
	ds_read_b64_tr_b16 v[72:73], v117 offset:17984
	ds_read_b64_tr_b16 v[74:75], v117 offset:10336
	ds_read_b64_tr_b16 v[76:77], v117 offset:12896
	ds_read_b64_tr_b16 v[78:79], v117 offset:15456
	ds_read_b64_tr_b16 v[80:81], v117 offset:18016
	s_waitcnt lgkmcnt(9)
	v_fmamk_f32 v108, v108, 0x3fb8aa3b, v170
	v_fmamk_f32 v109, v109, 0x3fb8aa3b, v171
	v_fmamk_f32 v110, v110, 0x3fb8aa3b, v172
	v_fmamk_f32 v111, v111, 0x3fb8aa3b, v173
	v_fmamk_f32 v112, v112, 0x3fb8aa3b, v174
	v_fmamk_f32 v113, v113, 0x3fb8aa3b, v175
	v_fmamk_f32 v114, v114, 0x3fb8aa3b, v176
	v_fmamk_f32 v115, v115, 0x3fb8aa3b, v177
	v_max3_f32 v96, v100, v101, v102
	v_max3_f32 v91, v103, v104, v105
	v_max3_f32 v92, v106, v107, v108
	v_max3_f32 v93, v109, v110, v111
	v_max3_f32 v95, v112, v113, v114
	v_max3_f32 v96, v96, v91, v115
	v_max3_f32 v92, v92, v93, v95
	v_max_f32_e32 v96, v96, v92
	v_mov_b32_e32 v91, v96
	s_nop 1
	v_permlane16_swap_b32_e32 v96, v91
	v_max_f32_e32 v96, v96, v91
	v_mov_b32_e32 v91, v96
	s_nop 1
	v_permlane32_swap_b32_e32 v96, v91
	v_max_f32_e32 v96, v96, v91
	v_max_f32_e32 v92, v162, v96
	v_max_f32_e32 v94, 0xe0ad78ec, v162
	v_max_f32_e32 v93, 0xe0ad78ec, v92
	v_sub_f32_e32 v94, v94, v93
	v_mov_b32_e32 v162, v92
	v_exp_f32_e32 v94, v94
	v_sub_f32_e32 v100, v100, v93
	v_sub_f32_e32 v101, v101, v93
	v_sub_f32_e32 v102, v102, v93
	v_sub_f32_e32 v103, v103, v93
	v_exp_f32_e32 v100, v100
	v_exp_f32_e32 v101, v101
	v_exp_f32_e32 v102, v102
	v_exp_f32_e32 v103, v103
	v_sub_f32_e32 v104, v104, v93
	v_sub_f32_e32 v105, v105, v93
	v_sub_f32_e32 v106, v106, v93
	v_sub_f32_e32 v107, v107, v93
	v_exp_f32_e32 v104, v104
	v_exp_f32_e32 v105, v105
	v_exp_f32_e32 v106, v106
	v_exp_f32_e32 v107, v107
	v_sub_f32_e32 v108, v108, v93
	v_sub_f32_e32 v109, v109, v93
	v_sub_f32_e32 v110, v110, v93
	v_sub_f32_e32 v111, v111, v93
	v_exp_f32_e32 v108, v108
	v_exp_f32_e32 v109, v109
	v_exp_f32_e32 v110, v110
	v_exp_f32_e32 v111, v111
	v_sub_f32_e32 v112, v112, v93
	v_sub_f32_e32 v113, v113, v93
	v_sub_f32_e32 v114, v114, v93
	v_sub_f32_e32 v115, v115, v93
	v_exp_f32_e32 v112, v112
	v_exp_f32_e32 v113, v113
	v_exp_f32_e32 v114, v114
	v_exp_f32_e32 v115, v115
	s_nop 0
	v_add_f32_e32 v90, v100, v101
	v_add_f32_e32 v91, v102, v103
	v_add_f32_e32 v92, v104, v105
	v_add_f32_e32 v93, v106, v107
	v_add_f32_e32 v90, v90, v108
	v_add_f32_e32 v91, v91, v109
	v_add_f32_e32 v92, v92, v110
	v_add_f32_e32 v93, v93, v111
	v_add_f32_e32 v90, v90, v112
	v_add_f32_e32 v91, v91, v113
	v_add_f32_e32 v92, v92, v114
	v_add_f32_e32 v93, v93, v115
	v_add_f32_e32 v90, v90, v91
	v_add_f32_e32 v92, v92, v93
	v_add_f32_e32 v90, v90, v92
	v_cvt_pk_bf16_f32 v82, v100, v101
	v_cvt_pk_bf16_f32 v83, v102, v103
	v_cvt_pk_bf16_f32 v84, v104, v105
	v_cvt_pk_bf16_f32 v85, v106, v107
	v_cvt_pk_bf16_f32 v86, v108, v109
	v_cvt_pk_bf16_f32 v87, v110, v111
	v_cvt_pk_bf16_f32 v88, v112, v113
	v_cvt_pk_bf16_f32 v89, v114, v115
	v_mov_b32_e32 v91, v90
	s_nop 1
	v_permlane16_swap_b32_e32 v90, v91
	v_add_f32_e32 v90, v90, v91
	v_mov_b32_e32 v91, v90
	s_nop 1
	v_permlane32_swap_b32_e32 v90, v91
	v_add_f32_e32 v90, v90, v91
	v_fma_f32 v161, v161, v94, v90
	v_cmp_neq_f32_e64 s[4:5], 1.0, v94
	s_cmp_eq_u64 s[4:5], 0
	s_cbranch_scc1 .Lwn_nosc_18
	v_pk_mul_f32 v[46:47], v[46:47], v[94:95] op_sel_hi:[1,0]
	v_pk_mul_f32 v[48:49], v[48:49], v[94:95] op_sel_hi:[1,0]
	v_pk_mul_f32 v[42:43], v[42:43], v[94:95] op_sel_hi:[1,0]
	v_pk_mul_f32 v[44:45], v[44:45], v[94:95] op_sel_hi:[1,0]
	v_pk_mul_f32 v[38:39], v[38:39], v[94:95] op_sel_hi:[1,0]
	v_pk_mul_f32 v[40:41], v[40:41], v[94:95] op_sel_hi:[1,0]
	v_pk_mul_f32 v[34:35], v[34:35], v[94:95] op_sel_hi:[1,0]
	v_pk_mul_f32 v[36:37], v[36:37], v[94:95] op_sel_hi:[1,0]
; #define LAS __attribute__((address_space(3)))
; template <int D, class SF>
; __device__ __forceinline__ void attn_step(const bf16x8 (&qf)[D / 32], const LAS bf16_t* Ks, const LAS bf16_t* Vt, f32x4 (&o)[D / 16], float& m, float& lsum, float& alpha_out, bf16x8& pf0_out, bf16x8& pf1_out, const int lane, SF sf) {
;     ...
; #pragma unroll
;     for (int t = 0; t < 4; ++t) s[t] = (f32x4){0.f, 0.f, 0.f, 0.f};
; #pragma unroll
;     for (int ks = 0; ks < D / 32; ++ks) {
; #pragma unroll
;         for (int t = 0; t < 4; ++t) { const bf16x8 kf = *(const LAS bf16x8*)(Ks + (16 * t + c) * KSTR + ks * 32 + 8 * i); s[t] = mfma16(kf, qf[ks], s[t]); }
;     }
;     float v[16];
; #pragma unroll
;     for (int t = 0; t < 4; ++t)
; #pragma unroll
;         for (int r = 0; r < 4; ++r) v[4 * t + r] = sf(16 * t + 4 * i + r, s[t][r]);
;     float mx = fmaxf(fmaxf(fmaxf(v[0], v[1]), fmaxf(v[2], v[3])), fmaxf(fmaxf(v[4], v[5]), fmaxf(v[6], v[7])));
;     mx = fmaxf(mx, fmaxf(fmaxf(fmaxf(v[8], v[9]), fmaxf(v[10], v[11])), fmaxf(fmaxf(v[12], v[13]), fmaxf(v[14], v[15]))));
;     mx = rows_max(mx);
;     const float mnew = fmaxf(m, mx);
;     const float mc = fmaxf(mnew, -1e20f);
;     const float alpha = __builtin_amdgcn_exp2f(fmaxf(m, -1e20f) - mc);
;     float p[16], rs = 0.f;
; #pragma unroll
;     for (int r = 0; r < 16; ++r) { p[r] = __builtin_amdgcn_exp2f(v[r] - mc); rs += p[r]; }
;     rs = rows_sum(rs);
;     lsum = lsum * alpha + rs; m = mnew;
;     union { u32x4 u; bf16x8 b; } pk0, pk1;
;     pk0.u.x = cvt_pk_bf16(p[0], p[1]); pk0.u.y = cvt_pk_bf16(p[2], p[3]); pk0.u.z = cvt_pk_bf16(p[4], p[5]); pk0.u.w = cvt_pk_bf16(p[6], p[7]);
;     pk1.u.x = cvt_pk_bf16(p[8], p[9]); pk1.u.y = cvt_pk_bf16(p[10], p[11]); pk1.u.z = cvt_pk_bf16(p[12], p[13]); pk1.u.w = cvt_pk_bf16(p[14], p[15]);
;     if (__builtin_amdgcn_ballot_w64(alpha != 1.0f) != 0ull) {
; #pragma unroll
;         for (int dt = 0; dt < D / 16; ++dt) o[dt] *= alpha;
;     }
; #pragma unroll
;     for (int dt = 0; dt < D / 16; ++dt) {
;         const LAS bf16_t* vp = Vt + (16 * dt + c) * 72 + 4 * i;
;         union { u32x4 u; bf16x8 b; } vf0, vf1; const u32x2 a0 = *(const LAS u32x2*)vp, a1 = *(const LAS u32x2*)(vp + 16), b0 = *(const LAS u32x2*)(vp + 32), b1 = *(const LAS u32x2*)(vp + 48);
;         vf0.u.x = a0.x; vf0.u.y = a0.y; vf0.u.z = a1.x; vf0.u.w = a1.y; vf1.u.x = b0.x; vf1.u.y = b0.y; vf1.u.z = b1.x; vf1.u.w = b1.y;
.Lwn_nosc_18:
	s_waitcnt lgkmcnt(0)
	s_nop 1
	v_mfma_f32_16x16x32_bf16 v[46:49], v[50:53], v[82:85], v[46:49]
	v_mfma_f32_16x16x32_bf16 v[42:45], v[58:61], v[82:85], v[42:45]
	v_mfma_f32_16x16x32_bf16 v[38:41], v[66:69], v[82:85], v[38:41]
	v_mfma_f32_16x16x32_bf16 v[34:37], v[74:77], v[82:85], v[34:37]
	v_mfma_f32_16x16x32_bf16 v[46:49], v[54:57], v[86:89], v[46:49]
	v_mfma_f32_16x16x32_bf16 v[42:45], v[62:65], v[86:89], v[42:45]
	v_mfma_f32_16x16x32_bf16 v[38:41], v[70:73], v[86:89], v[38:41]
	v_mfma_f32_16x16x32_bf16 v[34:37], v[78:81], v[86:89], v[34:37]
	v_sub_u32_e32 v90, v180, v139
	v_subrev_u32_e32 v90, s21, v90
	v_lshl_add_u32 v91, v90, 2, v131
	v_add_u32_e32 v91, 0xffffff34, v91
	ds_read_b32 v170, v91 offset:204
	ds_read_b32 v171, v91 offset:200
	ds_read_b32 v172, v91 offset:196
	ds_read_b32 v173, v91 offset:192
	ds_read_b32 v174, v91 offset:140
	ds_read_b32 v175, v91 offset:136
	ds_read_b32 v176, v91 offset:132
	ds_read_b32 v177, v91 offset:128
	ds_read_b128 v[50:53], v116 offset:0
	ds_read_b128 v[58:61], v116 offset:2560
	ds_read_b128 v[54:57], v116 offset:64
	ds_read_b128 v[62:65], v116 offset:2624
	ds_read_b128 v[66:69], v116 offset:5120
	ds_read_b128 v[74:77], v116 offset:7680
	ds_read_b128 v[70:73], v116 offset:5184
	ds_read_b128 v[78:81], v116 offset:7744
	s_waitcnt lgkmcnt(6)
	v_mfma_f32_16x16x32_bf16 v[100:103], v[50:53], v[10:13], 0
	v_mfma_f32_16x16x32_bf16 v[104:107], v[58:61], v[10:13], 0
	s_waitcnt lgkmcnt(4)
	v_mfma_f32_16x16x32_bf16 v[100:103], v[54:57], v[14:17], v[100:103]
	v_mfma_f32_16x16x32_bf16 v[104:107], v[62:65], v[14:17], v[104:107]
	s_waitcnt lgkmcnt(2)
	v_mfma_f32_16x16x32_bf16 v[108:111], v[66:69], v[10:13], 0
	v_mfma_f32_16x16x32_bf16 v[112:115], v[74:77], v[10:13], 0
	s_waitcnt lgkmcnt(0)
	v_mfma_f32_16x16x32_bf16 v[108:111], v[70:73], v[14:17], v[108:111]
	v_mfma_f32_16x16x32_bf16 v[112:115], v[78:81], v[14:17], v[112:115]
	ds_read_b64_tr_b16 v[50:51], v117 offset:10240
	ds_read_b64_tr_b16 v[52:53], v117 offset:12800
	ds_read_b64_tr_b16 v[54:55], v117 offset:15360
	ds_read_b64_tr_b16 v[56:57], v117 offset:17920
	ds_read_b64_tr_b16 v[58:59], v117 offset:10272
	ds_read_b64_tr_b16 v[60:61], v117 offset:12832
	ds_read_b64_tr_b16 v[62:63], v117 offset:15392
	v_fmamk_f32 v100, v100, 0x3fb8aa3b, v170
	v_fmamk_f32 v101, v101, 0x3fb8aa3b, v171
	v_fmamk_f32 v102, v102, 0x3fb8aa3b, v172
	v_fmamk_f32 v103, v103, 0x3fb8aa3b, v173
	v_fmamk_f32 v104, v104, 0x3fb8aa3b, v174
	v_fmamk_f32 v105, v105, 0x3fb8aa3b, v175
	v_fmamk_f32 v106, v106, 0x3fb8aa3b, v176
	v_fmamk_f32 v107, v107, 0x3fb8aa3b, v177
	ds_read_b32 v170, v91 offset:76
	ds_read_b32 v171, v91 offset:72
	ds_read_b32 v172, v91 offset:68
	ds_read_b32 v173, v91 offset:64
	ds_read_b32 v174, v91 offset:12
	ds_read_b32 v175, v91 offset:8
	ds_read_b32 v176, v91 offset:4
	ds_read_b32 v177, v91 offset:0
	ds_read_b64_tr_b16 v[64:65], v117 offset:17952
	ds_read_b64_tr_b16 v[66:67], v117 offset:10304
	ds_read_b64_tr_b16 v[68:69], v117 offset:12864
	ds_read_b64_tr_b16 v[70:71], v117 offset:15424
	ds_read_b64_tr_b16 v[72:73], v117 offset:17984
	ds_read_b64_tr_b16 v[74:75], v117 offset:10336
	ds_read_b64_tr_b16 v[76:77], v117 offset:12896
	ds_read_b64_tr_b16 v[78:79], v117 offset:15456
	ds_read_b64_tr_b16 v[80:81], v117 offset:18016
	s_waitcnt lgkmcnt(9)
	v_fmamk_f32 v108, v108, 0x3fb8aa3b, v170
	v_fmamk_f32 v109, v109, 0x3fb8aa3b, v171
	v_fmamk_f32 v110, v110, 0x3fb8aa3b, v172
	v_fmamk_f32 v111, v111, 0x3fb8aa3b, v173
	v_fmamk_f32 v112, v112, 0x3fb8aa3b, v174
	v_fmamk_f32 v113, v113, 0x3fb8aa3b, v175
	v_fmamk_f32 v114, v114, 0x3fb8aa3b, v176
	v_fmamk_f32 v115, v115, 0x3fb8aa3b, v177
	v_max3_f32 v96, v100, v101, v102
	v_max3_f32 v91, v103, v104, v105
	v_max3_f32 v92, v106, v107, v108
	v_max3_f32 v93, v109, v110, v111
	v_max3_f32 v95, v112, v113, v114
	v_max3_f32 v96, v96, v91, v115
	v_max3_f32 v92, v92, v93, v95
	v_max_f32_e32 v96, v96, v92
	v_mov_b32_e32 v91, v96
	s_nop 1
	v_permlane16_swap_b32_e32 v96, v91
	v_max_f32_e32 v96, v96, v91
	v_mov_b32_e32 v91, v96
	s_nop 1
	v_permlane32_swap_b32_e32 v96, v91
	v_max_f32_e32 v96, v96, v91
	v_max_f32_e32 v92, v160, v96
	v_max_f32_e32 v94, 0xe0ad78ec, v160
	v_max_f32_e32 v93, 0xe0ad78ec, v92
	v_sub_f32_e32 v94, v94, v93
	v_mov_b32_e32 v160, v92
	v_exp_f32_e32 v94, v94
	v_sub_f32_e32 v100, v100, v93
	v_sub_f32_e32 v101, v101, v93
	v_sub_f32_e32 v102, v102, v93
	v_sub_f32_e32 v103, v103, v93
	v_exp_f32_e32 v100, v100
	v_exp_f32_e32 v101, v101
	v_exp_f32_e32 v102, v102
	v_exp_f32_e32 v103, v103
	v_sub_f32_e32 v104, v104, v93
	v_sub_f32_e32 v105, v105, v93
	v_sub_f32_e32 v106, v106, v93
	v_sub_f32_e32 v107, v107, v93
	v_exp_f32_e32 v104, v104
	v_exp_f32_e32 v105, v105
	v_exp_f32_e32 v106, v106
	v_exp_f32_e32 v107, v107
	v_sub_f32_e32 v108, v108, v93
	v_sub_f32_e32 v109, v109, v93
	v_sub_f32_e32 v110, v110, v93
	v_sub_f32_e32 v111, v111, v93
	v_exp_f32_e32 v108, v108
	v_exp_f32_e32 v109, v109
	v_exp_f32_e32 v110, v110
	v_exp_f32_e32 v111, v111
	v_sub_f32_e32 v112, v112, v93
	v_sub_f32_e32 v113, v113, v93
	v_sub_f32_e32 v114, v114, v93
	v_sub_f32_e32 v115, v115, v93
	v_exp_f32_e32 v112, v112
	v_exp_f32_e32 v113, v113
	v_exp_f32_e32 v114, v114
	v_exp_f32_e32 v115, v115
	s_nop 0
	v_add_f32_e32 v90, v100, v101
	v_add_f32_e32 v91, v102, v103
	v_add_f32_e32 v92, v104, v105
	v_add_f32_e32 v93, v106, v107
	v_add_f32_e32 v90, v90, v108
	v_add_f32_e32 v91, v91, v109
	v_add_f32_e32 v92, v92, v110
	v_add_f32_e32 v93, v93, v111
	v_add_f32_e32 v90, v90, v112
	v_add_f32_e32 v91, v91, v113
	v_add_f32_e32 v92, v92, v114
	v_add_f32_e32 v93, v93, v115
	v_add_f32_e32 v90, v90, v91
	v_add_f32_e32 v92, v92, v93
	v_add_f32_e32 v90, v90, v92
	v_cvt_pk_bf16_f32 v82, v100, v101
	v_cvt_pk_bf16_f32 v83, v102, v103
	v_cvt_pk_bf16_f32 v84, v104, v105
	v_cvt_pk_bf16_f32 v85, v106, v107
	v_cvt_pk_bf16_f32 v86, v108, v109
	v_cvt_pk_bf16_f32 v87, v110, v111
	v_cvt_pk_bf16_f32 v88, v112, v113
	v_cvt_pk_bf16_f32 v89, v114, v115
	v_mov_b32_e32 v91, v90
	s_nop 1
	v_permlane16_swap_b32_e32 v90, v91
	v_add_f32_e32 v90, v90, v91
	v_mov_b32_e32 v91, v90
	s_nop 1
	v_permlane32_swap_b32_e32 v90, v91
	v_add_f32_e32 v90, v90, v91
	v_fma_f32 v159, v159, v94, v90
	v_cmp_neq_f32_e64 s[4:5], 1.0, v94
	s_cmp_eq_u64 s[4:5], 0
	s_cbranch_scc1 .Lwn_nosc_19
	v_pk_mul_f32 v[30:31], v[30:31], v[94:95] op_sel_hi:[1,0]
	v_pk_mul_f32 v[32:33], v[32:33], v[94:95] op_sel_hi:[1,0]
	v_pk_mul_f32 v[26:27], v[26:27], v[94:95] op_sel_hi:[1,0]
	v_pk_mul_f32 v[28:29], v[28:29], v[94:95] op_sel_hi:[1,0]
	v_pk_mul_f32 v[22:23], v[22:23], v[94:95] op_sel_hi:[1,0]
	v_pk_mul_f32 v[24:25], v[24:25], v[94:95] op_sel_hi:[1,0]
	v_pk_mul_f32 v[18:19], v[18:19], v[94:95] op_sel_hi:[1,0]
	v_pk_mul_f32 v[20:21], v[20:21], v[94:95] op_sel_hi:[1,0]

; template <int D, class SF>
; __device__ __forceinline__ void attn_step(const bf16x8 (&qf)[D / 32], const LAS bf16_t* Ks, const LAS bf16_t* Vt, f32x4 (&o)[D / 16], float& m, float& lsum, float& alpha_out, bf16x8& pf0_out, bf16x8& pf1_out, const int lane, SF sf) {
;     ...
; #pragma unroll
;     for (int t = 0; t < 4; ++t) s[t] = (f32x4){0.f, 0.f, 0.f, 0.f};
; #pragma unroll
;     for (int ks = 0; ks < D / 32; ++ks) {
; #pragma unroll
;         for (int t = 0; t < 4; ++t) { const bf16x8 kf = *(const LAS bf16x8*)(Ks + (16 * t + c) * KSTR + ks * 32 + 8 * i); s[t] = mfma16(kf, qf[ks], s[t]); }
;     }
;     float v[16];
; #pragma unroll
;     for (int t = 0; t < 4; ++t)
; #pragma unroll
;         for (int r = 0; r < 4; ++r) v[4 * t + r] = sf(16 * t + 4 * i + r, s[t][r]);
;     float mx = fmaxf(fmaxf(fmaxf(v[0], v[1]), fmaxf(v[2], v[3])), fmaxf(fmaxf(v[4], v[5]), fmaxf(v[6], v[7])));
;     mx = fmaxf(mx, fmaxf(fmaxf(fmaxf(v[8], v[9]), fmaxf(v[10], v[11])), fmaxf(fmaxf(v[12], v[13]), fmaxf(v[14], v[15]))));
;     mx = rows_max(mx);
;     const float mnew = fmaxf(m, mx);
;     const float mc = fmaxf(mnew, -1e20f);
;     const float alpha = __builtin_amdgcn_exp2f(fmaxf(m, -1e20f) - mc);
;     float p[16], rs = 0.f;
; #pragma unroll
;     for (int r = 0; r < 16; ++r) { p[r] = __builtin_amdgcn_exp2f(v[r] - mc); rs += p[r]; }
;     rs = rows_sum(rs);
;     lsum = lsum * alpha + rs; m = mnew;
;     union { u32x4 u; bf16x8 b; } pk0, pk1;
;     pk0.u.x = cvt_pk_bf16(p[0], p[1]); pk0.u.y = cvt_pk_bf16(p[2], p[3]); pk0.u.z = cvt_pk_bf16(p[4], p[5]); pk0.u.w = cvt_pk_bf16(p[6], p[7]);
;     pk1.u.x = cvt_pk_bf16(p[8], p[9]); pk1.u.y = cvt_pk_bf16(p[10], p[11]); pk1.u.z = cvt_pk_bf16(p[12], p[13]); pk1.u.w = cvt_pk_bf16(p[14], p[15]);
;     if (__builtin_amdgcn_ballot_w64(alpha != 1.0f) != 0ull) {
; #pragma unroll
;         for (int dt = 0; dt < D / 16; ++dt) o[dt] *= alpha;
;     }
; __device__ __forceinline__ void nsa_unit(LAS unsigned char* lds, const Ctx& P, int l, int b, int hkv, int tb) {
;     ...
;             for (int sl = 0; sl < 2; ++sl) if (sl == 0 || hasb) { const LAS bf16_t* Ks = KV + sl * 9216; const LAS bf16_t* Vt = Ks + 4608; const int kp0 = p0 + sl * 64;
; #pragma unroll
;                 for (int sb = 0; sb < 2; ++sb) { const int tqs = tq[sb];
;                     attn_step<64>(qf[sb], Ks, Vt, o[sb], m[sb], lsum[sb], alpha, pf, pf1, lane,
.Lwn_wc_17:
	s_cmp_gt_u32 s20, 3
	s_cbranch_scc1 .Lwn_wc_20
	s_add_i32 s21, s12, 192
	v_sub_u32_e32 v90, v130, v139
	v_subrev_u32_e32 v90, s21, v90
	v_lshl_add_u32 v91, v90, 2, v131
	v_add_u32_e32 v91, 0xffffff34, v91
	ds_read_b32 v170, v91 offset:204
	ds_read_b32 v171, v91 offset:200
	ds_read_b32 v172, v91 offset:196
	ds_read_b32 v173, v91 offset:192
	ds_read_b32 v174, v91 offset:140
	ds_read_b32 v175, v91 offset:136
	ds_read_b32 v176, v91 offset:132
	ds_read_b32 v177, v91 offset:128
	ds_read_b128 v[50:53], v116 offset:20480
	ds_read_b128 v[58:61], v116 offset:23040
	ds_read_b128 v[54:57], v116 offset:20544
	ds_read_b128 v[62:65], v116 offset:23104
	ds_read_b128 v[66:69], v116 offset:25600
	ds_read_b128 v[74:77], v116 offset:28160
	ds_read_b128 v[70:73], v116 offset:25664
	ds_read_b128 v[78:81], v116 offset:28224
	s_waitcnt lgkmcnt(6)
	v_mfma_f32_16x16x32_bf16 v[100:103], v[50:53], v[2:5], 0
	v_mfma_f32_16x16x32_bf16 v[104:107], v[58:61], v[2:5], 0
	s_waitcnt lgkmcnt(4)
	v_mfma_f32_16x16x32_bf16 v[100:103], v[54:57], v[6:9], v[100:103]
	v_mfma_f32_16x16x32_bf16 v[104:107], v[62:65], v[6:9], v[104:107]
	s_waitcnt lgkmcnt(2)
	v_mfma_f32_16x16x32_bf16 v[108:111], v[66:69], v[2:5], 0
	v_mfma_f32_16x16x32_bf16 v[112:115], v[74:77], v[2:5], 0
	s_waitcnt lgkmcnt(0)
	v_mfma_f32_16x16x32_bf16 v[108:111], v[70:73], v[6:9], v[108:111]
	v_mfma_f32_16x16x32_bf16 v[112:115], v[78:81], v[6:9], v[112:115]
	ds_read_b64_tr_b16 v[50:51], v117 offset:30720
	ds_read_b64_tr_b16 v[52:53], v117 offset:33280
	ds_read_b64_tr_b16 v[54:55], v117 offset:35840
	ds_read_b64_tr_b16 v[56:57], v117 offset:38400
	ds_read_b64_tr_b16 v[58:59], v117 offset:30752
	ds_read_b64_tr_b16 v[60:61], v117 offset:33312
	ds_read_b64_tr_b16 v[62:63], v117 offset:35872
	v_fmamk_f32 v100, v100, 0x3fb8aa3b, v170
	v_fmamk_f32 v101, v101, 0x3fb8aa3b, v171
	v_fmamk_f32 v102, v102, 0x3fb8aa3b, v172
	v_fmamk_f32 v103, v103, 0x3fb8aa3b, v173
	v_fmamk_f32 v104, v104, 0x3fb8aa3b, v174
	v_fmamk_f32 v105, v105, 0x3fb8aa3b, v175
	v_fmamk_f32 v106, v106, 0x3fb8aa3b, v176
	v_fmamk_f32 v107, v107, 0x3fb8aa3b, v177
	ds_read_b32 v170, v91 offset:76
	ds_read_b32 v171, v91 offset:72
	ds_read_b32 v172, v91 offset:68
	ds_read_b32 v173, v91 offset:64
	ds_read_b32 v174, v91 offset:12
	ds_read_b32 v175, v91 offset:8
	ds_read_b32 v176, v91 offset:4
	ds_read_b32 v177, v91 offset:0
	ds_read_b64_tr_b16 v[64:65], v117 offset:38432
	ds_read_b64_tr_b16 v[66:67], v117 offset:30784
	ds_read_b64_tr_b16 v[68:69], v117 offset:33344
	ds_read_b64_tr_b16 v[70:71], v117 offset:35904
	ds_read_b64_tr_b16 v[72:73], v117 offset:38464
	ds_read_b64_tr_b16 v[74:75], v117 offset:30816
	ds_read_b64_tr_b16 v[76:77], v117 offset:33376
	ds_read_b64_tr_b16 v[78:79], v117 offset:35936
	ds_read_b64_tr_b16 v[80:81], v117 offset:38496
	s_waitcnt lgkmcnt(9)
	v_fmamk_f32 v108, v108, 0x3fb8aa3b, v170
	v_fmamk_f32 v109, v109, 0x3fb8aa3b, v171
	v_fmamk_f32 v110, v110, 0x3fb8aa3b, v172
	v_fmamk_f32 v111, v111, 0x3fb8aa3b, v173
	v_fmamk_f32 v112, v112, 0x3fb8aa3b, v174
	v_fmamk_f32 v113, v113, 0x3fb8aa3b, v175
	v_fmamk_f32 v114, v114, 0x3fb8aa3b, v176
	v_fmamk_f32 v115, v115, 0x3fb8aa3b, v177
	v_max3_f32 v96, v100, v101, v102
	v_max3_f32 v91, v103, v104, v105
	v_max3_f32 v92, v106, v107, v108
	v_max3_f32 v93, v109, v110, v111
	v_max3_f32 v95, v112, v113, v114
	v_max3_f32 v96, v96, v91, v115
	v_max3_f32 v92, v92, v93, v95
	v_max_f32_e32 v96, v96, v92
	v_mov_b32_e32 v91, v96
	s_nop 1
	v_permlane16_swap_b32_e32 v96, v91
	v_max_f32_e32 v96, v96, v91
	v_mov_b32_e32 v91, v96
	s_nop 1
	v_permlane32_swap_b32_e32 v96, v91
	v_max_f32_e32 v96, v96, v91
	v_max_f32_e32 v92, v162, v96
	v_max_f32_e32 v94, 0xe0ad78ec, v162
	v_max_f32_e32 v93, 0xe0ad78ec, v92
	v_sub_f32_e32 v94, v94, v93
	v_mov_b32_e32 v162, v92
	v_exp_f32_e32 v94, v94
	v_sub_f32_e32 v100, v100, v93
	v_sub_f32_e32 v101, v101, v93
	v_sub_f32_e32 v102, v102, v93
	v_sub_f32_e32 v103, v103, v93
	v_exp_f32_e32 v100, v100
	v_exp_f32_e32 v101, v101
	v_exp_f32_e32 v102, v102
	v_exp_f32_e32 v103, v103
	v_sub_f32_e32 v104, v104, v93
	v_sub_f32_e32 v105, v105, v93
	v_sub_f32_e32 v106, v106, v93
	v_sub_f32_e32 v107, v107, v93
	v_exp_f32_e32 v104, v104
	v_exp_f32_e32 v105, v105
	v_exp_f32_e32 v106, v106
	v_exp_f32_e32 v107, v107
	v_sub_f32_e32 v108, v108, v93
	v_sub_f32_e32 v109, v109, v93
	v_sub_f32_e32 v110, v110, v93
	v_sub_f32_e32 v111, v111, v93
	v_exp_f32_e32 v108, v108
	v_exp_f32_e32 v109, v109
	v_exp_f32_e32 v110, v110
	v_exp_f32_e32 v111, v111
	v_sub_f32_e32 v112, v112, v93
	v_sub_f32_e32 v113, v113, v93
	v_sub_f32_e32 v114, v114, v93
	v_sub_f32_e32 v115, v115, v93
	v_exp_f32_e32 v112, v112
	v_exp_f32_e32 v113, v113
	v_exp_f32_e32 v114, v114
	v_exp_f32_e32 v115, v115
	s_nop 0
	v_add_f32_e32 v90, v100, v101
	v_add_f32_e32 v91, v102, v103
	v_add_f32_e32 v92, v104, v105
	v_add_f32_e32 v93, v106, v107
	v_add_f32_e32 v90, v90, v108
	v_add_f32_e32 v91, v91, v109
	v_add_f32_e32 v92, v92, v110
	v_add_f32_e32 v93, v93, v111
	v_add_f32_e32 v90, v90, v112
	v_add_f32_e32 v91, v91, v113
	v_add_f32_e32 v92, v92, v114
	v_add_f32_e32 v93, v93, v115
	v_add_f32_e32 v90, v90, v91
	v_add_f32_e32 v92, v92, v93
	v_add_f32_e32 v90, v90, v92
	v_cvt_pk_bf16_f32 v82, v100, v101
	v_cvt_pk_bf16_f32 v83, v102, v103
	v_cvt_pk_bf16_f32 v84, v104, v105
	v_cvt_pk_bf16_f32 v85, v106, v107
	v_cvt_pk_bf16_f32 v86, v108, v109
	v_cvt_pk_bf16_f32 v87, v110, v111
	v_cvt_pk_bf16_f32 v88, v112, v113
	v_cvt_pk_bf16_f32 v89, v114, v115
	v_mov_b32_e32 v91, v90
	s_nop 1
	v_permlane16_swap_b32_e32 v90, v91
	v_add_f32_e32 v90, v90, v91
	v_mov_b32_e32 v91, v90
	s_nop 1
	v_permlane32_swap_b32_e32 v90, v91
	v_add_f32_e32 v90, v90, v91
	v_fma_f32 v161, v161, v94, v90
	v_cmp_neq_f32_e64 s[4:5], 1.0, v94
	s_cmp_eq_u64 s[4:5], 0
	s_cbranch_scc1 .Lwn_nosc_21
	v_pk_mul_f32 v[46:47], v[46:47], v[94:95] op_sel_hi:[1,0]
	v_pk_mul_f32 v[48:49], v[48:49], v[94:95] op_sel_hi:[1,0]
	v_pk_mul_f32 v[42:43], v[42:43], v[94:95] op_sel_hi:[1,0]
	v_pk_mul_f32 v[44:45], v[44:45], v[94:95] op_sel_hi:[1,0]
	v_pk_mul_f32 v[38:39], v[38:39], v[94:95] op_sel_hi:[1,0]
	v_pk_mul_f32 v[40:41], v[40:41], v[94:95] op_sel_hi:[1,0]
	v_pk_mul_f32 v[34:35], v[34:35], v[94:95] op_sel_hi:[1,0]
	v_pk_mul_f32 v[36:37], v[36:37], v[94:95] op_sel_hi:[1,0]
; #define LAS __attribute__((address_space(3)))
; template <int D, class SF>
; __device__ __forceinline__ void attn_step(const bf16x8 (&qf)[D / 32], const LAS bf16_t* Ks, const LAS bf16_t* Vt, f32x4 (&o)[D / 16], float& m, float& lsum, float& alpha_out, bf16x8& pf0_out, bf16x8& pf1_out, const int lane, SF sf) {
;     ...
; #pragma unroll
;     for (int t = 0; t < 4; ++t) s[t] = (f32x4){0.f, 0.f, 0.f, 0.f};
; #pragma unroll
;     for (int ks = 0; ks < D / 32; ++ks) {
; #pragma unroll
;         for (int t = 0; t < 4; ++t) { const bf16x8 kf = *(const LAS bf16x8*)(Ks + (16 * t + c) * KSTR + ks * 32 + 8 * i); s[t] = mfma16(kf, qf[ks], s[t]); }
;     }
;     float v[16];
; #pragma unroll
;     for (int t = 0; t < 4; ++t)
; #pragma unroll
;         for (int r = 0; r < 4; ++r) v[4 * t + r] = sf(16 * t + 4 * i + r, s[t][r]);
;     float mx = fmaxf(fmaxf(fmaxf(v[0], v[1]), fmaxf(v[2], v[3])), fmaxf(fmaxf(v[4], v[5]), fmaxf(v[6], v[7])));
;     mx = fmaxf(mx, fmaxf(fmaxf(fmaxf(v[8], v[9]), fmaxf(v[10], v[11])), fmaxf(fmaxf(v[12], v[13]), fmaxf(v[14], v[15]))));
;     mx = rows_max(mx);
;     const float mnew = fmaxf(m, mx);
;     const float mc = fmaxf(mnew, -1e20f);
;     const float alpha = __builtin_amdgcn_exp2f(fmaxf(m, -1e20f) - mc);
;     float p[16], rs = 0.f;
; #pragma unroll
;     for (int r = 0; r < 16; ++r) { p[r] = __builtin_amdgcn_exp2f(v[r] - mc); rs += p[r]; }
;     rs = rows_sum(rs);
;     lsum = lsum * alpha + rs; m = mnew;
;     union { u32x4 u; bf16x8 b; } pk0, pk1;
;     pk0.u.x = cvt_pk_bf16(p[0], p[1]); pk0.u.y = cvt_pk_bf16(p[2], p[3]); pk0.u.z = cvt_pk_bf16(p[4], p[5]); pk0.u.w = cvt_pk_bf16(p[6], p[7]);
;     pk1.u.x = cvt_pk_bf16(p[8], p[9]); pk1.u.y = cvt_pk_bf16(p[10], p[11]); pk1.u.z = cvt_pk_bf16(p[12], p[13]); pk1.u.w = cvt_pk_bf16(p[14], p[15]);
;     if (__builtin_amdgcn_ballot_w64(alpha != 1.0f) != 0ull) {
; #pragma unroll
;         for (int dt = 0; dt < D / 16; ++dt) o[dt] *= alpha;
;     }
; #pragma unroll
;     for (int dt = 0; dt < D / 16; ++dt) {
;         const LAS bf16_t* vp = Vt + (16 * dt + c) * 72 + 4 * i;
;         union { u32x4 u; bf16x8 b; } vf0, vf1; const u32x2 a0 = *(const LAS u32x2*)vp, a1 = *(const LAS u32x2*)(vp + 16), b0 = *(const LAS u32x2*)(vp + 32), b1 = *(const LAS u32x2*)(vp + 48);
;         vf0.u.x = a0.x; vf0.u.y = a0.y; vf0.u.z = a1.x; vf0.u.w = a1.y; vf1.u.x = b0.x; vf1.u.y = b0.y; vf1.u.z = b1.x; vf1.u.w = b1.y;
.Lwn_nosc_21:
	s_waitcnt lgkmcnt(0)
	s_nop 1
	v_mfma_f32_16x16x32_bf16 v[46:49], v[50:53], v[82:85], v[46:49]
	v_mfma_f32_16x16x32_bf16 v[42:45], v[58:61], v[82:85], v[42:45]
	v_mfma_f32_16x16x32_bf16 v[38:41], v[66:69], v[82:85], v[38:41]
	v_mfma_f32_16x16x32_bf16 v[34:37], v[74:77], v[82:85], v[34:37]
	v_mfma_f32_16x16x32_bf16 v[46:49], v[54:57], v[86:89], v[46:49]
	v_mfma_f32_16x16x32_bf16 v[42:45], v[62:65], v[86:89], v[42:45]
	v_mfma_f32_16x16x32_bf16 v[38:41], v[70:73], v[86:89], v[38:41]
	v_mfma_f32_16x16x32_bf16 v[34:37], v[78:81], v[86:89], v[34:37]
	v_sub_u32_e32 v90, v180, v139
	v_subrev_u32_e32 v90, s21, v90
	v_lshl_add_u32 v91, v90, 2, v131
	v_add_u32_e32 v91, 0xffffff34, v91
	ds_read_b32 v170, v91 offset:204
	ds_read_b32 v171, v91 offset:200
	ds_read_b32 v172, v91 offset:196
	ds_read_b32 v173, v91 offset:192
	ds_read_b32 v174, v91 offset:140
	ds_read_b32 v175, v91 offset:136
	ds_read_b32 v176, v91 offset:132
	ds_read_b32 v177, v91 offset:128
	ds_read_b128 v[50:53], v116 offset:20480
	ds_read_b128 v[58:61], v116 offset:23040
	ds_read_b128 v[54:57], v116 offset:20544
	ds_read_b128 v[62:65], v116 offset:23104
	ds_read_b128 v[66:69], v116 offset:25600
	ds_read_b128 v[74:77], v116 offset:28160
	ds_read_b128 v[70:73], v116 offset:25664
	ds_read_b128 v[78:81], v116 offset:28224
	s_waitcnt lgkmcnt(6)
	v_mfma_f32_16x16x32_bf16 v[100:103], v[50:53], v[10:13], 0
	v_mfma_f32_16x16x32_bf16 v[104:107], v[58:61], v[10:13], 0
	s_waitcnt lgkmcnt(4)
	v_mfma_f32_16x16x32_bf16 v[100:103], v[54:57], v[14:17], v[100:103]
	v_mfma_f32_16x16x32_bf16 v[104:107], v[62:65], v[14:17], v[104:107]
	s_waitcnt lgkmcnt(2)
	v_mfma_f32_16x16x32_bf16 v[108:111], v[66:69], v[10:13], 0
	v_mfma_f32_16x16x32_bf16 v[112:115], v[74:77], v[10:13], 0
	s_waitcnt lgkmcnt(0)
	v_mfma_f32_16x16x32_bf16 v[108:111], v[70:73], v[14:17], v[108:111]
	v_mfma_f32_16x16x32_bf16 v[112:115], v[78:81], v[14:17], v[112:115]
	ds_read_b64_tr_b16 v[50:51], v117 offset:30720
	ds_read_b64_tr_b16 v[52:53], v117 offset:33280
	ds_read_b64_tr_b16 v[54:55], v117 offset:35840
	ds_read_b64_tr_b16 v[56:57], v117 offset:38400
	ds_read_b64_tr_b16 v[58:59], v117 offset:30752
	ds_read_b64_tr_b16 v[60:61], v117 offset:33312
	ds_read_b64_tr_b16 v[62:63], v117 offset:35872
	v_fmamk_f32 v100, v100, 0x3fb8aa3b, v170
	v_fmamk_f32 v101, v101, 0x3fb8aa3b, v171
	v_fmamk_f32 v102, v102, 0x3fb8aa3b, v172
	v_fmamk_f32 v103, v103, 0x3fb8aa3b, v173
	v_fmamk_f32 v104, v104, 0x3fb8aa3b, v174
	v_fmamk_f32 v105, v105, 0x3fb8aa3b, v175
	v_fmamk_f32 v106, v106, 0x3fb8aa3b, v176
	v_fmamk_f32 v107, v107, 0x3fb8aa3b, v177
	ds_read_b32 v170, v91 offset:76
	ds_read_b32 v171, v91 offset:72
	ds_read_b32 v172, v91 offset:68
	ds_read_b32 v173, v91 offset:64
	ds_read_b32 v174, v91 offset:12
	ds_read_b32 v175, v91 offset:8
	ds_read_b32 v176, v91 offset:4
	ds_read_b32 v177, v91 offset:0
	ds_read_b64_tr_b16 v[64:65], v117 offset:38432
	ds_read_b64_tr_b16 v[66:67], v117 offset:30784
	ds_read_b64_tr_b16 v[68:69], v117 offset:33344
	ds_read_b64_tr_b16 v[70:71], v117 offset:35904
	ds_read_b64_tr_b16 v[72:73], v117 offset:38464
	ds_read_b64_tr_b16 v[74:75], v117 offset:30816
	ds_read_b64_tr_b16 v[76:77], v117 offset:33376
	ds_read_b64_tr_b16 v[78:79], v117 offset:35936
	ds_read_b64_tr_b16 v[80:81], v117 offset:38496
	s_waitcnt lgkmcnt(9)
	v_fmamk_f32 v108, v108, 0x3fb8aa3b, v170
	v_fmamk_f32 v109, v109, 0x3fb8aa3b, v171
	v_fmamk_f32 v110, v110, 0x3fb8aa3b, v172
	v_fmamk_f32 v111, v111, 0x3fb8aa3b, v173
	v_fmamk_f32 v112, v112, 0x3fb8aa3b, v174
	v_fmamk_f32 v113, v113, 0x3fb8aa3b, v175
	v_fmamk_f32 v114, v114, 0x3fb8aa3b, v176
	v_fmamk_f32 v115, v115, 0x3fb8aa3b, v177
	v_max3_f32 v96, v100, v101, v102
	v_max3_f32 v91, v103, v104, v105
	v_max3_f32 v92, v106, v107, v108
	v_max3_f32 v93, v109, v110, v111
	v_max3_f32 v95, v112, v113, v114
	v_max3_f32 v96, v96, v91, v115
	v_max3_f32 v92, v92, v93, v95
	v_max_f32_e32 v96, v96, v92
	v_mov_b32_e32 v91, v96
	s_nop 1
	v_permlane16_swap_b32_e32 v96, v91
	v_max_f32_e32 v96, v96, v91
	v_mov_b32_e32 v91, v96
	s_nop 1
	v_permlane32_swap_b32_e32 v96, v91
	v_max_f32_e32 v96, v96, v91
	v_max_f32_e32 v92, v160, v96
	v_max_f32_e32 v94, 0xe0ad78ec, v160
	v_max_f32_e32 v93, 0xe0ad78ec, v92
	v_sub_f32_e32 v94, v94, v93
	v_mov_b32_e32 v160, v92
	v_exp_f32_e32 v94, v94
	v_sub_f32_e32 v100, v100, v93
	v_sub_f32_e32 v101, v101, v93
	v_sub_f32_e32 v102, v102, v93
	v_sub_f32_e32 v103, v103, v93
	v_exp_f32_e32 v100, v100
	v_exp_f32_e32 v101, v101
	v_exp_f32_e32 v102, v102
	v_exp_f32_e32 v103, v103
	v_sub_f32_e32 v104, v104, v93
	v_sub_f32_e32 v105, v105, v93
	v_sub_f32_e32 v106, v106, v93
	v_sub_f32_e32 v107, v107, v93
	v_exp_f32_e32 v104, v104
	v_exp_f32_e32 v105, v105
	v_exp_f32_e32 v106, v106
	v_exp_f32_e32 v107, v107
	v_sub_f32_e32 v108, v108, v93
	v_sub_f32_e32 v109, v109, v93
	v_sub_f32_e32 v110, v110, v93
	v_sub_f32_e32 v111, v111, v93
	v_exp_f32_e32 v108, v108
	v_exp_f32_e32 v109, v109
	v_exp_f32_e32 v110, v110
	v_exp_f32_e32 v111, v111
	v_sub_f32_e32 v112, v112, v93
	v_sub_f32_e32 v113, v113, v93
	v_sub_f32_e32 v114, v114, v93
	v_sub_f32_e32 v115, v115, v93
	v_exp_f32_e32 v112, v112
	v_exp_f32_e32 v113, v113
	v_exp_f32_e32 v114, v114
	v_exp_f32_e32 v115, v115
	s_nop 0
	v_add_f32_e32 v90, v100, v101
	v_add_f32_e32 v91, v102, v103
	v_add_f32_e32 v92, v104, v105
	v_add_f32_e32 v93, v106, v107
	v_add_f32_e32 v90, v90, v108
	v_add_f32_e32 v91, v91, v109
	v_add_f32_e32 v92, v92, v110
	v_add_f32_e32 v93, v93, v111
	v_add_f32_e32 v90, v90, v112
	v_add_f32_e32 v91, v91, v113
	v_add_f32_e32 v92, v92, v114
	v_add_f32_e32 v93, v93, v115
	v_add_f32_e32 v90, v90, v91
	v_add_f32_e32 v92, v92, v93
	v_add_f32_e32 v90, v90, v92
	v_cvt_pk_bf16_f32 v82, v100, v101
	v_cvt_pk_bf16_f32 v83, v102, v103
	v_cvt_pk_bf16_f32 v84, v104, v105
	v_cvt_pk_bf16_f32 v85, v106, v107
	v_cvt_pk_bf16_f32 v86, v108, v109
	v_cvt_pk_bf16_f32 v87, v110, v111
	v_cvt_pk_bf16_f32 v88, v112, v113
	v_cvt_pk_bf16_f32 v89, v114, v115
	v_mov_b32_e32 v91, v90
	s_nop 1
	v_permlane16_swap_b32_e32 v90, v91
	v_add_f32_e32 v90, v90, v91
	v_mov_b32_e32 v91, v90
	s_nop 1
	v_permlane32_swap_b32_e32 v90, v91
	v_add_f32_e32 v90, v90, v91
	v_fma_f32 v159, v159, v94, v90
	v_cmp_neq_f32_e64 s[4:5], 1.0, v94
	s_cmp_eq_u64 s[4:5], 0
	s_cbranch_scc1 .Lwn_nosc_22
	v_pk_mul_f32 v[30:31], v[30:31], v[94:95] op_sel_hi:[1,0]
	v_pk_mul_f32 v[32:33], v[32:33], v[94:95] op_sel_hi:[1,0]
	v_pk_mul_f32 v[26:27], v[26:27], v[94:95] op_sel_hi:[1,0]
	v_pk_mul_f32 v[28:29], v[28:29], v[94:95] op_sel_hi:[1,0]
	v_pk_mul_f32 v[22:23], v[22:23], v[94:95] op_sel_hi:[1,0]
	v_pk_mul_f32 v[24:25], v[24:25], v[94:95] op_sel_hi:[1,0]
	v_pk_mul_f32 v[18:19], v[18:19], v[94:95] op_sel_hi:[1,0]
	v_pk_mul_f32 v[20:21], v[20:21], v[94:95] op_sel_hi:[1,0]

; #define LAS __attribute__((address_space(3)))
; __device__ __forceinline__ f32x4 mfma16(bf16x8 a, bf16x8 b, f32x4 c) { return __builtin_amdgcn_mfma_f32_16x16x32_bf16(a, b, c, 0, 0, 0); }
; template <int D, class SF>
; __device__ __forceinline__ void attn_step(const bf16x8 (&qf)[D / 32], const LAS bf16_t* Ks, const LAS bf16_t* Vt, f32x4 (&o)[D / 16], float& m, float& lsum, float& alpha_out, bf16x8& pf0_out, bf16x8& pf1_out, const int lane, SF sf) {
;     ...
; #pragma unroll
;     for (int t = 0; t < 4; ++t) s[t] = (f32x4){0.f, 0.f, 0.f, 0.f};
; #pragma unroll
;     for (int ks = 0; ks < D / 32; ++ks) {
; #pragma unroll
;         for (int t = 0; t < 4; ++t) { const bf16x8 kf = *(const LAS bf16x8*)(Ks + (16 * t + c) * KSTR + ks * 32 + 8 * i); s[t] = mfma16(kf, qf[ks], s[t]); }
;     }
;     float v[16];
; #pragma unroll
;     for (int t = 0; t < 4; ++t)
; #pragma unroll
;         for (int r = 0; r < 4; ++r) v[4 * t + r] = sf(16 * t + 4 * i + r, s[t][r]);
;     float mx = fmaxf(fmaxf(fmaxf(v[0], v[1]), fmaxf(v[2], v[3])), fmaxf(fmaxf(v[4], v[5]), fmaxf(v[6], v[7])));
;     mx = fmaxf(mx, fmaxf(fmaxf(fmaxf(v[8], v[9]), fmaxf(v[10], v[11])), fmaxf(fmaxf(v[12], v[13]), fmaxf(v[14], v[15]))));
;     mx = rows_max(mx);
;     const float mnew = fmaxf(m, mx);
;     const float mc = fmaxf(mnew, -1e20f);
;     const float alpha = __builtin_amdgcn_exp2f(fmaxf(m, -1e20f) - mc);
; __device__ __forceinline__ void nsa_unit(LAS unsigned char* lds, const Ctx& P, int l, int b, int hkv, int tb) {
;     ...
;                 for (int sb = 0; sb < 2; ++sb) { const int tqs = tq[sb];
;                     attn_step<64>(qf[sb], Ks, Vt, o[sb], m[sb], lsum[sb], alpha, pf, pf1, lane,
;                         [&](int kk, float s) { const int kpos = kp0 + kk, dist = tqs - kpos; return (dist >= 0 && dist < 256 && kpos >= 0) ? s * LOG2E + lut[min((unsigned)dist, 1023u)] : NEGBIG; }); }
.Lwn_wc_20:
	s_cmp_gt_u32 s20, 4
	s_cbranch_scc1 .Lwn_wc_23
	s_add_i32 s21, s12, 256
	v_sub_u32_e32 v90, v130, v139
	v_subrev_u32_e32 v90, s21, v90
	v_subrev_u32_e32 v170, 0, v90
	v_min_u32_e32 v170, 0x3ff, v170
	v_lshl_add_u32 v170, v170, 2, v131
	ds_read_b32 v170, v170
	v_subrev_u32_e32 v171, 1, v90
	v_min_u32_e32 v171, 0x3ff, v171
	v_lshl_add_u32 v171, v171, 2, v131
	ds_read_b32 v171, v171
	v_subrev_u32_e32 v172, 2, v90
	v_min_u32_e32 v172, 0x3ff, v172
	v_lshl_add_u32 v172, v172, 2, v131
	ds_read_b32 v172, v172
	v_subrev_u32_e32 v173, 3, v90
	v_min_u32_e32 v173, 0x3ff, v173
	v_lshl_add_u32 v173, v173, 2, v131
	ds_read_b32 v173, v173
	v_subrev_u32_e32 v174, 16, v90
	v_min_u32_e32 v174, 0x3ff, v174
	v_lshl_add_u32 v174, v174, 2, v131
	ds_read_b32 v174, v174
	v_subrev_u32_e32 v175, 17, v90
	v_min_u32_e32 v175, 0x3ff, v175
	v_lshl_add_u32 v175, v175, 2, v131
	ds_read_b32 v175, v175
	v_subrev_u32_e32 v176, 18, v90
	v_min_u32_e32 v176, 0x3ff, v176
	v_lshl_add_u32 v176, v176, 2, v131
	ds_read_b32 v176, v176
	v_subrev_u32_e32 v177, 19, v90
	v_min_u32_e32 v177, 0x3ff, v177
	v_lshl_add_u32 v177, v177, 2, v131
	ds_read_b32 v177, v177
	ds_read_b128 v[50:53], v116 offset:40960
	ds_read_b128 v[58:61], v116 offset:43520
	ds_read_b128 v[54:57], v116 offset:41024
	ds_read_b128 v[62:65], v116 offset:43584
	ds_read_b128 v[66:69], v116 offset:46080
	ds_read_b128 v[74:77], v116 offset:48640
	ds_read_b128 v[70:73], v116 offset:46144
	ds_read_b128 v[78:81], v116 offset:48704
	s_waitcnt lgkmcnt(6)
	v_mfma_f32_16x16x32_bf16 v[100:103], v[50:53], v[2:5], 0
	v_mfma_f32_16x16x32_bf16 v[104:107], v[58:61], v[2:5], 0
	s_waitcnt lgkmcnt(4)
	v_mfma_f32_16x16x32_bf16 v[100:103], v[54:57], v[6:9], v[100:103]
	v_mfma_f32_16x16x32_bf16 v[104:107], v[62:65], v[6:9], v[104:107]
	s_waitcnt lgkmcnt(2)
	v_mfma_f32_16x16x32_bf16 v[108:111], v[66:69], v[2:5], 0
	v_mfma_f32_16x16x32_bf16 v[112:115], v[74:77], v[2:5], 0
	s_waitcnt lgkmcnt(0)
	v_mfma_f32_16x16x32_bf16 v[108:111], v[70:73], v[6:9], v[108:111]
	v_mfma_f32_16x16x32_bf16 v[112:115], v[78:81], v[6:9], v[112:115]
	ds_read_b64_tr_b16 v[50:51], v117 offset:51200
	ds_read_b64_tr_b16 v[52:53], v117 offset:53760
	ds_read_b64_tr_b16 v[54:55], v117 offset:56320
	ds_read_b64_tr_b16 v[56:57], v117 offset:58880
	ds_read_b64_tr_b16 v[58:59], v117 offset:51232
	ds_read_b64_tr_b16 v[60:61], v117 offset:53792
	ds_read_b64_tr_b16 v[62:63], v117 offset:56352
	v_fmamk_f32 v100, v100, 0x3fb8aa3b, v170
	v_fmamk_f32 v101, v101, 0x3fb8aa3b, v171
	v_fmamk_f32 v102, v102, 0x3fb8aa3b, v172
	v_fmamk_f32 v103, v103, 0x3fb8aa3b, v173
	v_fmamk_f32 v104, v104, 0x3fb8aa3b, v174
	v_fmamk_f32 v105, v105, 0x3fb8aa3b, v175
	v_fmamk_f32 v106, v106, 0x3fb8aa3b, v176
	v_fmamk_f32 v107, v107, 0x3fb8aa3b, v177
	v_cmp_le_i32_e32 vcc, 0, v90
	s_nop 1
	v_cndmask_b32_e32 v100, v243, v100, vcc
	v_cmp_le_i32_e32 vcc, 1, v90
	s_nop 1
	v_cndmask_b32_e32 v101, v243, v101, vcc
	v_cmp_le_i32_e32 vcc, 2, v90
	s_nop 1
	v_cndmask_b32_e32 v102, v243, v102, vcc
	v_cmp_le_i32_e32 vcc, 3, v90
	s_nop 1
	v_cndmask_b32_e32 v103, v243, v103, vcc
	v_cmp_le_i32_e32 vcc, 16, v90
	s_nop 1
	v_cndmask_b32_e32 v104, v243, v104, vcc
	v_cmp_le_i32_e32 vcc, 17, v90
	s_nop 1
	v_cndmask_b32_e32 v105, v243, v105, vcc
	v_cmp_le_i32_e32 vcc, 18, v90
	s_nop 1
	v_cndmask_b32_e32 v106, v243, v106, vcc
	v_cmp_le_i32_e32 vcc, 19, v90
	s_nop 1
	v_cndmask_b32_e32 v107, v243, v107, vcc
	v_subrev_u32_e32 v170, 32, v90
	v_min_u32_e32 v170, 0x3ff, v170
	v_lshl_add_u32 v170, v170, 2, v131
	ds_read_b32 v170, v170
	v_subrev_u32_e32 v171, 33, v90
	v_min_u32_e32 v171, 0x3ff, v171
	v_lshl_add_u32 v171, v171, 2, v131
	ds_read_b32 v171, v171
	v_subrev_u32_e32 v172, 34, v90
	v_min_u32_e32 v172, 0x3ff, v172
	v_lshl_add_u32 v172, v172, 2, v131
	ds_read_b32 v172, v172
	v_subrev_u32_e32 v173, 35, v90
	v_min_u32_e32 v173, 0x3ff, v173
	v_lshl_add_u32 v173, v173, 2, v131
	ds_read_b32 v173, v173
	v_subrev_u32_e32 v174, 48, v90
	v_min_u32_e32 v174, 0x3ff, v174
	v_lshl_add_u32 v174, v174, 2, v131
	ds_read_b32 v174, v174
	v_subrev_u32_e32 v175, 49, v90
	v_min_u32_e32 v175, 0x3ff, v175
	v_lshl_add_u32 v175, v175, 2, v131
	ds_read_b32 v175, v175
	v_subrev_u32_e32 v176, 50, v90
	v_min_u32_e32 v176, 0x3ff, v176
	v_lshl_add_u32 v176, v176, 2, v131
	ds_read_b32 v176, v176
	v_subrev_u32_e32 v177, 51, v90
	v_min_u32_e32 v177, 0x3ff, v177
	v_lshl_add_u32 v177, v177, 2, v131
	ds_read_b32 v177, v177
	ds_read_b64_tr_b16 v[64:65], v117 offset:58912
	ds_read_b64_tr_b16 v[66:67], v117 offset:51264
	ds_read_b64_tr_b16 v[68:69], v117 offset:53824
	ds_read_b64_tr_b16 v[70:71], v117 offset:56384
	ds_read_b64_tr_b16 v[72:73], v117 offset:58944
	ds_read_b64_tr_b16 v[74:75], v117 offset:51296
	ds_read_b64_tr_b16 v[76:77], v117 offset:53856
	ds_read_b64_tr_b16 v[78:79], v117 offset:56416
	ds_read_b64_tr_b16 v[80:81], v117 offset:58976
	s_waitcnt lgkmcnt(9)
; template <int D, class SF>
; __device__ __forceinline__ void attn_step(const bf16x8 (&qf)[D / 32], const LAS bf16_t* Ks, const LAS bf16_t* Vt, f32x4 (&o)[D / 16], float& m, float& lsum, float& alpha_out, bf16x8& pf0_out, bf16x8& pf1_out, const int lane, SF sf) {
;     ...
; #pragma unroll
;     for (int t = 0; t < 4; ++t) s[t] = (f32x4){0.f, 0.f, 0.f, 0.f};
; #pragma unroll
;     for (int ks = 0; ks < D / 32; ++ks) {
; #pragma unroll
;         for (int t = 0; t < 4; ++t) { const bf16x8 kf = *(const LAS bf16x8*)(Ks + (16 * t + c) * KSTR + ks * 32 + 8 * i); s[t] = mfma16(kf, qf[ks], s[t]); }
;     }
;     ...
;     for (int t = 0; t < 4; ++t)
; #pragma unroll
;         for (int r = 0; r < 4; ++r) v[4 * t + r] = sf(16 * t + 4 * i + r, s[t][r]);
;     float mx = fmaxf(fmaxf(fmaxf(v[0], v[1]), fmaxf(v[2], v[3])), fmaxf(fmaxf(v[4], v[5]), fmaxf(v[6], v[7])));
;     mx = fmaxf(mx, fmaxf(fmaxf(fmaxf(v[8], v[9]), fmaxf(v[10], v[11])), fmaxf(fmaxf(v[12], v[13]), fmaxf(v[14], v[15]))));
;     mx = rows_max(mx);
;     const float mnew = fmaxf(m, mx);
;     const float mc = fmaxf(mnew, -1e20f);
;     const float alpha = __builtin_amdgcn_exp2f(fmaxf(m, -1e20f) - mc);
;     float p[16], rs = 0.f;
; #pragma unroll
;     for (int r = 0; r < 16; ++r) { p[r] = __builtin_amdgcn_exp2f(v[r] - mc); rs += p[r]; }
;     rs = rows_sum(rs);
;     lsum = lsum * alpha + rs; m = mnew;
;     union { u32x4 u; bf16x8 b; } pk0, pk1;
;     pk0.u.x = cvt_pk_bf16(p[0], p[1]); pk0.u.y = cvt_pk_bf16(p[2], p[3]); pk0.u.z = cvt_pk_bf16(p[4], p[5]); pk0.u.w = cvt_pk_bf16(p[6], p[7]);
;     pk1.u.x = cvt_pk_bf16(p[8], p[9]); pk1.u.y = cvt_pk_bf16(p[10], p[11]); pk1.u.z = cvt_pk_bf16(p[12], p[13]); pk1.u.w = cvt_pk_bf16(p[14], p[15]);
;     if (__builtin_amdgcn_ballot_w64(alpha != 1.0f) != 0ull) {
; #pragma unroll
;         for (int dt = 0; dt < D / 16; ++dt) o[dt] *= alpha;
;     }
; #pragma unroll
;     for (int dt = 0; dt < D / 16; ++dt) {
;         const LAS bf16_t* vp = Vt + (16 * dt + c) * 72 + 4 * i;
;         union { u32x4 u; bf16x8 b; } vf0, vf1; const u32x2 a0 = *(const LAS u32x2*)vp, a1 = *(const LAS u32x2*)(vp + 16), b0 = *(const LAS u32x2*)(vp + 32), b1 = *(const LAS u32x2*)(vp + 48);
;         vf0.u.x = a0.x; vf0.u.y = a0.y; vf0.u.z = a1.x; vf0.u.w = a1.y; vf1.u.x = b0.x; vf1.u.y = b0.y; vf1.u.z = b1.x; vf1.u.w = b1.y;
;         o[dt] = mfma16(vf0.b, pk0.b, o[dt]); o[dt] = mfma16(vf1.b, pk1.b, o[dt]);
	v_fmamk_f32 v108, v108, 0x3fb8aa3b, v170
	v_fmamk_f32 v109, v109, 0x3fb8aa3b, v171
	v_fmamk_f32 v110, v110, 0x3fb8aa3b, v172
	v_fmamk_f32 v111, v111, 0x3fb8aa3b, v173
	v_fmamk_f32 v112, v112, 0x3fb8aa3b, v174
	v_fmamk_f32 v113, v113, 0x3fb8aa3b, v175
	v_fmamk_f32 v114, v114, 0x3fb8aa3b, v176
	v_fmamk_f32 v115, v115, 0x3fb8aa3b, v177
	v_cmp_le_i32_e32 vcc, 32, v90
	s_nop 1
	v_cndmask_b32_e32 v108, v243, v108, vcc
	v_cmp_le_i32_e32 vcc, 33, v90
	s_nop 1
	v_cndmask_b32_e32 v109, v243, v109, vcc
	v_cmp_le_i32_e32 vcc, 34, v90
	s_nop 1
	v_cndmask_b32_e32 v110, v243, v110, vcc
	v_cmp_le_i32_e32 vcc, 35, v90
	s_nop 1
	v_cndmask_b32_e32 v111, v243, v111, vcc
	v_cmp_le_i32_e32 vcc, 48, v90
	s_nop 1
	v_cndmask_b32_e32 v112, v243, v112, vcc
	v_cmp_le_i32_e32 vcc, 49, v90
	s_nop 1
	v_cndmask_b32_e32 v113, v243, v113, vcc
	v_cmp_le_i32_e32 vcc, 50, v90
	s_nop 1
	v_cndmask_b32_e32 v114, v243, v114, vcc
	v_cmp_le_i32_e32 vcc, 51, v90
	s_nop 1
	v_cndmask_b32_e32 v115, v243, v115, vcc
	v_max3_f32 v96, v100, v101, v102
	v_max3_f32 v91, v103, v104, v105
	v_max3_f32 v92, v106, v107, v108
	v_max3_f32 v93, v109, v110, v111
	v_max3_f32 v95, v112, v113, v114
	v_max3_f32 v96, v96, v91, v115
	v_max3_f32 v92, v92, v93, v95
	v_max_f32_e32 v96, v96, v92
	v_mov_b32_e32 v91, v96
	s_nop 1
	v_permlane16_swap_b32_e32 v96, v91
	v_max_f32_e32 v96, v96, v91
	v_mov_b32_e32 v91, v96
	s_nop 1
	v_permlane32_swap_b32_e32 v96, v91
	v_max_f32_e32 v96, v96, v91
	v_max_f32_e32 v92, v162, v96
	v_max_f32_e32 v94, 0xe0ad78ec, v162
	v_max_f32_e32 v93, 0xe0ad78ec, v92
	v_sub_f32_e32 v94, v94, v93
	v_mov_b32_e32 v162, v92
	v_exp_f32_e32 v94, v94
	v_sub_f32_e32 v100, v100, v93
	v_sub_f32_e32 v101, v101, v93
	v_sub_f32_e32 v102, v102, v93
	v_sub_f32_e32 v103, v103, v93
	v_exp_f32_e32 v100, v100
	v_exp_f32_e32 v101, v101
	v_exp_f32_e32 v102, v102
	v_exp_f32_e32 v103, v103
	v_sub_f32_e32 v104, v104, v93
	v_sub_f32_e32 v105, v105, v93
	v_sub_f32_e32 v106, v106, v93
	v_sub_f32_e32 v107, v107, v93
	v_exp_f32_e32 v104, v104
	v_exp_f32_e32 v105, v105
	v_exp_f32_e32 v106, v106
	v_exp_f32_e32 v107, v107
	v_sub_f32_e32 v108, v108, v93
	v_sub_f32_e32 v109, v109, v93
	v_sub_f32_e32 v110, v110, v93
	v_sub_f32_e32 v111, v111, v93
	v_exp_f32_e32 v108, v108
	v_exp_f32_e32 v109, v109
	v_exp_f32_e32 v110, v110
	v_exp_f32_e32 v111, v111
	v_sub_f32_e32 v112, v112, v93
	v_sub_f32_e32 v113, v113, v93
	v_sub_f32_e32 v114, v114, v93
	v_sub_f32_e32 v115, v115, v93
	v_exp_f32_e32 v112, v112
	v_exp_f32_e32 v113, v113
	v_exp_f32_e32 v114, v114
	v_exp_f32_e32 v115, v115
	s_nop 0
	v_add_f32_e32 v90, v100, v101
	v_add_f32_e32 v91, v102, v103
	v_add_f32_e32 v92, v104, v105
	v_add_f32_e32 v93, v106, v107
	v_add_f32_e32 v90, v90, v108
	v_add_f32_e32 v91, v91, v109
	v_add_f32_e32 v92, v92, v110
	v_add_f32_e32 v93, v93, v111
	v_add_f32_e32 v90, v90, v112
	v_add_f32_e32 v91, v91, v113
	v_add_f32_e32 v92, v92, v114
	v_add_f32_e32 v93, v93, v115
	v_add_f32_e32 v90, v90, v91
	v_add_f32_e32 v92, v92, v93
	v_add_f32_e32 v90, v90, v92
	v_cvt_pk_bf16_f32 v82, v100, v101
	v_cvt_pk_bf16_f32 v83, v102, v103
	v_cvt_pk_bf16_f32 v84, v104, v105
	v_cvt_pk_bf16_f32 v85, v106, v107
	v_cvt_pk_bf16_f32 v86, v108, v109
	v_cvt_pk_bf16_f32 v87, v110, v111
	v_cvt_pk_bf16_f32 v88, v112, v113
	v_cvt_pk_bf16_f32 v89, v114, v115
	v_mov_b32_e32 v91, v90
	s_nop 1
	v_permlane16_swap_b32_e32 v90, v91
	v_add_f32_e32 v90, v90, v91
	v_mov_b32_e32 v91, v90
	s_nop 1
	v_permlane32_swap_b32_e32 v90, v91
	v_add_f32_e32 v90, v90, v91
	v_fma_f32 v161, v161, v94, v90
	v_cmp_neq_f32_e64 s[4:5], 1.0, v94
	s_cmp_eq_u64 s[4:5], 0
	s_cbranch_scc1 .Lwn_nosc_24
	v_pk_mul_f32 v[46:47], v[46:47], v[94:95] op_sel_hi:[1,0]
	v_pk_mul_f32 v[48:49], v[48:49], v[94:95] op_sel_hi:[1,0]
	v_pk_mul_f32 v[42:43], v[42:43], v[94:95] op_sel_hi:[1,0]
	v_pk_mul_f32 v[44:45], v[44:45], v[94:95] op_sel_hi:[1,0]
	v_pk_mul_f32 v[38:39], v[38:39], v[94:95] op_sel_hi:[1,0]
	v_pk_mul_f32 v[40:41], v[40:41], v[94:95] op_sel_hi:[1,0]
	v_pk_mul_f32 v[34:35], v[34:35], v[94:95] op_sel_hi:[1,0]
	v_pk_mul_f32 v[36:37], v[36:37], v[94:95] op_sel_hi:[1,0]
.Lwn_nosc_24:
	s_waitcnt lgkmcnt(0)
	s_nop 1
	v_mfma_f32_16x16x32_bf16 v[46:49], v[50:53], v[82:85], v[46:49]
	v_mfma_f32_16x16x32_bf16 v[42:45], v[58:61], v[82:85], v[42:45]
	v_mfma_f32_16x16x32_bf16 v[38:41], v[66:69], v[82:85], v[38:41]
	v_mfma_f32_16x16x32_bf16 v[34:37], v[74:77], v[82:85], v[34:37]
	v_mfma_f32_16x16x32_bf16 v[46:49], v[54:57], v[86:89], v[46:49]
	v_mfma_f32_16x16x32_bf16 v[42:45], v[62:65], v[86:89], v[42:45]
	v_mfma_f32_16x16x32_bf16 v[38:41], v[70:73], v[86:89], v[38:41]
	v_mfma_f32_16x16x32_bf16 v[34:37], v[78:81], v[86:89], v[34:37]
	v_sub_u32_e32 v90, v180, v139
	v_subrev_u32_e32 v90, s21, v90
	v_subrev_u32_e32 v170, 0, v90
	v_min_u32_e32 v170, 0x3ff, v170
	v_lshl_add_u32 v170, v170, 2, v131
	ds_read_b32 v170, v170
	v_subrev_u32_e32 v171, 1, v90
	v_min_u32_e32 v171, 0x3ff, v171
	v_lshl_add_u32 v171, v171, 2, v131
	ds_read_b32 v171, v171
	v_subrev_u32_e32 v172, 2, v90
	v_min_u32_e32 v172, 0x3ff, v172
	v_lshl_add_u32 v172, v172, 2, v131
	ds_read_b32 v172, v172
	v_subrev_u32_e32 v173, 3, v90
	v_min_u32_e32 v173, 0x3ff, v173
	v_lshl_add_u32 v173, v173, 2, v131
	ds_read_b32 v173, v173
	v_subrev_u32_e32 v174, 16, v90
	v_min_u32_e32 v174, 0x3ff, v174
	v_lshl_add_u32 v174, v174, 2, v131
	ds_read_b32 v174, v174
	v_subrev_u32_e32 v175, 17, v90
	v_min_u32_e32 v175, 0x3ff, v175
	v_lshl_add_u32 v175, v175, 2, v131
	ds_read_b32 v175, v175
	v_subrev_u32_e32 v176, 18, v90
	v_min_u32_e32 v176, 0x3ff, v176
	v_lshl_add_u32 v176, v176, 2, v131
	ds_read_b32 v176, v176
	v_subrev_u32_e32 v177, 19, v90
	v_min_u32_e32 v177, 0x3ff, v177
	v_lshl_add_u32 v177, v177, 2, v131
	ds_read_b32 v177, v177
	ds_read_b128 v[50:53], v116 offset:40960
	ds_read_b128 v[58:61], v116 offset:43520
	ds_read_b128 v[54:57], v116 offset:41024
	ds_read_b128 v[62:65], v116 offset:43584
	ds_read_b128 v[66:69], v116 offset:46080
	ds_read_b128 v[74:77], v116 offset:48640
	ds_read_b128 v[70:73], v116 offset:46144
	ds_read_b128 v[78:81], v116 offset:48704
	s_waitcnt lgkmcnt(6)
; template <int D, class SF>
; __device__ __forceinline__ void attn_step(const bf16x8 (&qf)[D / 32], const LAS bf16_t* Ks, const LAS bf16_t* Vt, f32x4 (&o)[D / 16], float& m, float& lsum, float& alpha_out, bf16x8& pf0_out, bf16x8& pf1_out, const int lane, SF sf) {
;     ...
; #pragma unroll
;     for (int t = 0; t < 4; ++t) s[t] = (f32x4){0.f, 0.f, 0.f, 0.f};
; #pragma unroll
;     for (int ks = 0; ks < D / 32; ++ks) {
; #pragma unroll
;         for (int t = 0; t < 4; ++t) { const bf16x8 kf = *(const LAS bf16x8*)(Ks + (16 * t + c) * KSTR + ks * 32 + 8 * i); s[t] = mfma16(kf, qf[ks], s[t]); }
;     }
;     float v[16];
; #pragma unroll
;     for (int t = 0; t < 4; ++t)
; #pragma unroll
;         for (int r = 0; r < 4; ++r) v[4 * t + r] = sf(16 * t + 4 * i + r, s[t][r]);
;     float mx = fmaxf(fmaxf(fmaxf(v[0], v[1]), fmaxf(v[2], v[3])), fmaxf(fmaxf(v[4], v[5]), fmaxf(v[6], v[7])));
;     mx = fmaxf(mx, fmaxf(fmaxf(fmaxf(v[8], v[9]), fmaxf(v[10], v[11])), fmaxf(fmaxf(v[12], v[13]), fmaxf(v[14], v[15]))));
;     mx = rows_max(mx);
;     const float mnew = fmaxf(m, mx);
;     const float mc = fmaxf(mnew, -1e20f);
;     const float alpha = __builtin_amdgcn_exp2f(fmaxf(m, -1e20f) - mc);
;     float p[16], rs = 0.f;
; #pragma unroll
;     for (int r = 0; r < 16; ++r) { p[r] = __builtin_amdgcn_exp2f(v[r] - mc); rs += p[r]; }
;     rs = rows_sum(rs);
;     lsum = lsum * alpha + rs; m = mnew;
;     union { u32x4 u; bf16x8 b; } pk0, pk1;
;     pk0.u.x = cvt_pk_bf16(p[0], p[1]); pk0.u.y = cvt_pk_bf16(p[2], p[3]); pk0.u.z = cvt_pk_bf16(p[4], p[5]); pk0.u.w = cvt_pk_bf16(p[6], p[7]);
;     pk1.u.x = cvt_pk_bf16(p[8], p[9]); pk1.u.y = cvt_pk_bf16(p[10], p[11]); pk1.u.z = cvt_pk_bf16(p[12], p[13]); pk1.u.w = cvt_pk_bf16(p[14], p[15]);
;     if (__builtin_amdgcn_ballot_w64(alpha != 1.0f) != 0ull) {
; #pragma unroll
;         for (int dt = 0; dt < D / 16; ++dt) o[dt] *= alpha;
;     }
; __device__ __forceinline__ void nsa_unit(LAS unsigned char* lds, const Ctx& P, int l, int b, int hkv, int tb) {
;     ...
;                 for (int sb = 0; sb < 2; ++sb) { const int tqs = tq[sb];
;                     attn_step<64>(qf[sb], Ks, Vt, o[sb], m[sb], lsum[sb], alpha, pf, pf1, lane,
;                         [&](int kk, float s) { const int kpos = kp0 + kk, dist = tqs - kpos; return (dist >= 0 && dist < 256 && kpos >= 0) ? s * LOG2E + lut[min((unsigned)dist, 1023u)] : NEGBIG; }); }
	v_mfma_f32_16x16x32_bf16 v[100:103], v[50:53], v[10:13], 0
	v_mfma_f32_16x16x32_bf16 v[104:107], v[58:61], v[10:13], 0
	s_waitcnt lgkmcnt(4)
	v_mfma_f32_16x16x32_bf16 v[100:103], v[54:57], v[14:17], v[100:103]
	v_mfma_f32_16x16x32_bf16 v[104:107], v[62:65], v[14:17], v[104:107]
	s_waitcnt lgkmcnt(2)
	v_mfma_f32_16x16x32_bf16 v[108:111], v[66:69], v[10:13], 0
	v_mfma_f32_16x16x32_bf16 v[112:115], v[74:77], v[10:13], 0
	s_waitcnt lgkmcnt(0)
	v_mfma_f32_16x16x32_bf16 v[108:111], v[70:73], v[14:17], v[108:111]
	v_mfma_f32_16x16x32_bf16 v[112:115], v[78:81], v[14:17], v[112:115]
	ds_read_b64_tr_b16 v[50:51], v117 offset:51200
	ds_read_b64_tr_b16 v[52:53], v117 offset:53760
	ds_read_b64_tr_b16 v[54:55], v117 offset:56320
	ds_read_b64_tr_b16 v[56:57], v117 offset:58880
	ds_read_b64_tr_b16 v[58:59], v117 offset:51232
	ds_read_b64_tr_b16 v[60:61], v117 offset:53792
	ds_read_b64_tr_b16 v[62:63], v117 offset:56352
	v_fmamk_f32 v100, v100, 0x3fb8aa3b, v170
	v_fmamk_f32 v101, v101, 0x3fb8aa3b, v171
	v_fmamk_f32 v102, v102, 0x3fb8aa3b, v172
	v_fmamk_f32 v103, v103, 0x3fb8aa3b, v173
	v_fmamk_f32 v104, v104, 0x3fb8aa3b, v174
	v_fmamk_f32 v105, v105, 0x3fb8aa3b, v175
	v_fmamk_f32 v106, v106, 0x3fb8aa3b, v176
	v_fmamk_f32 v107, v107, 0x3fb8aa3b, v177
	v_cmp_le_i32_e32 vcc, 0, v90
	s_nop 1
	v_cndmask_b32_e32 v100, v243, v100, vcc
	v_cmp_le_i32_e32 vcc, 1, v90
	s_nop 1
	v_cndmask_b32_e32 v101, v243, v101, vcc
	v_cmp_le_i32_e32 vcc, 2, v90
	s_nop 1
	v_cndmask_b32_e32 v102, v243, v102, vcc
	v_cmp_le_i32_e32 vcc, 3, v90
	s_nop 1
	v_cndmask_b32_e32 v103, v243, v103, vcc
	v_cmp_le_i32_e32 vcc, 16, v90
	s_nop 1
	v_cndmask_b32_e32 v104, v243, v104, vcc
	v_cmp_le_i32_e32 vcc, 17, v90
	s_nop 1
	v_cndmask_b32_e32 v105, v243, v105, vcc
	v_cmp_le_i32_e32 vcc, 18, v90
	s_nop 1
	v_cndmask_b32_e32 v106, v243, v106, vcc
	v_cmp_le_i32_e32 vcc, 19, v90
	s_nop 1
	v_cndmask_b32_e32 v107, v243, v107, vcc
	v_subrev_u32_e32 v170, 32, v90
	v_min_u32_e32 v170, 0x3ff, v170
	v_lshl_add_u32 v170, v170, 2, v131
	ds_read_b32 v170, v170
	v_subrev_u32_e32 v171, 33, v90
	v_min_u32_e32 v171, 0x3ff, v171
	v_lshl_add_u32 v171, v171, 2, v131
	ds_read_b32 v171, v171
	v_subrev_u32_e32 v172, 34, v90
	v_min_u32_e32 v172, 0x3ff, v172
	v_lshl_add_u32 v172, v172, 2, v131
	ds_read_b32 v172, v172
	v_subrev_u32_e32 v173, 35, v90
	v_min_u32_e32 v173, 0x3ff, v173
	v_lshl_add_u32 v173, v173, 2, v131
	ds_read_b32 v173, v173
	v_subrev_u32_e32 v174, 48, v90
	v_min_u32_e32 v174, 0x3ff, v174
	v_lshl_add_u32 v174, v174, 2, v131
	ds_read_b32 v174, v174
	v_subrev_u32_e32 v175, 49, v90
	v_min_u32_e32 v175, 0x3ff, v175
	v_lshl_add_u32 v175, v175, 2, v131
	ds_read_b32 v175, v175
	v_subrev_u32_e32 v176, 50, v90
	v_min_u32_e32 v176, 0x3ff, v176
	v_lshl_add_u32 v176, v176, 2, v131
	ds_read_b32 v176, v176
	v_subrev_u32_e32 v177, 51, v90
	v_min_u32_e32 v177, 0x3ff, v177
	v_lshl_add_u32 v177, v177, 2, v131
	ds_read_b32 v177, v177
	ds_read_b64_tr_b16 v[64:65], v117 offset:58912
	ds_read_b64_tr_b16 v[66:67], v117 offset:51264
	ds_read_b64_tr_b16 v[68:69], v117 offset:53824
	ds_read_b64_tr_b16 v[70:71], v117 offset:56384
	ds_read_b64_tr_b16 v[72:73], v117 offset:58944
	ds_read_b64_tr_b16 v[74:75], v117 offset:51296
	ds_read_b64_tr_b16 v[76:77], v117 offset:53856
	ds_read_b64_tr_b16 v[78:79], v117 offset:56416
	ds_read_b64_tr_b16 v[80:81], v117 offset:58976
	s_waitcnt lgkmcnt(9)
	v_fmamk_f32 v108, v108, 0x3fb8aa3b, v170
	v_fmamk_f32 v109, v109, 0x3fb8aa3b, v171
	v_fmamk_f32 v110, v110, 0x3fb8aa3b, v172
	v_fmamk_f32 v111, v111, 0x3fb8aa3b, v173
	v_fmamk_f32 v112, v112, 0x3fb8aa3b, v174
	v_fmamk_f32 v113, v113, 0x3fb8aa3b, v175
	v_fmamk_f32 v114, v114, 0x3fb8aa3b, v176
	v_fmamk_f32 v115, v115, 0x3fb8aa3b, v177
	v_cmp_le_i32_e32 vcc, 32, v90
	s_nop 1
	v_cndmask_b32_e32 v108, v243, v108, vcc
	v_cmp_le_i32_e32 vcc, 33, v90
	s_nop 1
	v_cndmask_b32_e32 v109, v243, v109, vcc
	v_cmp_le_i32_e32 vcc, 34, v90
	s_nop 1
	v_cndmask_b32_e32 v110, v243, v110, vcc
	v_cmp_le_i32_e32 vcc, 35, v90
	s_nop 1
	v_cndmask_b32_e32 v111, v243, v111, vcc
	v_cmp_le_i32_e32 vcc, 48, v90
	s_nop 1
	v_cndmask_b32_e32 v112, v243, v112, vcc
	v_cmp_le_i32_e32 vcc, 49, v90
	s_nop 1
	v_cndmask_b32_e32 v113, v243, v113, vcc
	v_cmp_le_i32_e32 vcc, 50, v90
	s_nop 1
	v_cndmask_b32_e32 v114, v243, v114, vcc
	v_cmp_le_i32_e32 vcc, 51, v90
	s_nop 1
	v_cndmask_b32_e32 v115, v243, v115, vcc
	v_max3_f32 v96, v100, v101, v102
	v_max3_f32 v91, v103, v104, v105
	v_max3_f32 v92, v106, v107, v108
	v_max3_f32 v93, v109, v110, v111
	v_max3_f32 v95, v112, v113, v114
	v_max3_f32 v96, v96, v91, v115
	v_max3_f32 v92, v92, v93, v95
	v_max_f32_e32 v96, v96, v92
	v_mov_b32_e32 v91, v96
	s_nop 1
	v_permlane16_swap_b32_e32 v96, v91
	v_max_f32_e32 v96, v96, v91
	v_mov_b32_e32 v91, v96
	s_nop 1
	v_permlane32_swap_b32_e32 v96, v91
	v_max_f32_e32 v96, v96, v91
	v_max_f32_e32 v92, v160, v96
	v_max_f32_e32 v94, 0xe0ad78ec, v160
	v_max_f32_e32 v93, 0xe0ad78ec, v92
	v_sub_f32_e32 v94, v94, v93
	v_mov_b32_e32 v160, v92
	v_exp_f32_e32 v94, v94
	v_sub_f32_e32 v100, v100, v93
	v_sub_f32_e32 v101, v101, v93
	v_sub_f32_e32 v102, v102, v93
	v_sub_f32_e32 v103, v103, v93
	v_exp_f32_e32 v100, v100
	v_exp_f32_e32 v101, v101
	v_exp_f32_e32 v102, v102
	v_exp_f32_e32 v103, v103
	v_sub_f32_e32 v104, v104, v93
	v_sub_f32_e32 v105, v105, v93
	v_sub_f32_e32 v106, v106, v93
	v_sub_f32_e32 v107, v107, v93
	v_exp_f32_e32 v104, v104
	v_exp_f32_e32 v105, v105
	v_exp_f32_e32 v106, v106
	v_exp_f32_e32 v107, v107
	v_sub_f32_e32 v108, v108, v93
	v_sub_f32_e32 v109, v109, v93
	v_sub_f32_e32 v110, v110, v93
	v_sub_f32_e32 v111, v111, v93
	v_exp_f32_e32 v108, v108
	v_exp_f32_e32 v109, v109
	v_exp_f32_e32 v110, v110
	v_exp_f32_e32 v111, v111
	v_sub_f32_e32 v112, v112, v93
	v_sub_f32_e32 v113, v113, v93
	v_sub_f32_e32 v114, v114, v93
	v_sub_f32_e32 v115, v115, v93
	v_exp_f32_e32 v112, v112
	v_exp_f32_e32 v113, v113
	v_exp_f32_e32 v114, v114
	v_exp_f32_e32 v115, v115
	s_nop 0
	v_add_f32_e32 v90, v100, v101
	v_add_f32_e32 v91, v102, v103
	v_add_f32_e32 v92, v104, v105
	v_add_f32_e32 v93, v106, v107
	v_add_f32_e32 v90, v90, v108
	v_add_f32_e32 v91, v91, v109
	v_add_f32_e32 v92, v92, v110
	v_add_f32_e32 v93, v93, v111
	v_add_f32_e32 v90, v90, v112
	v_add_f32_e32 v91, v91, v113
	v_add_f32_e32 v92, v92, v114
	v_add_f32_e32 v93, v93, v115
	v_add_f32_e32 v90, v90, v91
	v_add_f32_e32 v92, v92, v93
	v_add_f32_e32 v90, v90, v92
	v_cvt_pk_bf16_f32 v82, v100, v101
	v_cvt_pk_bf16_f32 v83, v102, v103
	v_cvt_pk_bf16_f32 v84, v104, v105
	v_cvt_pk_bf16_f32 v85, v106, v107
	v_cvt_pk_bf16_f32 v86, v108, v109
	v_cvt_pk_bf16_f32 v87, v110, v111
	v_cvt_pk_bf16_f32 v88, v112, v113
	v_cvt_pk_bf16_f32 v89, v114, v115
	v_mov_b32_e32 v91, v90
	s_nop 1
	v_permlane16_swap_b32_e32 v90, v91
	v_add_f32_e32 v90, v90, v91
	v_mov_b32_e32 v91, v90
	s_nop 1
	v_permlane32_swap_b32_e32 v90, v91
	v_add_f32_e32 v90, v90, v91
	v_fma_f32 v159, v159, v94, v90
	v_cmp_neq_f32_e64 s[4:5], 1.0, v94
	s_cmp_eq_u64 s[4:5], 0
	s_cbranch_scc1 .Lwn_nosc_25
; template <int D, class SF>
; __device__ __forceinline__ void attn_step(const bf16x8 (&qf)[D / 32], const LAS bf16_t* Ks, const LAS bf16_t* Vt, f32x4 (&o)[D / 16], float& m, float& lsum, float& alpha_out, bf16x8& pf0_out, bf16x8& pf1_out, const int lane, SF sf) {
;     ...
;         for (int dt = 0; dt < D / 16; ++dt) o[dt] *= alpha;
	v_pk_mul_f32 v[30:31], v[30:31], v[94:95] op_sel_hi:[1,0]
	v_pk_mul_f32 v[32:33], v[32:33], v[94:95] op_sel_hi:[1,0]
	v_pk_mul_f32 v[26:27], v[26:27], v[94:95] op_sel_hi:[1,0]
	v_pk_mul_f32 v[28:29], v[28:29], v[94:95] op_sel_hi:[1,0]
	v_pk_mul_f32 v[22:23], v[22:23], v[94:95] op_sel_hi:[1,0]
	v_pk_mul_f32 v[24:25], v[24:25], v[94:95] op_sel_hi:[1,0]
	v_pk_mul_f32 v[18:19], v[18:19], v[94:95] op_sel_hi:[1,0]
	v_pk_mul_f32 v[20:21], v[20:21], v[94:95] op_sel_hi:[1,0]
